# fast mode-specialized w_in epilogue + pipelined LDS reads in diff-latent attention
# speedup vs baseline: 1.0185x; 1.0185x over previous
.LBB0_302:
	s_ashr_i32 s33, s8, 1
	s_cmp_lt_i32 s10, 32
	s_cbranch_scc1 .Lfe_ctx
	s_cmp_eq_u32 s33, 2
	s_cbranch_scc1 .Lfe_generic
	s_cmp_eq_u32 s33, 3
	s_cbranch_scc1 .Lfe_generic
	s_branch .Lfe_fast
.Lfe_ctx:
	s_cmp_eq_u32 s33, 3
	s_cbranch_scc1 .Lfe_generic
	s_cmp_eq_u32 s33, 6
	s_cbranch_scc1 .Lfe_generic
.Lfe_fast:
	s_cmp_gt_i32 s33, 7
	s_cbranch_scc1 .Lfe_gf
	s_lshl_b32 s9, s10, 8
	s_add_i32 s9, s9, s86
	s_mul_i32 s11, s9, 0x2080
	s_lshl_b32 s12, s8, 9
	s_add_i32 s11, s11, s12
	s_lshl_b32 s12, s87, 1
	s_add_i32 s11, s11, s12
	s_add_u32 s12, s18, s11
	s_addc_u32 s13, s19, 0
	v_mul_u32_u24_e32 v240, 0x2080, v176
	v_lshl_add_u32 v240, v177, 4, v240
	s_cmp_eq_u32 s33, 2
	s_cbranch_scc1 .Lfe_act_q
	s_cmp_eq_u32 s33, 5
	s_cbranch_scc1 .Lfe_act_q
	v_cvt_pk_bf16_f32 v124, v124, v125
	v_cvt_pk_bf16_f32 v125, v126, v127
	v_cvt_pk_bf16_f32 v126, v120, v121
	v_cvt_pk_bf16_f32 v127, v122, v123
	global_store_dwordx4 v240, v[124:127], s[12:13]
	v_cvt_pk_bf16_f32 v116, v116, v117
	v_cvt_pk_bf16_f32 v117, v118, v119
	v_cvt_pk_bf16_f32 v118, v112, v113
	v_cvt_pk_bf16_f32 v119, v114, v115
	global_store_dwordx4 v240, v[116:119], s[12:13] offset:256
	s_add_u32 s12, s12, 0x20800
	s_addc_u32 s13, s13, 0
	v_cvt_pk_bf16_f32 v108, v108, v109
	v_cvt_pk_bf16_f32 v109, v110, v111
	v_cvt_pk_bf16_f32 v110, v104, v105
	v_cvt_pk_bf16_f32 v111, v106, v107
	global_store_dwordx4 v240, v[108:111], s[12:13]
	v_cvt_pk_bf16_f32 v100, v100, v101
	v_cvt_pk_bf16_f32 v101, v102, v103
	v_cvt_pk_bf16_f32 v102, v96, v97
	v_cvt_pk_bf16_f32 v103, v98, v99
	global_store_dwordx4 v240, v[100:103], s[12:13] offset:256
	s_add_u32 s12, s12, 0x20800
	s_addc_u32 s13, s13, 0
	v_cvt_pk_bf16_f32 v92, v92, v93
	v_cvt_pk_bf16_f32 v93, v94, v95
	v_cvt_pk_bf16_f32 v94, v88, v89
	v_cvt_pk_bf16_f32 v95, v90, v91
	global_store_dwordx4 v240, v[92:95], s[12:13]
	v_cvt_pk_bf16_f32 v84, v84, v85
	v_cvt_pk_bf16_f32 v85, v86, v87
	v_cvt_pk_bf16_f32 v86, v80, v81
	v_cvt_pk_bf16_f32 v87, v82, v83
	global_store_dwordx4 v240, v[84:87], s[12:13] offset:256
	s_add_u32 s12, s12, 0x20800
	s_addc_u32 s13, s13, 0
	v_cvt_pk_bf16_f32 v76, v76, v77
	v_cvt_pk_bf16_f32 v77, v78, v79
	v_cvt_pk_bf16_f32 v78, v72, v73
	v_cvt_pk_bf16_f32 v79, v74, v75
	global_store_dwordx4 v240, v[76:79], s[12:13]
	v_cvt_pk_bf16_f32 v68, v68, v69
	v_cvt_pk_bf16_f32 v69, v70, v71
	v_cvt_pk_bf16_f32 v70, v64, v65
	v_cvt_pk_bf16_f32 v71, v66, v67
	global_store_dwordx4 v240, v[68:71], s[12:13] offset:256
	s_add_u32 s12, s12, 0xa2800
	s_addc_u32 s13, s13, 0
	v_cvt_pk_bf16_f32 v60, v60, v61
	v_cvt_pk_bf16_f32 v61, v62, v63
	v_cvt_pk_bf16_f32 v62, v56, v57
	v_cvt_pk_bf16_f32 v63, v58, v59
	global_store_dwordx4 v240, v[60:63], s[12:13]
	v_cvt_pk_bf16_f32 v52, v52, v53
	v_cvt_pk_bf16_f32 v53, v54, v55
	v_cvt_pk_bf16_f32 v54, v48, v49
	v_cvt_pk_bf16_f32 v55, v50, v51
	global_store_dwordx4 v240, v[52:55], s[12:13] offset:256
	s_add_u32 s12, s12, 0x20800
	s_addc_u32 s13, s13, 0
	v_cvt_pk_bf16_f32 v44, v44, v45
	v_cvt_pk_bf16_f32 v45, v46, v47
	v_cvt_pk_bf16_f32 v46, v40, v41
	v_cvt_pk_bf16_f32 v47, v42, v43
	global_store_dwordx4 v240, v[44:47], s[12:13]
	v_cvt_pk_bf16_f32 v36, v36, v37
	v_cvt_pk_bf16_f32 v37, v38, v39
	v_cvt_pk_bf16_f32 v38, v32, v33
	v_cvt_pk_bf16_f32 v39, v34, v35
	global_store_dwordx4 v240, v[36:39], s[12:13] offset:256
	s_add_u32 s12, s12, 0x20800
	s_addc_u32 s13, s13, 0
	v_cvt_pk_bf16_f32 v28, v28, v29
	v_cvt_pk_bf16_f32 v29, v30, v31
	v_cvt_pk_bf16_f32 v30, v24, v25
	v_cvt_pk_bf16_f32 v31, v26, v27
	global_store_dwordx4 v240, v[28:31], s[12:13]
	v_cvt_pk_bf16_f32 v20, v20, v21
	v_cvt_pk_bf16_f32 v21, v22, v23
	v_cvt_pk_bf16_f32 v22, v16, v17
	v_cvt_pk_bf16_f32 v23, v18, v19
	global_store_dwordx4 v240, v[20:23], s[12:13] offset:256
	s_add_u32 s12, s12, 0x20800
	s_addc_u32 s13, s13, 0
	v_cvt_pk_bf16_f32 v12, v12, v13
	v_cvt_pk_bf16_f32 v13, v14, v15
	v_cvt_pk_bf16_f32 v14, v8, v9
	v_cvt_pk_bf16_f32 v15, v10, v11
	global_store_dwordx4 v240, v[12:15], s[12:13]
	v_cvt_pk_bf16_f32 v4, v4, v5
	v_cvt_pk_bf16_f32 v5, v6, v7
	v_cvt_pk_bf16_f32 v6, v0, v1
	v_cvt_pk_bf16_f32 v7, v2, v3
	global_store_dwordx4 v240, v[4:7], s[12:13] offset:256
	s_branch .Lfe_join
.Lfe_act_q:
	v_mul_f32_e32 v124, s78, v124
	v_mul_f32_e32 v125, s78, v125
	v_mul_f32_e32 v126, s78, v126
	v_mul_f32_e32 v127, s78, v127
	v_mul_f32_e32 v120, s78, v120
	v_mul_f32_e32 v121, s78, v121
	v_mul_f32_e32 v122, s78, v122
	v_mul_f32_e32 v123, s78, v123
	v_cvt_pk_bf16_f32 v124, v124, v125
	v_cvt_pk_bf16_f32 v125, v126, v127
	v_cvt_pk_bf16_f32 v126, v120, v121
	v_cvt_pk_bf16_f32 v127, v122, v123
	global_store_dwordx4 v240, v[124:127], s[12:13]
	v_mul_f32_e32 v116, s78, v116
	v_mul_f32_e32 v117, s78, v117
	v_mul_f32_e32 v118, s78, v118
	v_mul_f32_e32 v119, s78, v119
	v_mul_f32_e32 v112, s78, v112
	v_mul_f32_e32 v113, s78, v113
	v_mul_f32_e32 v114, s78, v114
	v_mul_f32_e32 v115, s78, v115
	v_cvt_pk_bf16_f32 v116, v116, v117
	v_cvt_pk_bf16_f32 v117, v118, v119
	v_cvt_pk_bf16_f32 v118, v112, v113
	v_cvt_pk_bf16_f32 v119, v114, v115
	global_store_dwordx4 v240, v[116:119], s[12:13] offset:256
	s_add_u32 s12, s12, 0x20800
	s_addc_u32 s13, s13, 0
	v_mul_f32_e32 v108, s78, v108
	v_mul_f32_e32 v109, s78, v109
	v_mul_f32_e32 v110, s78, v110
	v_mul_f32_e32 v111, s78, v111
	v_mul_f32_e32 v104, s78, v104
	v_mul_f32_e32 v105, s78, v105
	v_mul_f32_e32 v106, s78, v106
	v_mul_f32_e32 v107, s78, v107
	v_cvt_pk_bf16_f32 v108, v108, v109
	v_cvt_pk_bf16_f32 v109, v110, v111
	v_cvt_pk_bf16_f32 v110, v104, v105
	v_cvt_pk_bf16_f32 v111, v106, v107
	global_store_dwordx4 v240, v[108:111], s[12:13]
	v_mul_f32_e32 v100, s78, v100
	v_mul_f32_e32 v101, s78, v101
	v_mul_f32_e32 v102, s78, v102
	v_mul_f32_e32 v103, s78, v103
	v_mul_f32_e32 v96, s78, v96
	v_mul_f32_e32 v97, s78, v97
	v_mul_f32_e32 v98, s78, v98
	v_mul_f32_e32 v99, s78, v99
	v_cvt_pk_bf16_f32 v100, v100, v101
	v_cvt_pk_bf16_f32 v101, v102, v103
	v_cvt_pk_bf16_f32 v102, v96, v97
	v_cvt_pk_bf16_f32 v103, v98, v99
	global_store_dwordx4 v240, v[100:103], s[12:13] offset:256
	s_add_u32 s12, s12, 0x20800
	s_addc_u32 s13, s13, 0
	v_mul_f32_e32 v92, s78, v92
	v_mul_f32_e32 v93, s78, v93
	v_mul_f32_e32 v94, s78, v94
	v_mul_f32_e32 v95, s78, v95
	v_mul_f32_e32 v88, s78, v88
	v_mul_f32_e32 v89, s78, v89
	v_mul_f32_e32 v90, s78, v90
	v_mul_f32_e32 v91, s78, v91
	v_cvt_pk_bf16_f32 v92, v92, v93
	v_cvt_pk_bf16_f32 v93, v94, v95
	v_cvt_pk_bf16_f32 v94, v88, v89
	v_cvt_pk_bf16_f32 v95, v90, v91
	global_store_dwordx4 v240, v[92:95], s[12:13]
	v_mul_f32_e32 v84, s78, v84
	v_mul_f32_e32 v85, s78, v85
	v_mul_f32_e32 v86, s78, v86
	v_mul_f32_e32 v87, s78, v87
	v_mul_f32_e32 v80, s78, v80
	v_mul_f32_e32 v81, s78, v81
	v_mul_f32_e32 v82, s78, v82
	v_mul_f32_e32 v83, s78, v83
	v_cvt_pk_bf16_f32 v84, v84, v85
	v_cvt_pk_bf16_f32 v85, v86, v87
	v_cvt_pk_bf16_f32 v86, v80, v81
	v_cvt_pk_bf16_f32 v87, v82, v83
	global_store_dwordx4 v240, v[84:87], s[12:13] offset:256
	s_add_u32 s12, s12, 0x20800
	s_addc_u32 s13, s13, 0
	v_mul_f32_e32 v76, s78, v76
	v_mul_f32_e32 v77, s78, v77
	v_mul_f32_e32 v78, s78, v78
	v_mul_f32_e32 v79, s78, v79
	v_mul_f32_e32 v72, s78, v72
	v_mul_f32_e32 v73, s78, v73
	v_mul_f32_e32 v74, s78, v74
	v_mul_f32_e32 v75, s78, v75
	v_cvt_pk_bf16_f32 v76, v76, v77
	v_cvt_pk_bf16_f32 v77, v78, v79
	v_cvt_pk_bf16_f32 v78, v72, v73
	v_cvt_pk_bf16_f32 v79, v74, v75
	global_store_dwordx4 v240, v[76:79], s[12:13]
	v_mul_f32_e32 v68, s78, v68
	v_mul_f32_e32 v69, s78, v69
	v_mul_f32_e32 v70, s78, v70
	v_mul_f32_e32 v71, s78, v71
	v_mul_f32_e32 v64, s78, v64
	v_mul_f32_e32 v65, s78, v65
	v_mul_f32_e32 v66, s78, v66
	v_mul_f32_e32 v67, s78, v67
	v_cvt_pk_bf16_f32 v68, v68, v69
	v_cvt_pk_bf16_f32 v69, v70, v71
	v_cvt_pk_bf16_f32 v70, v64, v65
	v_cvt_pk_bf16_f32 v71, v66, v67
	global_store_dwordx4 v240, v[68:71], s[12:13] offset:256
	s_add_u32 s12, s12, 0xa2800
	s_addc_u32 s13, s13, 0
	v_mul_f32_e32 v60, s78, v60
	v_mul_f32_e32 v61, s78, v61
	v_mul_f32_e32 v62, s78, v62
	v_mul_f32_e32 v63, s78, v63
	v_mul_f32_e32 v56, s78, v56
	v_mul_f32_e32 v57, s78, v57
	v_mul_f32_e32 v58, s78, v58
	v_mul_f32_e32 v59, s78, v59
	v_cvt_pk_bf16_f32 v60, v60, v61
	v_cvt_pk_bf16_f32 v61, v62, v63
	v_cvt_pk_bf16_f32 v62, v56, v57
	v_cvt_pk_bf16_f32 v63, v58, v59
	global_store_dwordx4 v240, v[60:63], s[12:13]
	v_mul_f32_e32 v52, s78, v52
	v_mul_f32_e32 v53, s78, v53
	v_mul_f32_e32 v54, s78, v54
	v_mul_f32_e32 v55, s78, v55
	v_mul_f32_e32 v48, s78, v48
	v_mul_f32_e32 v49, s78, v49
	v_mul_f32_e32 v50, s78, v50
	v_mul_f32_e32 v51, s78, v51
	v_cvt_pk_bf16_f32 v52, v52, v53
	v_cvt_pk_bf16_f32 v53, v54, v55
	v_cvt_pk_bf16_f32 v54, v48, v49
	v_cvt_pk_bf16_f32 v55, v50, v51
	global_store_dwordx4 v240, v[52:55], s[12:13] offset:256
	s_add_u32 s12, s12, 0x20800
	s_addc_u32 s13, s13, 0
	v_mul_f32_e32 v44, s78, v44
	v_mul_f32_e32 v45, s78, v45
	v_mul_f32_e32 v46, s78, v46
	v_mul_f32_e32 v47, s78, v47
	v_mul_f32_e32 v40, s78, v40
	v_mul_f32_e32 v41, s78, v41
	v_mul_f32_e32 v42, s78, v42
	v_mul_f32_e32 v43, s78, v43
	v_cvt_pk_bf16_f32 v44, v44, v45
	v_cvt_pk_bf16_f32 v45, v46, v47
	v_cvt_pk_bf16_f32 v46, v40, v41
	v_cvt_pk_bf16_f32 v47, v42, v43
	global_store_dwordx4 v240, v[44:47], s[12:13]
	v_mul_f32_e32 v36, s78, v36
	v_mul_f32_e32 v37, s78, v37
	v_mul_f32_e32 v38, s78, v38
	v_mul_f32_e32 v39, s78, v39
	v_mul_f32_e32 v32, s78, v32
	v_mul_f32_e32 v33, s78, v33
	v_mul_f32_e32 v34, s78, v34
	v_mul_f32_e32 v35, s78, v35
	v_cvt_pk_bf16_f32 v36, v36, v37
	v_cvt_pk_bf16_f32 v37, v38, v39
	v_cvt_pk_bf16_f32 v38, v32, v33
	v_cvt_pk_bf16_f32 v39, v34, v35
	global_store_dwordx4 v240, v[36:39], s[12:13] offset:256
	s_add_u32 s12, s12, 0x20800
	s_addc_u32 s13, s13, 0
	v_mul_f32_e32 v28, s78, v28
	v_mul_f32_e32 v29, s78, v29
	v_mul_f32_e32 v30, s78, v30
	v_mul_f32_e32 v31, s78, v31
	v_mul_f32_e32 v24, s78, v24
	v_mul_f32_e32 v25, s78, v25
	v_mul_f32_e32 v26, s78, v26
	v_mul_f32_e32 v27, s78, v27
	v_cvt_pk_bf16_f32 v28, v28, v29
	v_cvt_pk_bf16_f32 v29, v30, v31
	v_cvt_pk_bf16_f32 v30, v24, v25
	v_cvt_pk_bf16_f32 v31, v26, v27
	global_store_dwordx4 v240, v[28:31], s[12:13]
	v_mul_f32_e32 v20, s78, v20
	v_mul_f32_e32 v21, s78, v21
	v_mul_f32_e32 v22, s78, v22
	v_mul_f32_e32 v23, s78, v23
	v_mul_f32_e32 v16, s78, v16
	v_mul_f32_e32 v17, s78, v17
	v_mul_f32_e32 v18, s78, v18
	v_mul_f32_e32 v19, s78, v19
	v_cvt_pk_bf16_f32 v20, v20, v21
	v_cvt_pk_bf16_f32 v21, v22, v23
	v_cvt_pk_bf16_f32 v22, v16, v17
	v_cvt_pk_bf16_f32 v23, v18, v19
	global_store_dwordx4 v240, v[20:23], s[12:13] offset:256
	s_add_u32 s12, s12, 0x20800
	s_addc_u32 s13, s13, 0
	v_mul_f32_e32 v12, s78, v12
	v_mul_f32_e32 v13, s78, v13
	v_mul_f32_e32 v14, s78, v14
	v_mul_f32_e32 v15, s78, v15
	v_mul_f32_e32 v8, s78, v8
	v_mul_f32_e32 v9, s78, v9
	v_mul_f32_e32 v10, s78, v10
	v_mul_f32_e32 v11, s78, v11
	v_cvt_pk_bf16_f32 v12, v12, v13
	v_cvt_pk_bf16_f32 v13, v14, v15
	v_cvt_pk_bf16_f32 v14, v8, v9
	v_cvt_pk_bf16_f32 v15, v10, v11
	global_store_dwordx4 v240, v[12:15], s[12:13]
	v_mul_f32_e32 v4, s78, v4
	v_mul_f32_e32 v5, s78, v5
	v_mul_f32_e32 v6, s78, v6
	v_mul_f32_e32 v7, s78, v7
	v_mul_f32_e32 v0, s78, v0
	v_mul_f32_e32 v1, s78, v1
	v_mul_f32_e32 v2, s78, v2
	v_mul_f32_e32 v3, s78, v3
	v_cvt_pk_bf16_f32 v4, v4, v5
	v_cvt_pk_bf16_f32 v5, v6, v7
	v_cvt_pk_bf16_f32 v6, v0, v1
	v_cvt_pk_bf16_f32 v7, v2, v3
	global_store_dwordx4 v240, v[4:7], s[12:13] offset:256
	s_branch .Lfe_join
.Lfe_gf:
	s_mul_i32 s9, s10, 20
	s_add_i32 s9, s9, s8
	s_add_i32 s9, s9, -16
	s_lshl_b32 s9, s9, 17
	s_lshl_b32 s11, s84, 1
	s_add_i32 s9, s9, s11
	s_add_u32 s12, s37, s9
	s_addc_u32 s13, s4, 0
	v_lshlrev_b32_e32 v240, 8, v177
	v_lshl_add_u32 v240, v176, 4, v240
	s_cmp_gt_i32 s33, 9
	s_cbranch_scc1 .Lfe_gf_sig
	v_mul_f32_e32 v248, 0xbfb8aa3b, v124
	v_mul_f32_e32 v249, 0xbfb8aa3b, v125
	v_mul_f32_e32 v250, 0xbfb8aa3b, v126
	v_mul_f32_e32 v251, 0xbfb8aa3b, v127
	v_mul_f32_e32 v252, 0xbfb8aa3b, v120
	v_mul_f32_e32 v253, 0xbfb8aa3b, v121
	v_mul_f32_e32 v254, 0xbfb8aa3b, v122
	v_mul_f32_e32 v255, 0xbfb8aa3b, v123
	v_exp_f32_e32 v248, v248
	v_exp_f32_e32 v249, v249
	v_exp_f32_e32 v250, v250
	v_exp_f32_e32 v251, v251
	v_exp_f32_e32 v252, v252
	v_exp_f32_e32 v253, v253
	v_exp_f32_e32 v254, v254
	v_exp_f32_e32 v255, v255
	v_add_f32_e32 v248, 1.0, v248
	v_add_f32_e32 v249, 1.0, v249
	v_add_f32_e32 v250, 1.0, v250
	v_add_f32_e32 v251, 1.0, v251
	v_add_f32_e32 v252, 1.0, v252
	v_add_f32_e32 v253, 1.0, v253
	v_add_f32_e32 v254, 1.0, v254
	v_add_f32_e32 v255, 1.0, v255
	v_rcp_f32_e32 v248, v248
	v_rcp_f32_e32 v249, v249
	v_rcp_f32_e32 v250, v250
	v_rcp_f32_e32 v251, v251
	v_rcp_f32_e32 v252, v252
	v_rcp_f32_e32 v253, v253
	v_rcp_f32_e32 v254, v254
	v_rcp_f32_e32 v255, v255
	v_mul_f32_e32 v124, v124, v248
	v_mul_f32_e32 v125, v125, v249
	v_mul_f32_e32 v126, v126, v250
	v_mul_f32_e32 v127, v127, v251
	v_mul_f32_e32 v120, v120, v252
	v_mul_f32_e32 v121, v121, v253
	v_mul_f32_e32 v122, v122, v254
	v_mul_f32_e32 v123, v123, v255
	v_cvt_pk_bf16_f32 v124, v124, v125
	v_cvt_pk_bf16_f32 v125, v126, v127
	v_cvt_pk_bf16_f32 v126, v120, v121
	v_cvt_pk_bf16_f32 v127, v122, v123
	global_store_dwordx4 v240, v[124:127], s[12:13]
	v_mul_f32_e32 v248, 0xbfb8aa3b, v116
	v_mul_f32_e32 v249, 0xbfb8aa3b, v117
	v_mul_f32_e32 v250, 0xbfb8aa3b, v118
	v_mul_f32_e32 v251, 0xbfb8aa3b, v119
	v_mul_f32_e32 v252, 0xbfb8aa3b, v112
	v_mul_f32_e32 v253, 0xbfb8aa3b, v113
	v_mul_f32_e32 v254, 0xbfb8aa3b, v114
	v_mul_f32_e32 v255, 0xbfb8aa3b, v115
	v_exp_f32_e32 v248, v248
	v_exp_f32_e32 v249, v249
	v_exp_f32_e32 v250, v250
	v_exp_f32_e32 v251, v251
	v_exp_f32_e32 v252, v252
	v_exp_f32_e32 v253, v253
	v_exp_f32_e32 v254, v254
	v_exp_f32_e32 v255, v255
	v_add_f32_e32 v248, 1.0, v248
	v_add_f32_e32 v249, 1.0, v249
	v_add_f32_e32 v250, 1.0, v250
	v_add_f32_e32 v251, 1.0, v251
	v_add_f32_e32 v252, 1.0, v252
	v_add_f32_e32 v253, 1.0, v253
	v_add_f32_e32 v254, 1.0, v254
	v_add_f32_e32 v255, 1.0, v255
	v_rcp_f32_e32 v248, v248
	v_rcp_f32_e32 v249, v249
	v_rcp_f32_e32 v250, v250
	v_rcp_f32_e32 v251, v251
	v_rcp_f32_e32 v252, v252
	v_rcp_f32_e32 v253, v253
	v_rcp_f32_e32 v254, v254
	v_rcp_f32_e32 v255, v255
	v_mul_f32_e32 v116, v116, v248
	v_mul_f32_e32 v117, v117, v249
	v_mul_f32_e32 v118, v118, v250
	v_mul_f32_e32 v119, v119, v251
	v_mul_f32_e32 v112, v112, v252
	v_mul_f32_e32 v113, v113, v253
	v_mul_f32_e32 v114, v114, v254
	v_mul_f32_e32 v115, v115, v255
	v_cvt_pk_bf16_f32 v116, v116, v117
	v_cvt_pk_bf16_f32 v117, v118, v119
	v_cvt_pk_bf16_f32 v118, v112, v113
	v_cvt_pk_bf16_f32 v119, v114, v115
	global_store_dwordx4 v240, v[116:119], s[12:13] offset:1024
	s_add_u32 s12, s12, 0x800
	s_addc_u32 s13, s13, 0
	v_mul_f32_e32 v248, 0xbfb8aa3b, v108
	v_mul_f32_e32 v249, 0xbfb8aa3b, v109
	v_mul_f32_e32 v250, 0xbfb8aa3b, v110
	v_mul_f32_e32 v251, 0xbfb8aa3b, v111
	v_mul_f32_e32 v252, 0xbfb8aa3b, v104
	v_mul_f32_e32 v253, 0xbfb8aa3b, v105
	v_mul_f32_e32 v254, 0xbfb8aa3b, v106
	v_mul_f32_e32 v255, 0xbfb8aa3b, v107
	v_exp_f32_e32 v248, v248
	v_exp_f32_e32 v249, v249
	v_exp_f32_e32 v250, v250
	v_exp_f32_e32 v251, v251
	v_exp_f32_e32 v252, v252
	v_exp_f32_e32 v253, v253
	v_exp_f32_e32 v254, v254
	v_exp_f32_e32 v255, v255
	v_add_f32_e32 v248, 1.0, v248
	v_add_f32_e32 v249, 1.0, v249
	v_add_f32_e32 v250, 1.0, v250
	v_add_f32_e32 v251, 1.0, v251
	v_add_f32_e32 v252, 1.0, v252
	v_add_f32_e32 v253, 1.0, v253
	v_add_f32_e32 v254, 1.0, v254
	v_add_f32_e32 v255, 1.0, v255
	v_rcp_f32_e32 v248, v248
	v_rcp_f32_e32 v249, v249
	v_rcp_f32_e32 v250, v250
	v_rcp_f32_e32 v251, v251
	v_rcp_f32_e32 v252, v252
	v_rcp_f32_e32 v253, v253
	v_rcp_f32_e32 v254, v254
	v_rcp_f32_e32 v255, v255
	v_mul_f32_e32 v108, v108, v248
	v_mul_f32_e32 v109, v109, v249
	v_mul_f32_e32 v110, v110, v250
	v_mul_f32_e32 v111, v111, v251
	v_mul_f32_e32 v104, v104, v252
	v_mul_f32_e32 v105, v105, v253
	v_mul_f32_e32 v106, v106, v254
	v_mul_f32_e32 v107, v107, v255
	v_cvt_pk_bf16_f32 v108, v108, v109
	v_cvt_pk_bf16_f32 v109, v110, v111
	v_cvt_pk_bf16_f32 v110, v104, v105
	v_cvt_pk_bf16_f32 v111, v106, v107
	global_store_dwordx4 v240, v[108:111], s[12:13]
	v_mul_f32_e32 v248, 0xbfb8aa3b, v100
	v_mul_f32_e32 v249, 0xbfb8aa3b, v101
	v_mul_f32_e32 v250, 0xbfb8aa3b, v102
	v_mul_f32_e32 v251, 0xbfb8aa3b, v103
	v_mul_f32_e32 v252, 0xbfb8aa3b, v96
	v_mul_f32_e32 v253, 0xbfb8aa3b, v97
	v_mul_f32_e32 v254, 0xbfb8aa3b, v98
	v_mul_f32_e32 v255, 0xbfb8aa3b, v99
	v_exp_f32_e32 v248, v248
	v_exp_f32_e32 v249, v249
	v_exp_f32_e32 v250, v250
	v_exp_f32_e32 v251, v251
	v_exp_f32_e32 v252, v252
	v_exp_f32_e32 v253, v253
	v_exp_f32_e32 v254, v254
	v_exp_f32_e32 v255, v255
	v_add_f32_e32 v248, 1.0, v248
	v_add_f32_e32 v249, 1.0, v249
	v_add_f32_e32 v250, 1.0, v250
	v_add_f32_e32 v251, 1.0, v251
	v_add_f32_e32 v252, 1.0, v252
	v_add_f32_e32 v253, 1.0, v253
	v_add_f32_e32 v254, 1.0, v254
	v_add_f32_e32 v255, 1.0, v255
	v_rcp_f32_e32 v248, v248
	v_rcp_f32_e32 v249, v249
	v_rcp_f32_e32 v250, v250
	v_rcp_f32_e32 v251, v251
	v_rcp_f32_e32 v252, v252
	v_rcp_f32_e32 v253, v253
	v_rcp_f32_e32 v254, v254
	v_rcp_f32_e32 v255, v255
	v_mul_f32_e32 v100, v100, v248
	v_mul_f32_e32 v101, v101, v249
	v_mul_f32_e32 v102, v102, v250
	v_mul_f32_e32 v103, v103, v251
	v_mul_f32_e32 v96, v96, v252
	v_mul_f32_e32 v97, v97, v253
	v_mul_f32_e32 v98, v98, v254
	v_mul_f32_e32 v99, v99, v255
	v_cvt_pk_bf16_f32 v100, v100, v101
	v_cvt_pk_bf16_f32 v101, v102, v103
	v_cvt_pk_bf16_f32 v102, v96, v97
	v_cvt_pk_bf16_f32 v103, v98, v99
	global_store_dwordx4 v240, v[100:103], s[12:13] offset:1024
	s_add_u32 s12, s12, 0x800
	s_addc_u32 s13, s13, 0
	v_mul_f32_e32 v248, 0xbfb8aa3b, v92
	v_mul_f32_e32 v249, 0xbfb8aa3b, v93
	v_mul_f32_e32 v250, 0xbfb8aa3b, v94
	v_mul_f32_e32 v251, 0xbfb8aa3b, v95
	v_mul_f32_e32 v252, 0xbfb8aa3b, v88
	v_mul_f32_e32 v253, 0xbfb8aa3b, v89
	v_mul_f32_e32 v254, 0xbfb8aa3b, v90
	v_mul_f32_e32 v255, 0xbfb8aa3b, v91
	v_exp_f32_e32 v248, v248
	v_exp_f32_e32 v249, v249
	v_exp_f32_e32 v250, v250
	v_exp_f32_e32 v251, v251
	v_exp_f32_e32 v252, v252
	v_exp_f32_e32 v253, v253
	v_exp_f32_e32 v254, v254
	v_exp_f32_e32 v255, v255
	v_add_f32_e32 v248, 1.0, v248
	v_add_f32_e32 v249, 1.0, v249
	v_add_f32_e32 v250, 1.0, v250
	v_add_f32_e32 v251, 1.0, v251
	v_add_f32_e32 v252, 1.0, v252
	v_add_f32_e32 v253, 1.0, v253
	v_add_f32_e32 v254, 1.0, v254
	v_add_f32_e32 v255, 1.0, v255
	v_rcp_f32_e32 v248, v248
	v_rcp_f32_e32 v249, v249
	v_rcp_f32_e32 v250, v250
	v_rcp_f32_e32 v251, v251
	v_rcp_f32_e32 v252, v252
	v_rcp_f32_e32 v253, v253
	v_rcp_f32_e32 v254, v254
	v_rcp_f32_e32 v255, v255
	v_mul_f32_e32 v92, v92, v248
	v_mul_f32_e32 v93, v93, v249
	v_mul_f32_e32 v94, v94, v250
	v_mul_f32_e32 v95, v95, v251
	v_mul_f32_e32 v88, v88, v252
	v_mul_f32_e32 v89, v89, v253
	v_mul_f32_e32 v90, v90, v254
	v_mul_f32_e32 v91, v91, v255
	v_cvt_pk_bf16_f32 v92, v92, v93
	v_cvt_pk_bf16_f32 v93, v94, v95
	v_cvt_pk_bf16_f32 v94, v88, v89
	v_cvt_pk_bf16_f32 v95, v90, v91
	global_store_dwordx4 v240, v[92:95], s[12:13]
	v_mul_f32_e32 v248, 0xbfb8aa3b, v84
	v_mul_f32_e32 v249, 0xbfb8aa3b, v85
	v_mul_f32_e32 v250, 0xbfb8aa3b, v86
	v_mul_f32_e32 v251, 0xbfb8aa3b, v87
	v_mul_f32_e32 v252, 0xbfb8aa3b, v80
	v_mul_f32_e32 v253, 0xbfb8aa3b, v81
	v_mul_f32_e32 v254, 0xbfb8aa3b, v82
	v_mul_f32_e32 v255, 0xbfb8aa3b, v83
	v_exp_f32_e32 v248, v248
	v_exp_f32_e32 v249, v249
	v_exp_f32_e32 v250, v250
	v_exp_f32_e32 v251, v251
	v_exp_f32_e32 v252, v252
	v_exp_f32_e32 v253, v253
	v_exp_f32_e32 v254, v254
	v_exp_f32_e32 v255, v255
	v_add_f32_e32 v248, 1.0, v248
	v_add_f32_e32 v249, 1.0, v249
	v_add_f32_e32 v250, 1.0, v250
	v_add_f32_e32 v251, 1.0, v251
	v_add_f32_e32 v252, 1.0, v252
	v_add_f32_e32 v253, 1.0, v253
	v_add_f32_e32 v254, 1.0, v254
	v_add_f32_e32 v255, 1.0, v255
	v_rcp_f32_e32 v248, v248
	v_rcp_f32_e32 v249, v249
	v_rcp_f32_e32 v250, v250
	v_rcp_f32_e32 v251, v251
	v_rcp_f32_e32 v252, v252
	v_rcp_f32_e32 v253, v253
	v_rcp_f32_e32 v254, v254
	v_rcp_f32_e32 v255, v255
	v_mul_f32_e32 v84, v84, v248
	v_mul_f32_e32 v85, v85, v249
	v_mul_f32_e32 v86, v86, v250
	v_mul_f32_e32 v87, v87, v251
	v_mul_f32_e32 v80, v80, v252
	v_mul_f32_e32 v81, v81, v253
	v_mul_f32_e32 v82, v82, v254
	v_mul_f32_e32 v83, v83, v255
	v_cvt_pk_bf16_f32 v84, v84, v85
	v_cvt_pk_bf16_f32 v85, v86, v87
	v_cvt_pk_bf16_f32 v86, v80, v81
	v_cvt_pk_bf16_f32 v87, v82, v83
	global_store_dwordx4 v240, v[84:87], s[12:13] offset:1024
	s_add_u32 s12, s12, 0x800
	s_addc_u32 s13, s13, 0
	v_mul_f32_e32 v248, 0xbfb8aa3b, v76
	v_mul_f32_e32 v249, 0xbfb8aa3b, v77
	v_mul_f32_e32 v250, 0xbfb8aa3b, v78
	v_mul_f32_e32 v251, 0xbfb8aa3b, v79
	v_mul_f32_e32 v252, 0xbfb8aa3b, v72
	v_mul_f32_e32 v253, 0xbfb8aa3b, v73
	v_mul_f32_e32 v254, 0xbfb8aa3b, v74
	v_mul_f32_e32 v255, 0xbfb8aa3b, v75
	v_exp_f32_e32 v248, v248
	v_exp_f32_e32 v249, v249
	v_exp_f32_e32 v250, v250
	v_exp_f32_e32 v251, v251
	v_exp_f32_e32 v252, v252
	v_exp_f32_e32 v253, v253
	v_exp_f32_e32 v254, v254
	v_exp_f32_e32 v255, v255
	v_add_f32_e32 v248, 1.0, v248
	v_add_f32_e32 v249, 1.0, v249
	v_add_f32_e32 v250, 1.0, v250
	v_add_f32_e32 v251, 1.0, v251
	v_add_f32_e32 v252, 1.0, v252
	v_add_f32_e32 v253, 1.0, v253
	v_add_f32_e32 v254, 1.0, v254
	v_add_f32_e32 v255, 1.0, v255
	v_rcp_f32_e32 v248, v248
	v_rcp_f32_e32 v249, v249
	v_rcp_f32_e32 v250, v250
	v_rcp_f32_e32 v251, v251
	v_rcp_f32_e32 v252, v252
	v_rcp_f32_e32 v253, v253
	v_rcp_f32_e32 v254, v254
	v_rcp_f32_e32 v255, v255
	v_mul_f32_e32 v76, v76, v248
	v_mul_f32_e32 v77, v77, v249
	v_mul_f32_e32 v78, v78, v250
	v_mul_f32_e32 v79, v79, v251
	v_mul_f32_e32 v72, v72, v252
	v_mul_f32_e32 v73, v73, v253
	v_mul_f32_e32 v74, v74, v254
	v_mul_f32_e32 v75, v75, v255
	v_cvt_pk_bf16_f32 v76, v76, v77
	v_cvt_pk_bf16_f32 v77, v78, v79
	v_cvt_pk_bf16_f32 v78, v72, v73
	v_cvt_pk_bf16_f32 v79, v74, v75
	global_store_dwordx4 v240, v[76:79], s[12:13]
	v_mul_f32_e32 v248, 0xbfb8aa3b, v68
	v_mul_f32_e32 v249, 0xbfb8aa3b, v69
	v_mul_f32_e32 v250, 0xbfb8aa3b, v70
	v_mul_f32_e32 v251, 0xbfb8aa3b, v71
	v_mul_f32_e32 v252, 0xbfb8aa3b, v64
	v_mul_f32_e32 v253, 0xbfb8aa3b, v65
	v_mul_f32_e32 v254, 0xbfb8aa3b, v66
	v_mul_f32_e32 v255, 0xbfb8aa3b, v67
	v_exp_f32_e32 v248, v248
	v_exp_f32_e32 v249, v249
	v_exp_f32_e32 v250, v250
	v_exp_f32_e32 v251, v251
	v_exp_f32_e32 v252, v252
	v_exp_f32_e32 v253, v253
	v_exp_f32_e32 v254, v254
	v_exp_f32_e32 v255, v255
	v_add_f32_e32 v248, 1.0, v248
	v_add_f32_e32 v249, 1.0, v249
	v_add_f32_e32 v250, 1.0, v250
	v_add_f32_e32 v251, 1.0, v251
	v_add_f32_e32 v252, 1.0, v252
	v_add_f32_e32 v253, 1.0, v253
	v_add_f32_e32 v254, 1.0, v254
	v_add_f32_e32 v255, 1.0, v255
	v_rcp_f32_e32 v248, v248
	v_rcp_f32_e32 v249, v249
	v_rcp_f32_e32 v250, v250
	v_rcp_f32_e32 v251, v251
	v_rcp_f32_e32 v252, v252
	v_rcp_f32_e32 v253, v253
	v_rcp_f32_e32 v254, v254
	v_rcp_f32_e32 v255, v255
	v_mul_f32_e32 v68, v68, v248
	v_mul_f32_e32 v69, v69, v249
	v_mul_f32_e32 v70, v70, v250
	v_mul_f32_e32 v71, v71, v251
	v_mul_f32_e32 v64, v64, v252
	v_mul_f32_e32 v65, v65, v253
	v_mul_f32_e32 v66, v66, v254
	v_mul_f32_e32 v67, v67, v255
	v_cvt_pk_bf16_f32 v68, v68, v69
	v_cvt_pk_bf16_f32 v69, v70, v71
	v_cvt_pk_bf16_f32 v70, v64, v65
	v_cvt_pk_bf16_f32 v71, v66, v67
	global_store_dwordx4 v240, v[68:71], s[12:13] offset:1024
	s_add_u32 s12, s12, 0x800
	s_addc_u32 s13, s13, 0
	v_mul_f32_e32 v248, 0xbfb8aa3b, v60
	v_mul_f32_e32 v249, 0xbfb8aa3b, v61
	v_mul_f32_e32 v250, 0xbfb8aa3b, v62
	v_mul_f32_e32 v251, 0xbfb8aa3b, v63
	v_mul_f32_e32 v252, 0xbfb8aa3b, v56
	v_mul_f32_e32 v253, 0xbfb8aa3b, v57
	v_mul_f32_e32 v254, 0xbfb8aa3b, v58
	v_mul_f32_e32 v255, 0xbfb8aa3b, v59
	v_exp_f32_e32 v248, v248
	v_exp_f32_e32 v249, v249
	v_exp_f32_e32 v250, v250
	v_exp_f32_e32 v251, v251
	v_exp_f32_e32 v252, v252
	v_exp_f32_e32 v253, v253
	v_exp_f32_e32 v254, v254
	v_exp_f32_e32 v255, v255
	v_add_f32_e32 v248, 1.0, v248
	v_add_f32_e32 v249, 1.0, v249
	v_add_f32_e32 v250, 1.0, v250
	v_add_f32_e32 v251, 1.0, v251
	v_add_f32_e32 v252, 1.0, v252
	v_add_f32_e32 v253, 1.0, v253
	v_add_f32_e32 v254, 1.0, v254
	v_add_f32_e32 v255, 1.0, v255
	v_rcp_f32_e32 v248, v248
	v_rcp_f32_e32 v249, v249
	v_rcp_f32_e32 v250, v250
	v_rcp_f32_e32 v251, v251
	v_rcp_f32_e32 v252, v252
	v_rcp_f32_e32 v253, v253
	v_rcp_f32_e32 v254, v254
	v_rcp_f32_e32 v255, v255
	v_mul_f32_e32 v60, v60, v248
	v_mul_f32_e32 v61, v61, v249
	v_mul_f32_e32 v62, v62, v250
	v_mul_f32_e32 v63, v63, v251
	v_mul_f32_e32 v56, v56, v252
	v_mul_f32_e32 v57, v57, v253
	v_mul_f32_e32 v58, v58, v254
	v_mul_f32_e32 v59, v59, v255
	v_cvt_pk_bf16_f32 v60, v60, v61
	v_cvt_pk_bf16_f32 v61, v62, v63
	v_cvt_pk_bf16_f32 v62, v56, v57
	v_cvt_pk_bf16_f32 v63, v58, v59
	global_store_dwordx4 v240, v[60:63], s[12:13]
	v_mul_f32_e32 v248, 0xbfb8aa3b, v52
	v_mul_f32_e32 v249, 0xbfb8aa3b, v53
	v_mul_f32_e32 v250, 0xbfb8aa3b, v54
	v_mul_f32_e32 v251, 0xbfb8aa3b, v55
	v_mul_f32_e32 v252, 0xbfb8aa3b, v48
	v_mul_f32_e32 v253, 0xbfb8aa3b, v49
	v_mul_f32_e32 v254, 0xbfb8aa3b, v50
	v_mul_f32_e32 v255, 0xbfb8aa3b, v51
	v_exp_f32_e32 v248, v248
	v_exp_f32_e32 v249, v249
	v_exp_f32_e32 v250, v250
	v_exp_f32_e32 v251, v251
	v_exp_f32_e32 v252, v252
	v_exp_f32_e32 v253, v253
	v_exp_f32_e32 v254, v254
	v_exp_f32_e32 v255, v255
	v_add_f32_e32 v248, 1.0, v248
	v_add_f32_e32 v249, 1.0, v249
	v_add_f32_e32 v250, 1.0, v250
	v_add_f32_e32 v251, 1.0, v251
	v_add_f32_e32 v252, 1.0, v252
	v_add_f32_e32 v253, 1.0, v253
	v_add_f32_e32 v254, 1.0, v254
	v_add_f32_e32 v255, 1.0, v255
	v_rcp_f32_e32 v248, v248
	v_rcp_f32_e32 v249, v249
	v_rcp_f32_e32 v250, v250
	v_rcp_f32_e32 v251, v251
	v_rcp_f32_e32 v252, v252
	v_rcp_f32_e32 v253, v253
	v_rcp_f32_e32 v254, v254
	v_rcp_f32_e32 v255, v255
	v_mul_f32_e32 v52, v52, v248
	v_mul_f32_e32 v53, v53, v249
	v_mul_f32_e32 v54, v54, v250
	v_mul_f32_e32 v55, v55, v251
	v_mul_f32_e32 v48, v48, v252
	v_mul_f32_e32 v49, v49, v253
	v_mul_f32_e32 v50, v50, v254
	v_mul_f32_e32 v51, v51, v255
	v_cvt_pk_bf16_f32 v52, v52, v53
	v_cvt_pk_bf16_f32 v53, v54, v55
	v_cvt_pk_bf16_f32 v54, v48, v49
	v_cvt_pk_bf16_f32 v55, v50, v51
	global_store_dwordx4 v240, v[52:55], s[12:13] offset:1024
	s_add_u32 s12, s12, 0x800
	s_addc_u32 s13, s13, 0
	v_mul_f32_e32 v248, 0xbfb8aa3b, v44
	v_mul_f32_e32 v249, 0xbfb8aa3b, v45
	v_mul_f32_e32 v250, 0xbfb8aa3b, v46
	v_mul_f32_e32 v251, 0xbfb8aa3b, v47
	v_mul_f32_e32 v252, 0xbfb8aa3b, v40
	v_mul_f32_e32 v253, 0xbfb8aa3b, v41
	v_mul_f32_e32 v254, 0xbfb8aa3b, v42
	v_mul_f32_e32 v255, 0xbfb8aa3b, v43
	v_exp_f32_e32 v248, v248
	v_exp_f32_e32 v249, v249
	v_exp_f32_e32 v250, v250
	v_exp_f32_e32 v251, v251
	v_exp_f32_e32 v252, v252
	v_exp_f32_e32 v253, v253
	v_exp_f32_e32 v254, v254
	v_exp_f32_e32 v255, v255
	v_add_f32_e32 v248, 1.0, v248
	v_add_f32_e32 v249, 1.0, v249
	v_add_f32_e32 v250, 1.0, v250
	v_add_f32_e32 v251, 1.0, v251
	v_add_f32_e32 v252, 1.0, v252
	v_add_f32_e32 v253, 1.0, v253
	v_add_f32_e32 v254, 1.0, v254
	v_add_f32_e32 v255, 1.0, v255
	v_rcp_f32_e32 v248, v248
	v_rcp_f32_e32 v249, v249
	v_rcp_f32_e32 v250, v250
	v_rcp_f32_e32 v251, v251
	v_rcp_f32_e32 v252, v252
	v_rcp_f32_e32 v253, v253
	v_rcp_f32_e32 v254, v254
	v_rcp_f32_e32 v255, v255
	v_mul_f32_e32 v44, v44, v248
	v_mul_f32_e32 v45, v45, v249
	v_mul_f32_e32 v46, v46, v250
	v_mul_f32_e32 v47, v47, v251
	v_mul_f32_e32 v40, v40, v252
	v_mul_f32_e32 v41, v41, v253
	v_mul_f32_e32 v42, v42, v254
	v_mul_f32_e32 v43, v43, v255
	v_cvt_pk_bf16_f32 v44, v44, v45
	v_cvt_pk_bf16_f32 v45, v46, v47
	v_cvt_pk_bf16_f32 v46, v40, v41
	v_cvt_pk_bf16_f32 v47, v42, v43
	global_store_dwordx4 v240, v[44:47], s[12:13]
	v_mul_f32_e32 v248, 0xbfb8aa3b, v36
	v_mul_f32_e32 v249, 0xbfb8aa3b, v37
	v_mul_f32_e32 v250, 0xbfb8aa3b, v38
	v_mul_f32_e32 v251, 0xbfb8aa3b, v39
	v_mul_f32_e32 v252, 0xbfb8aa3b, v32
	v_mul_f32_e32 v253, 0xbfb8aa3b, v33
	v_mul_f32_e32 v254, 0xbfb8aa3b, v34
	v_mul_f32_e32 v255, 0xbfb8aa3b, v35
	v_exp_f32_e32 v248, v248
	v_exp_f32_e32 v249, v249
	v_exp_f32_e32 v250, v250
	v_exp_f32_e32 v251, v251
	v_exp_f32_e32 v252, v252
	v_exp_f32_e32 v253, v253
	v_exp_f32_e32 v254, v254
	v_exp_f32_e32 v255, v255
	v_add_f32_e32 v248, 1.0, v248
	v_add_f32_e32 v249, 1.0, v249
	v_add_f32_e32 v250, 1.0, v250
	v_add_f32_e32 v251, 1.0, v251
	v_add_f32_e32 v252, 1.0, v252
	v_add_f32_e32 v253, 1.0, v253
	v_add_f32_e32 v254, 1.0, v254
	v_add_f32_e32 v255, 1.0, v255
	v_rcp_f32_e32 v248, v248
	v_rcp_f32_e32 v249, v249
	v_rcp_f32_e32 v250, v250
	v_rcp_f32_e32 v251, v251
	v_rcp_f32_e32 v252, v252
	v_rcp_f32_e32 v253, v253
	v_rcp_f32_e32 v254, v254
	v_rcp_f32_e32 v255, v255
	v_mul_f32_e32 v36, v36, v248
	v_mul_f32_e32 v37, v37, v249
	v_mul_f32_e32 v38, v38, v250
	v_mul_f32_e32 v39, v39, v251
	v_mul_f32_e32 v32, v32, v252
	v_mul_f32_e32 v33, v33, v253
	v_mul_f32_e32 v34, v34, v254
	v_mul_f32_e32 v35, v35, v255
	v_cvt_pk_bf16_f32 v36, v36, v37
	v_cvt_pk_bf16_f32 v37, v38, v39
	v_cvt_pk_bf16_f32 v38, v32, v33
	v_cvt_pk_bf16_f32 v39, v34, v35
	global_store_dwordx4 v240, v[36:39], s[12:13] offset:1024
	s_add_u32 s12, s12, 0x800
	s_addc_u32 s13, s13, 0
	v_mul_f32_e32 v248, 0xbfb8aa3b, v28
	v_mul_f32_e32 v249, 0xbfb8aa3b, v29
	v_mul_f32_e32 v250, 0xbfb8aa3b, v30
	v_mul_f32_e32 v251, 0xbfb8aa3b, v31
	v_mul_f32_e32 v252, 0xbfb8aa3b, v24
	v_mul_f32_e32 v253, 0xbfb8aa3b, v25
	v_mul_f32_e32 v254, 0xbfb8aa3b, v26
	v_mul_f32_e32 v255, 0xbfb8aa3b, v27
	v_exp_f32_e32 v248, v248
	v_exp_f32_e32 v249, v249
	v_exp_f32_e32 v250, v250
	v_exp_f32_e32 v251, v251
	v_exp_f32_e32 v252, v252
	v_exp_f32_e32 v253, v253
	v_exp_f32_e32 v254, v254
	v_exp_f32_e32 v255, v255
	v_add_f32_e32 v248, 1.0, v248
	v_add_f32_e32 v249, 1.0, v249
	v_add_f32_e32 v250, 1.0, v250
	v_add_f32_e32 v251, 1.0, v251
	v_add_f32_e32 v252, 1.0, v252
	v_add_f32_e32 v253, 1.0, v253
	v_add_f32_e32 v254, 1.0, v254
	v_add_f32_e32 v255, 1.0, v255
	v_rcp_f32_e32 v248, v248
	v_rcp_f32_e32 v249, v249
	v_rcp_f32_e32 v250, v250
	v_rcp_f32_e32 v251, v251
	v_rcp_f32_e32 v252, v252
	v_rcp_f32_e32 v253, v253
	v_rcp_f32_e32 v254, v254
	v_rcp_f32_e32 v255, v255
	v_mul_f32_e32 v28, v28, v248
	v_mul_f32_e32 v29, v29, v249
	v_mul_f32_e32 v30, v30, v250
	v_mul_f32_e32 v31, v31, v251
	v_mul_f32_e32 v24, v24, v252
	v_mul_f32_e32 v25, v25, v253
	v_mul_f32_e32 v26, v26, v254
	v_mul_f32_e32 v27, v27, v255
	v_cvt_pk_bf16_f32 v28, v28, v29
	v_cvt_pk_bf16_f32 v29, v30, v31
	v_cvt_pk_bf16_f32 v30, v24, v25
	v_cvt_pk_bf16_f32 v31, v26, v27
	global_store_dwordx4 v240, v[28:31], s[12:13]
	v_mul_f32_e32 v248, 0xbfb8aa3b, v20
	v_mul_f32_e32 v249, 0xbfb8aa3b, v21
	v_mul_f32_e32 v250, 0xbfb8aa3b, v22
	v_mul_f32_e32 v251, 0xbfb8aa3b, v23
	v_mul_f32_e32 v252, 0xbfb8aa3b, v16
	v_mul_f32_e32 v253, 0xbfb8aa3b, v17
	v_mul_f32_e32 v254, 0xbfb8aa3b, v18
	v_mul_f32_e32 v255, 0xbfb8aa3b, v19
	v_exp_f32_e32 v248, v248
	v_exp_f32_e32 v249, v249
	v_exp_f32_e32 v250, v250
	v_exp_f32_e32 v251, v251
	v_exp_f32_e32 v252, v252
	v_exp_f32_e32 v253, v253
	v_exp_f32_e32 v254, v254
	v_exp_f32_e32 v255, v255
	v_add_f32_e32 v248, 1.0, v248
	v_add_f32_e32 v249, 1.0, v249
	v_add_f32_e32 v250, 1.0, v250
	v_add_f32_e32 v251, 1.0, v251
	v_add_f32_e32 v252, 1.0, v252
	v_add_f32_e32 v253, 1.0, v253
	v_add_f32_e32 v254, 1.0, v254
	v_add_f32_e32 v255, 1.0, v255
	v_rcp_f32_e32 v248, v248
	v_rcp_f32_e32 v249, v249
	v_rcp_f32_e32 v250, v250
	v_rcp_f32_e32 v251, v251
	v_rcp_f32_e32 v252, v252
	v_rcp_f32_e32 v253, v253
	v_rcp_f32_e32 v254, v254
	v_rcp_f32_e32 v255, v255
	v_mul_f32_e32 v20, v20, v248
	v_mul_f32_e32 v21, v21, v249
	v_mul_f32_e32 v22, v22, v250
	v_mul_f32_e32 v23, v23, v251
	v_mul_f32_e32 v16, v16, v252
	v_mul_f32_e32 v17, v17, v253
	v_mul_f32_e32 v18, v18, v254
	v_mul_f32_e32 v19, v19, v255
	v_cvt_pk_bf16_f32 v20, v20, v21
	v_cvt_pk_bf16_f32 v21, v22, v23
	v_cvt_pk_bf16_f32 v22, v16, v17
	v_cvt_pk_bf16_f32 v23, v18, v19
	global_store_dwordx4 v240, v[20:23], s[12:13] offset:1024
	s_add_u32 s12, s12, 0x800
	s_addc_u32 s13, s13, 0
	v_mul_f32_e32 v248, 0xbfb8aa3b, v12
	v_mul_f32_e32 v249, 0xbfb8aa3b, v13
	v_mul_f32_e32 v250, 0xbfb8aa3b, v14
	v_mul_f32_e32 v251, 0xbfb8aa3b, v15
	v_mul_f32_e32 v252, 0xbfb8aa3b, v8
	v_mul_f32_e32 v253, 0xbfb8aa3b, v9
	v_mul_f32_e32 v254, 0xbfb8aa3b, v10
	v_mul_f32_e32 v255, 0xbfb8aa3b, v11
	v_exp_f32_e32 v248, v248
	v_exp_f32_e32 v249, v249
	v_exp_f32_e32 v250, v250
	v_exp_f32_e32 v251, v251
	v_exp_f32_e32 v252, v252
	v_exp_f32_e32 v253, v253
	v_exp_f32_e32 v254, v254
	v_exp_f32_e32 v255, v255
	v_add_f32_e32 v248, 1.0, v248
	v_add_f32_e32 v249, 1.0, v249
	v_add_f32_e32 v250, 1.0, v250
	v_add_f32_e32 v251, 1.0, v251
	v_add_f32_e32 v252, 1.0, v252
	v_add_f32_e32 v253, 1.0, v253
	v_add_f32_e32 v254, 1.0, v254
	v_add_f32_e32 v255, 1.0, v255
	v_rcp_f32_e32 v248, v248
	v_rcp_f32_e32 v249, v249
	v_rcp_f32_e32 v250, v250
	v_rcp_f32_e32 v251, v251
	v_rcp_f32_e32 v252, v252
	v_rcp_f32_e32 v253, v253
	v_rcp_f32_e32 v254, v254
	v_rcp_f32_e32 v255, v255
	v_mul_f32_e32 v12, v12, v248
	v_mul_f32_e32 v13, v13, v249
	v_mul_f32_e32 v14, v14, v250
	v_mul_f32_e32 v15, v15, v251
	v_mul_f32_e32 v8, v8, v252
	v_mul_f32_e32 v9, v9, v253
	v_mul_f32_e32 v10, v10, v254
	v_mul_f32_e32 v11, v11, v255
	v_cvt_pk_bf16_f32 v12, v12, v13
	v_cvt_pk_bf16_f32 v13, v14, v15
	v_cvt_pk_bf16_f32 v14, v8, v9
	v_cvt_pk_bf16_f32 v15, v10, v11
	global_store_dwordx4 v240, v[12:15], s[12:13]
	v_mul_f32_e32 v248, 0xbfb8aa3b, v4
	v_mul_f32_e32 v249, 0xbfb8aa3b, v5
	v_mul_f32_e32 v250, 0xbfb8aa3b, v6
	v_mul_f32_e32 v251, 0xbfb8aa3b, v7
	v_mul_f32_e32 v252, 0xbfb8aa3b, v0
	v_mul_f32_e32 v253, 0xbfb8aa3b, v1
	v_mul_f32_e32 v254, 0xbfb8aa3b, v2
	v_mul_f32_e32 v255, 0xbfb8aa3b, v3
	v_exp_f32_e32 v248, v248
	v_exp_f32_e32 v249, v249
	v_exp_f32_e32 v250, v250
	v_exp_f32_e32 v251, v251
	v_exp_f32_e32 v252, v252
	v_exp_f32_e32 v253, v253
	v_exp_f32_e32 v254, v254
	v_exp_f32_e32 v255, v255
	v_add_f32_e32 v248, 1.0, v248
	v_add_f32_e32 v249, 1.0, v249
	v_add_f32_e32 v250, 1.0, v250
	v_add_f32_e32 v251, 1.0, v251
	v_add_f32_e32 v252, 1.0, v252
	v_add_f32_e32 v253, 1.0, v253
	v_add_f32_e32 v254, 1.0, v254
	v_add_f32_e32 v255, 1.0, v255
	v_rcp_f32_e32 v248, v248
	v_rcp_f32_e32 v249, v249
	v_rcp_f32_e32 v250, v250
	v_rcp_f32_e32 v251, v251
	v_rcp_f32_e32 v252, v252
	v_rcp_f32_e32 v253, v253
	v_rcp_f32_e32 v254, v254
	v_rcp_f32_e32 v255, v255
	v_mul_f32_e32 v4, v4, v248
	v_mul_f32_e32 v5, v5, v249
	v_mul_f32_e32 v6, v6, v250
	v_mul_f32_e32 v7, v7, v251
	v_mul_f32_e32 v0, v0, v252
	v_mul_f32_e32 v1, v1, v253
	v_mul_f32_e32 v2, v2, v254
	v_mul_f32_e32 v3, v3, v255
	v_cvt_pk_bf16_f32 v4, v4, v5
	v_cvt_pk_bf16_f32 v5, v6, v7
	v_cvt_pk_bf16_f32 v6, v0, v1
	v_cvt_pk_bf16_f32 v7, v2, v3
	global_store_dwordx4 v240, v[4:7], s[12:13] offset:1024
	s_branch .Lfe_join
.Lfe_gf_sig:
	v_mul_f32_e32 v248, 0xbfb8aa3b, v124
	v_mul_f32_e32 v249, 0xbfb8aa3b, v125
	v_mul_f32_e32 v250, 0xbfb8aa3b, v126
	v_mul_f32_e32 v251, 0xbfb8aa3b, v127
	v_mul_f32_e32 v252, 0xbfb8aa3b, v120
	v_mul_f32_e32 v253, 0xbfb8aa3b, v121
	v_mul_f32_e32 v254, 0xbfb8aa3b, v122
	v_mul_f32_e32 v255, 0xbfb8aa3b, v123
	v_exp_f32_e32 v248, v248
	v_exp_f32_e32 v249, v249
	v_exp_f32_e32 v250, v250
	v_exp_f32_e32 v251, v251
	v_exp_f32_e32 v252, v252
	v_exp_f32_e32 v253, v253
	v_exp_f32_e32 v254, v254
	v_exp_f32_e32 v255, v255
	v_add_f32_e32 v124, 1.0, v248
	v_add_f32_e32 v125, 1.0, v249
	v_add_f32_e32 v126, 1.0, v250
	v_add_f32_e32 v127, 1.0, v251
	v_add_f32_e32 v120, 1.0, v252
	v_add_f32_e32 v121, 1.0, v253
	v_add_f32_e32 v122, 1.0, v254
	v_add_f32_e32 v123, 1.0, v255
	v_cvt_pk_bf16_f32 v124, v124, v125
	v_cvt_pk_bf16_f32 v125, v126, v127
	v_cvt_pk_bf16_f32 v126, v120, v121
	v_cvt_pk_bf16_f32 v127, v122, v123
	global_store_dwordx4 v240, v[124:127], s[12:13]
	v_mul_f32_e32 v248, 0xbfb8aa3b, v116
	v_mul_f32_e32 v249, 0xbfb8aa3b, v117
	v_mul_f32_e32 v250, 0xbfb8aa3b, v118
	v_mul_f32_e32 v251, 0xbfb8aa3b, v119
	v_mul_f32_e32 v252, 0xbfb8aa3b, v112
	v_mul_f32_e32 v253, 0xbfb8aa3b, v113
	v_mul_f32_e32 v254, 0xbfb8aa3b, v114
	v_mul_f32_e32 v255, 0xbfb8aa3b, v115
	v_exp_f32_e32 v248, v248
	v_exp_f32_e32 v249, v249
	v_exp_f32_e32 v250, v250
	v_exp_f32_e32 v251, v251
	v_exp_f32_e32 v252, v252
	v_exp_f32_e32 v253, v253
	v_exp_f32_e32 v254, v254
	v_exp_f32_e32 v255, v255
	v_add_f32_e32 v116, 1.0, v248
	v_add_f32_e32 v117, 1.0, v249
	v_add_f32_e32 v118, 1.0, v250
	v_add_f32_e32 v119, 1.0, v251
	v_add_f32_e32 v112, 1.0, v252
	v_add_f32_e32 v113, 1.0, v253
	v_add_f32_e32 v114, 1.0, v254
	v_add_f32_e32 v115, 1.0, v255
	v_cvt_pk_bf16_f32 v116, v116, v117
	v_cvt_pk_bf16_f32 v117, v118, v119
	v_cvt_pk_bf16_f32 v118, v112, v113
	v_cvt_pk_bf16_f32 v119, v114, v115
	global_store_dwordx4 v240, v[116:119], s[12:13] offset:1024
	s_add_u32 s12, s12, 0x800
	s_addc_u32 s13, s13, 0
	v_mul_f32_e32 v248, 0xbfb8aa3b, v108
	v_mul_f32_e32 v249, 0xbfb8aa3b, v109
	v_mul_f32_e32 v250, 0xbfb8aa3b, v110
	v_mul_f32_e32 v251, 0xbfb8aa3b, v111
	v_mul_f32_e32 v252, 0xbfb8aa3b, v104
	v_mul_f32_e32 v253, 0xbfb8aa3b, v105
	v_mul_f32_e32 v254, 0xbfb8aa3b, v106
	v_mul_f32_e32 v255, 0xbfb8aa3b, v107
	v_exp_f32_e32 v248, v248
	v_exp_f32_e32 v249, v249
	v_exp_f32_e32 v250, v250
	v_exp_f32_e32 v251, v251
	v_exp_f32_e32 v252, v252
	v_exp_f32_e32 v253, v253
	v_exp_f32_e32 v254, v254
	v_exp_f32_e32 v255, v255
	v_add_f32_e32 v108, 1.0, v248
	v_add_f32_e32 v109, 1.0, v249
	v_add_f32_e32 v110, 1.0, v250
	v_add_f32_e32 v111, 1.0, v251
	v_add_f32_e32 v104, 1.0, v252
	v_add_f32_e32 v105, 1.0, v253
	v_add_f32_e32 v106, 1.0, v254
	v_add_f32_e32 v107, 1.0, v255
	v_cvt_pk_bf16_f32 v108, v108, v109
	v_cvt_pk_bf16_f32 v109, v110, v111
	v_cvt_pk_bf16_f32 v110, v104, v105
	v_cvt_pk_bf16_f32 v111, v106, v107
	global_store_dwordx4 v240, v[108:111], s[12:13]
	v_mul_f32_e32 v248, 0xbfb8aa3b, v100
	v_mul_f32_e32 v249, 0xbfb8aa3b, v101
	v_mul_f32_e32 v250, 0xbfb8aa3b, v102
	v_mul_f32_e32 v251, 0xbfb8aa3b, v103
	v_mul_f32_e32 v252, 0xbfb8aa3b, v96
	v_mul_f32_e32 v253, 0xbfb8aa3b, v97
	v_mul_f32_e32 v254, 0xbfb8aa3b, v98
	v_mul_f32_e32 v255, 0xbfb8aa3b, v99
	v_exp_f32_e32 v248, v248
	v_exp_f32_e32 v249, v249
	v_exp_f32_e32 v250, v250
	v_exp_f32_e32 v251, v251
	v_exp_f32_e32 v252, v252
	v_exp_f32_e32 v253, v253
	v_exp_f32_e32 v254, v254
	v_exp_f32_e32 v255, v255
	v_add_f32_e32 v100, 1.0, v248
	v_add_f32_e32 v101, 1.0, v249
	v_add_f32_e32 v102, 1.0, v250
	v_add_f32_e32 v103, 1.0, v251
	v_add_f32_e32 v96, 1.0, v252
	v_add_f32_e32 v97, 1.0, v253
	v_add_f32_e32 v98, 1.0, v254
	v_add_f32_e32 v99, 1.0, v255
	v_cvt_pk_bf16_f32 v100, v100, v101
	v_cvt_pk_bf16_f32 v101, v102, v103
	v_cvt_pk_bf16_f32 v102, v96, v97
	v_cvt_pk_bf16_f32 v103, v98, v99
	global_store_dwordx4 v240, v[100:103], s[12:13] offset:1024
	s_add_u32 s12, s12, 0x800
	s_addc_u32 s13, s13, 0
	v_mul_f32_e32 v248, 0xbfb8aa3b, v92
	v_mul_f32_e32 v249, 0xbfb8aa3b, v93
	v_mul_f32_e32 v250, 0xbfb8aa3b, v94
	v_mul_f32_e32 v251, 0xbfb8aa3b, v95
	v_mul_f32_e32 v252, 0xbfb8aa3b, v88
	v_mul_f32_e32 v253, 0xbfb8aa3b, v89
	v_mul_f32_e32 v254, 0xbfb8aa3b, v90
	v_mul_f32_e32 v255, 0xbfb8aa3b, v91
	v_exp_f32_e32 v248, v248
	v_exp_f32_e32 v249, v249
	v_exp_f32_e32 v250, v250
	v_exp_f32_e32 v251, v251
	v_exp_f32_e32 v252, v252
	v_exp_f32_e32 v253, v253
	v_exp_f32_e32 v254, v254
	v_exp_f32_e32 v255, v255
	v_add_f32_e32 v92, 1.0, v248
	v_add_f32_e32 v93, 1.0, v249
	v_add_f32_e32 v94, 1.0, v250
	v_add_f32_e32 v95, 1.0, v251
	v_add_f32_e32 v88, 1.0, v252
	v_add_f32_e32 v89, 1.0, v253
	v_add_f32_e32 v90, 1.0, v254
	v_add_f32_e32 v91, 1.0, v255
	v_cvt_pk_bf16_f32 v92, v92, v93
	v_cvt_pk_bf16_f32 v93, v94, v95
	v_cvt_pk_bf16_f32 v94, v88, v89
	v_cvt_pk_bf16_f32 v95, v90, v91
	global_store_dwordx4 v240, v[92:95], s[12:13]
	v_mul_f32_e32 v248, 0xbfb8aa3b, v84
	v_mul_f32_e32 v249, 0xbfb8aa3b, v85
	v_mul_f32_e32 v250, 0xbfb8aa3b, v86
	v_mul_f32_e32 v251, 0xbfb8aa3b, v87
	v_mul_f32_e32 v252, 0xbfb8aa3b, v80
	v_mul_f32_e32 v253, 0xbfb8aa3b, v81
	v_mul_f32_e32 v254, 0xbfb8aa3b, v82
	v_mul_f32_e32 v255, 0xbfb8aa3b, v83
	v_exp_f32_e32 v248, v248
	v_exp_f32_e32 v249, v249
	v_exp_f32_e32 v250, v250
	v_exp_f32_e32 v251, v251
	v_exp_f32_e32 v252, v252
	v_exp_f32_e32 v253, v253
	v_exp_f32_e32 v254, v254
	v_exp_f32_e32 v255, v255
	v_add_f32_e32 v84, 1.0, v248
	v_add_f32_e32 v85, 1.0, v249
	v_add_f32_e32 v86, 1.0, v250
	v_add_f32_e32 v87, 1.0, v251
	v_add_f32_e32 v80, 1.0, v252
	v_add_f32_e32 v81, 1.0, v253
	v_add_f32_e32 v82, 1.0, v254
	v_add_f32_e32 v83, 1.0, v255
	v_cvt_pk_bf16_f32 v84, v84, v85
	v_cvt_pk_bf16_f32 v85, v86, v87
	v_cvt_pk_bf16_f32 v86, v80, v81
	v_cvt_pk_bf16_f32 v87, v82, v83
	global_store_dwordx4 v240, v[84:87], s[12:13] offset:1024
	s_add_u32 s12, s12, 0x800
	s_addc_u32 s13, s13, 0
	v_mul_f32_e32 v248, 0xbfb8aa3b, v76
	v_mul_f32_e32 v249, 0xbfb8aa3b, v77
	v_mul_f32_e32 v250, 0xbfb8aa3b, v78
	v_mul_f32_e32 v251, 0xbfb8aa3b, v79
	v_mul_f32_e32 v252, 0xbfb8aa3b, v72
	v_mul_f32_e32 v253, 0xbfb8aa3b, v73
	v_mul_f32_e32 v254, 0xbfb8aa3b, v74
	v_mul_f32_e32 v255, 0xbfb8aa3b, v75
	v_exp_f32_e32 v248, v248
	v_exp_f32_e32 v249, v249
	v_exp_f32_e32 v250, v250
	v_exp_f32_e32 v251, v251
	v_exp_f32_e32 v252, v252
	v_exp_f32_e32 v253, v253
	v_exp_f32_e32 v254, v254
	v_exp_f32_e32 v255, v255
	v_add_f32_e32 v76, 1.0, v248
	v_add_f32_e32 v77, 1.0, v249
	v_add_f32_e32 v78, 1.0, v250
	v_add_f32_e32 v79, 1.0, v251
	v_add_f32_e32 v72, 1.0, v252
	v_add_f32_e32 v73, 1.0, v253
	v_add_f32_e32 v74, 1.0, v254
	v_add_f32_e32 v75, 1.0, v255
	v_cvt_pk_bf16_f32 v76, v76, v77
	v_cvt_pk_bf16_f32 v77, v78, v79
	v_cvt_pk_bf16_f32 v78, v72, v73
	v_cvt_pk_bf16_f32 v79, v74, v75
	global_store_dwordx4 v240, v[76:79], s[12:13]
	v_mul_f32_e32 v248, 0xbfb8aa3b, v68
	v_mul_f32_e32 v249, 0xbfb8aa3b, v69
	v_mul_f32_e32 v250, 0xbfb8aa3b, v70
	v_mul_f32_e32 v251, 0xbfb8aa3b, v71
	v_mul_f32_e32 v252, 0xbfb8aa3b, v64
	v_mul_f32_e32 v253, 0xbfb8aa3b, v65
	v_mul_f32_e32 v254, 0xbfb8aa3b, v66
	v_mul_f32_e32 v255, 0xbfb8aa3b, v67
	v_exp_f32_e32 v248, v248
	v_exp_f32_e32 v249, v249
	v_exp_f32_e32 v250, v250
	v_exp_f32_e32 v251, v251
	v_exp_f32_e32 v252, v252
	v_exp_f32_e32 v253, v253
	v_exp_f32_e32 v254, v254
	v_exp_f32_e32 v255, v255
	v_add_f32_e32 v68, 1.0, v248
	v_add_f32_e32 v69, 1.0, v249
	v_add_f32_e32 v70, 1.0, v250
	v_add_f32_e32 v71, 1.0, v251
	v_add_f32_e32 v64, 1.0, v252
	v_add_f32_e32 v65, 1.0, v253
	v_add_f32_e32 v66, 1.0, v254
	v_add_f32_e32 v67, 1.0, v255
	v_cvt_pk_bf16_f32 v68, v68, v69
	v_cvt_pk_bf16_f32 v69, v70, v71
	v_cvt_pk_bf16_f32 v70, v64, v65
	v_cvt_pk_bf16_f32 v71, v66, v67
	global_store_dwordx4 v240, v[68:71], s[12:13] offset:1024
	s_add_u32 s12, s12, 0x800
	s_addc_u32 s13, s13, 0
	v_mul_f32_e32 v248, 0xbfb8aa3b, v60
	v_mul_f32_e32 v249, 0xbfb8aa3b, v61
	v_mul_f32_e32 v250, 0xbfb8aa3b, v62
	v_mul_f32_e32 v251, 0xbfb8aa3b, v63
	v_mul_f32_e32 v252, 0xbfb8aa3b, v56
	v_mul_f32_e32 v253, 0xbfb8aa3b, v57
	v_mul_f32_e32 v254, 0xbfb8aa3b, v58
	v_mul_f32_e32 v255, 0xbfb8aa3b, v59
	v_exp_f32_e32 v248, v248
	v_exp_f32_e32 v249, v249
	v_exp_f32_e32 v250, v250
	v_exp_f32_e32 v251, v251
	v_exp_f32_e32 v252, v252
	v_exp_f32_e32 v253, v253
	v_exp_f32_e32 v254, v254
	v_exp_f32_e32 v255, v255
	v_add_f32_e32 v60, 1.0, v248
	v_add_f32_e32 v61, 1.0, v249
	v_add_f32_e32 v62, 1.0, v250
	v_add_f32_e32 v63, 1.0, v251
	v_add_f32_e32 v56, 1.0, v252
	v_add_f32_e32 v57, 1.0, v253
	v_add_f32_e32 v58, 1.0, v254
	v_add_f32_e32 v59, 1.0, v255
	v_cvt_pk_bf16_f32 v60, v60, v61
	v_cvt_pk_bf16_f32 v61, v62, v63
	v_cvt_pk_bf16_f32 v62, v56, v57
	v_cvt_pk_bf16_f32 v63, v58, v59
	global_store_dwordx4 v240, v[60:63], s[12:13]
	v_mul_f32_e32 v248, 0xbfb8aa3b, v52
	v_mul_f32_e32 v249, 0xbfb8aa3b, v53
	v_mul_f32_e32 v250, 0xbfb8aa3b, v54
	v_mul_f32_e32 v251, 0xbfb8aa3b, v55
	v_mul_f32_e32 v252, 0xbfb8aa3b, v48
	v_mul_f32_e32 v253, 0xbfb8aa3b, v49
	v_mul_f32_e32 v254, 0xbfb8aa3b, v50
	v_mul_f32_e32 v255, 0xbfb8aa3b, v51
	v_exp_f32_e32 v248, v248
	v_exp_f32_e32 v249, v249
	v_exp_f32_e32 v250, v250
	v_exp_f32_e32 v251, v251
	v_exp_f32_e32 v252, v252
	v_exp_f32_e32 v253, v253
	v_exp_f32_e32 v254, v254
	v_exp_f32_e32 v255, v255
	v_add_f32_e32 v52, 1.0, v248
	v_add_f32_e32 v53, 1.0, v249
	v_add_f32_e32 v54, 1.0, v250
	v_add_f32_e32 v55, 1.0, v251
	v_add_f32_e32 v48, 1.0, v252
	v_add_f32_e32 v49, 1.0, v253
	v_add_f32_e32 v50, 1.0, v254
	v_add_f32_e32 v51, 1.0, v255
	v_cvt_pk_bf16_f32 v52, v52, v53
	v_cvt_pk_bf16_f32 v53, v54, v55
	v_cvt_pk_bf16_f32 v54, v48, v49
	v_cvt_pk_bf16_f32 v55, v50, v51
	global_store_dwordx4 v240, v[52:55], s[12:13] offset:1024
	s_add_u32 s12, s12, 0x800
	s_addc_u32 s13, s13, 0
	v_mul_f32_e32 v248, 0xbfb8aa3b, v44
	v_mul_f32_e32 v249, 0xbfb8aa3b, v45
	v_mul_f32_e32 v250, 0xbfb8aa3b, v46
	v_mul_f32_e32 v251, 0xbfb8aa3b, v47
	v_mul_f32_e32 v252, 0xbfb8aa3b, v40
	v_mul_f32_e32 v253, 0xbfb8aa3b, v41
	v_mul_f32_e32 v254, 0xbfb8aa3b, v42
	v_mul_f32_e32 v255, 0xbfb8aa3b, v43
	v_exp_f32_e32 v248, v248
	v_exp_f32_e32 v249, v249
	v_exp_f32_e32 v250, v250
	v_exp_f32_e32 v251, v251
	v_exp_f32_e32 v252, v252
	v_exp_f32_e32 v253, v253
	v_exp_f32_e32 v254, v254
	v_exp_f32_e32 v255, v255
	v_add_f32_e32 v44, 1.0, v248
	v_add_f32_e32 v45, 1.0, v249
	v_add_f32_e32 v46, 1.0, v250
	v_add_f32_e32 v47, 1.0, v251
	v_add_f32_e32 v40, 1.0, v252
	v_add_f32_e32 v41, 1.0, v253
	v_add_f32_e32 v42, 1.0, v254
	v_add_f32_e32 v43, 1.0, v255
	v_cvt_pk_bf16_f32 v44, v44, v45
	v_cvt_pk_bf16_f32 v45, v46, v47
	v_cvt_pk_bf16_f32 v46, v40, v41
	v_cvt_pk_bf16_f32 v47, v42, v43
	global_store_dwordx4 v240, v[44:47], s[12:13]
	v_mul_f32_e32 v248, 0xbfb8aa3b, v36
	v_mul_f32_e32 v249, 0xbfb8aa3b, v37
	v_mul_f32_e32 v250, 0xbfb8aa3b, v38
	v_mul_f32_e32 v251, 0xbfb8aa3b, v39
	v_mul_f32_e32 v252, 0xbfb8aa3b, v32
	v_mul_f32_e32 v253, 0xbfb8aa3b, v33
	v_mul_f32_e32 v254, 0xbfb8aa3b, v34
	v_mul_f32_e32 v255, 0xbfb8aa3b, v35
	v_exp_f32_e32 v248, v248
	v_exp_f32_e32 v249, v249
	v_exp_f32_e32 v250, v250
	v_exp_f32_e32 v251, v251
	v_exp_f32_e32 v252, v252
	v_exp_f32_e32 v253, v253
	v_exp_f32_e32 v254, v254
	v_exp_f32_e32 v255, v255
	v_add_f32_e32 v36, 1.0, v248
	v_add_f32_e32 v37, 1.0, v249
	v_add_f32_e32 v38, 1.0, v250
	v_add_f32_e32 v39, 1.0, v251
	v_add_f32_e32 v32, 1.0, v252
	v_add_f32_e32 v33, 1.0, v253
	v_add_f32_e32 v34, 1.0, v254
	v_add_f32_e32 v35, 1.0, v255
	v_cvt_pk_bf16_f32 v36, v36, v37
	v_cvt_pk_bf16_f32 v37, v38, v39
	v_cvt_pk_bf16_f32 v38, v32, v33
	v_cvt_pk_bf16_f32 v39, v34, v35
	global_store_dwordx4 v240, v[36:39], s[12:13] offset:1024
	s_add_u32 s12, s12, 0x800
	s_addc_u32 s13, s13, 0
	v_mul_f32_e32 v248, 0xbfb8aa3b, v28
	v_mul_f32_e32 v249, 0xbfb8aa3b, v29
	v_mul_f32_e32 v250, 0xbfb8aa3b, v30
	v_mul_f32_e32 v251, 0xbfb8aa3b, v31
	v_mul_f32_e32 v252, 0xbfb8aa3b, v24
	v_mul_f32_e32 v253, 0xbfb8aa3b, v25
	v_mul_f32_e32 v254, 0xbfb8aa3b, v26
	v_mul_f32_e32 v255, 0xbfb8aa3b, v27
	v_exp_f32_e32 v248, v248
	v_exp_f32_e32 v249, v249
	v_exp_f32_e32 v250, v250
	v_exp_f32_e32 v251, v251
	v_exp_f32_e32 v252, v252
	v_exp_f32_e32 v253, v253
	v_exp_f32_e32 v254, v254
	v_exp_f32_e32 v255, v255
	v_add_f32_e32 v28, 1.0, v248
	v_add_f32_e32 v29, 1.0, v249
	v_add_f32_e32 v30, 1.0, v250
	v_add_f32_e32 v31, 1.0, v251
	v_add_f32_e32 v24, 1.0, v252
	v_add_f32_e32 v25, 1.0, v253
	v_add_f32_e32 v26, 1.0, v254
	v_add_f32_e32 v27, 1.0, v255
	v_cvt_pk_bf16_f32 v28, v28, v29
	v_cvt_pk_bf16_f32 v29, v30, v31
	v_cvt_pk_bf16_f32 v30, v24, v25
	v_cvt_pk_bf16_f32 v31, v26, v27
	global_store_dwordx4 v240, v[28:31], s[12:13]
	v_mul_f32_e32 v248, 0xbfb8aa3b, v20
	v_mul_f32_e32 v249, 0xbfb8aa3b, v21
	v_mul_f32_e32 v250, 0xbfb8aa3b, v22
	v_mul_f32_e32 v251, 0xbfb8aa3b, v23
	v_mul_f32_e32 v252, 0xbfb8aa3b, v16
	v_mul_f32_e32 v253, 0xbfb8aa3b, v17
	v_mul_f32_e32 v254, 0xbfb8aa3b, v18
	v_mul_f32_e32 v255, 0xbfb8aa3b, v19
	v_exp_f32_e32 v248, v248
	v_exp_f32_e32 v249, v249
	v_exp_f32_e32 v250, v250
	v_exp_f32_e32 v251, v251
	v_exp_f32_e32 v252, v252
	v_exp_f32_e32 v253, v253
	v_exp_f32_e32 v254, v254
	v_exp_f32_e32 v255, v255
	v_add_f32_e32 v20, 1.0, v248
	v_add_f32_e32 v21, 1.0, v249
	v_add_f32_e32 v22, 1.0, v250
	v_add_f32_e32 v23, 1.0, v251
	v_add_f32_e32 v16, 1.0, v252
	v_add_f32_e32 v17, 1.0, v253
	v_add_f32_e32 v18, 1.0, v254
	v_add_f32_e32 v19, 1.0, v255
	v_cvt_pk_bf16_f32 v20, v20, v21
	v_cvt_pk_bf16_f32 v21, v22, v23
	v_cvt_pk_bf16_f32 v22, v16, v17
	v_cvt_pk_bf16_f32 v23, v18, v19
	global_store_dwordx4 v240, v[20:23], s[12:13] offset:1024
	s_add_u32 s12, s12, 0x800
	s_addc_u32 s13, s13, 0
	v_mul_f32_e32 v248, 0xbfb8aa3b, v12
	v_mul_f32_e32 v249, 0xbfb8aa3b, v13
	v_mul_f32_e32 v250, 0xbfb8aa3b, v14
	v_mul_f32_e32 v251, 0xbfb8aa3b, v15
	v_mul_f32_e32 v252, 0xbfb8aa3b, v8
	v_mul_f32_e32 v253, 0xbfb8aa3b, v9
	v_mul_f32_e32 v254, 0xbfb8aa3b, v10
	v_mul_f32_e32 v255, 0xbfb8aa3b, v11
	v_exp_f32_e32 v248, v248
	v_exp_f32_e32 v249, v249
	v_exp_f32_e32 v250, v250
	v_exp_f32_e32 v251, v251
	v_exp_f32_e32 v252, v252
	v_exp_f32_e32 v253, v253
	v_exp_f32_e32 v254, v254
	v_exp_f32_e32 v255, v255
	v_add_f32_e32 v12, 1.0, v248
	v_add_f32_e32 v13, 1.0, v249
	v_add_f32_e32 v14, 1.0, v250
	v_add_f32_e32 v15, 1.0, v251
	v_add_f32_e32 v8, 1.0, v252
	v_add_f32_e32 v9, 1.0, v253
	v_add_f32_e32 v10, 1.0, v254
	v_add_f32_e32 v11, 1.0, v255
	v_cvt_pk_bf16_f32 v12, v12, v13
	v_cvt_pk_bf16_f32 v13, v14, v15
	v_cvt_pk_bf16_f32 v14, v8, v9
	v_cvt_pk_bf16_f32 v15, v10, v11
	global_store_dwordx4 v240, v[12:15], s[12:13]
	v_mul_f32_e32 v248, 0xbfb8aa3b, v4
	v_mul_f32_e32 v249, 0xbfb8aa3b, v5
	v_mul_f32_e32 v250, 0xbfb8aa3b, v6
	v_mul_f32_e32 v251, 0xbfb8aa3b, v7
	v_mul_f32_e32 v252, 0xbfb8aa3b, v0
	v_mul_f32_e32 v253, 0xbfb8aa3b, v1
	v_mul_f32_e32 v254, 0xbfb8aa3b, v2
	v_mul_f32_e32 v255, 0xbfb8aa3b, v3
	v_exp_f32_e32 v248, v248
	v_exp_f32_e32 v249, v249
	v_exp_f32_e32 v250, v250
	v_exp_f32_e32 v251, v251
	v_exp_f32_e32 v252, v252
	v_exp_f32_e32 v253, v253
	v_exp_f32_e32 v254, v254
	v_exp_f32_e32 v255, v255
	v_add_f32_e32 v4, 1.0, v248
	v_add_f32_e32 v5, 1.0, v249
	v_add_f32_e32 v6, 1.0, v250
	v_add_f32_e32 v7, 1.0, v251
	v_add_f32_e32 v0, 1.0, v252
	v_add_f32_e32 v1, 1.0, v253
	v_add_f32_e32 v2, 1.0, v254
	v_add_f32_e32 v3, 1.0, v255
	v_cvt_pk_bf16_f32 v4, v4, v5
	v_cvt_pk_bf16_f32 v5, v6, v7
	v_cvt_pk_bf16_f32 v6, v0, v1
	v_cvt_pk_bf16_f32 v7, v2, v3
	global_store_dwordx4 v240, v[4:7], s[12:13] offset:1024
.Lfe_join:
	s_andn2_b64 vcc, exec, s[42:43]
	s_mov_b64 s[8:9], -1
	s_cbranch_vccnz .LBB0_295
	s_branch .Lfe_tail

.Lfe_tail:
	s_andn2_b64 vcc, exec, s[2:3]
	s_cbranch_vccnz .LBB0_294
	s_barrier
	s_branch .LBB0_294

.LBB0_925:
	s_bfe_u32 s8, s36, 0x10002
	s_lshl_b32 s1, s8, 12
	s_or_b32 s14, s1, 0x2000
	s_ashr_i32 s0, s36, 3
	s_and_b32 s9, s36, 3
	s_mul_i32 s1, s14, 0x2080
	s_add_u32 s1, s12, s1
	s_addc_u32 s3, s13, 0
	s_lshl_b32 s40, s9, 8
	s_add_u32 s2, s1, s40
	s_addc_u32 s3, s3, 0
	s_lshl_b32 s1, s9, 22
	s_add_u32 s1, s4, s1
	s_addc_u32 s7, s5, 0
	s_lshl_b32 s6, s14, 1
	s_add_u32 s6, s1, s6
	s_addc_u32 s7, s7, 0
	s_ashr_i32 s1, s0, 31
	s_lshl_b64 s[0:1], s[0:1], 7
	v_mov_b32_e32 v194, v206
	s_add_u32 s0, s0, s14
	s_addc_u32 s14, s1, 0
	v_readfirstlane_b32 s37, v194
	s_bfe_u32 s38, s37, 0x20006
	v_and_or_b32 v0, v194, 31, s0
	v_lshl_or_b32 v196, s38, 5, v0
	v_mov_b64_e32 v[0:1], s[12:13]
	s_ashr_i32 s39, s37, 8
	v_mad_u64_u32 v[162:163], s[0:1], v196, s79, v[0:1]
	v_mad_i32_i24 v163, s14, v211, v163
	s_lshl_b32 s0, s39, 6
	v_mov_b32_e32 v24, v206
	v_lshl_add_u64 v[0:1], v[162:163], 0, s[40:41]
	s_ashr_i32 s1, s0, 31
	v_lshl_add_u64 v[0:1], s[0:1], 1, v[0:1]
	v_lshrrev_b32_e32 v2, 1, v24
	v_and_b32_e32 v164, 16, v2
	v_mov_b32_e32 v165, v193
	v_lshl_add_u64 v[0:1], v[0:1], 0, v[164:165]
	v_lshlrev_b32_e32 v25, 3, v24
	global_load_dwordx4 v[140:143], v[0:1], off offset:2048
	global_load_dwordx4 v[136:139], v[0:1], off offset:2080
	global_load_dwordx4 v[132:135], v[0:1], off offset:2112
	global_load_dwordx4 v[128:131], v[0:1], off offset:2144
	v_and_b32_e32 v0, 56, v25
	v_lshlrev_b32_e32 v192, 1, v0
	v_lshl_add_u64 v[0:1], s[6:7], 0, v[192:193]
	s_mov_b64 s[6:7], 0x22000000
	v_lshl_add_u64 v[14:15], v[0:1], 0, s[6:7]
	v_ashrrev_i32_e32 v0, 31, v24
	v_lshrrev_b32_e32 v0, 28, v0
	v_add_u32_e32 v0, v24, v0
	v_add_u32_e32 v16, 0x200, v24
	v_ashrrev_i32_e32 v197, 4, v0
	v_and_b32_e32 v0, -16, v0
	v_ashrrev_i32_e32 v12, 31, v16
	v_sub_u32_e32 v26, v24, v0
	v_lshrrev_b32_e32 v12, 28, v12
	v_lshlrev_b32_e32 v168, 3, v26
	v_add_u32_e32 v12, v16, v12
	v_mov_b64_e32 v[10:11], s[2:3]
	v_ashrrev_i32_e32 v169, 31, v168
	v_ashrrev_i32_e32 v170, 3, v24
	v_ashrrev_i32_e32 v198, 4, v12
	v_and_b32_e32 v12, -16, v12
	v_mad_i64_i32 v[2:3], s[6:7], v197, s79, v[10:11]
	v_lshlrev_b64 v[0:1], 1, v[168:169]
	v_ashrrev_i32_e32 v171, 31, v170
	v_sub_u32_e32 v27, v16, v12
	v_lshl_add_u64 v[2:3], v[2:3], 0, v[0:1]
	v_lshlrev_b64 v[6:7], 15, v[170:171]
	v_lshlrev_b32_e32 v172, 3, v27
	global_load_dwordx4 v[2:5], v[2:3], off offset:3072
	v_lshl_add_u64 v[18:19], v[14:15], 0, v[6:7]
	v_ashrrev_i32_e32 v173, 31, v172
	v_ashrrev_i32_e32 v174, 3, v16
	global_load_dwordx4 v[6:9], v[18:19], off
	v_mad_i64_i32 v[10:11], s[6:7], v198, s79, v[10:11]
	v_lshlrev_b64 v[20:21], 1, v[172:173]
	v_ashrrev_i32_e32 v175, 31, v174
	v_lshl_add_u64 v[10:11], v[10:11], 0, v[20:21]
	v_lshlrev_b64 v[16:17], 15, v[174:175]
	global_load_dwordx4 v[10:13], v[10:11], off offset:3072
	v_lshl_add_u64 v[22:23], v[14:15], 0, v[16:17]
	global_load_dwordx4 v[14:17], v[22:23], off
	v_mov_b32_e32 v195, s14
	v_readfirstlane_b32 s14, v24
	v_and_b32_e32 v32, 31, v24
	v_lshlrev_b32_e32 v24, 4, v24
	s_movk_i32 s6, 0x110
	v_and_b32_e32 v24, 0x60, v24
	v_and_b32_e32 v25, 8, v25
	v_mul_lo_u32 v202, v197, s6
	v_add3_u32 v199, 0, v24, v25
	v_add_u32_e32 v24, 0, v202
	v_lshlrev_b32_e32 v203, 4, v26
	v_mul_lo_u32 v201, v170, s80
	s_cmpk_gt_i32 s14, 0xff
	v_add_u32_e32 v200, v24, v203
	v_add_u32_e32 v24, v199, v201
	s_cselect_b64 s[0:1], -1, 0
	s_cmpk_lt_i32 s14, 0x100
	v_mul_lo_u32 v220, v198, s6
	s_cselect_b64 s[14:15], -1, 0
	v_lshlrev_b32_e32 v221, 4, v27
	v_mul_lo_u32 v219, v174, s80
	s_add_u32 s6, s2, 0x82c00
	v_add_u32_e32 v25, v199, v219
	s_addc_u32 s7, s3, 0
	s_add_u32 s2, s2, 0x104c00
	s_addc_u32 s3, s3, 0
	v_mul_u32_u24_e32 v26, 0x110, v32
	s_mov_b32 s54, s41
	s_mov_b32 s55, s41
	s_mov_b32 s40, s41
	s_mov_b32 s42, s41
	s_mov_b32 s43, s41
	s_mov_b32 s44, s41
	s_mov_b32 s45, s41
	s_mov_b32 s46, s41
	s_mov_b32 s47, s41
	s_mov_b32 s48, s41
	s_mov_b32 s49, s41
	s_mov_b32 s50, s41
	s_mov_b32 s51, s41
	s_mov_b32 s52, s41
	s_mov_b32 s53, s41
	v_mov_b64_e32 v[62:63], s[54:55]
	v_add_u32_e32 v33, 0, v164
	v_mov_b64_e32 v[48:49], s[40:41]
	v_mul_u32_u24_e32 v165, 0x90, v32
	v_mov_b64_e32 v[60:61], s[52:53]
	v_mov_b64_e32 v[58:59], s[50:51]
	v_mov_b64_e32 v[56:57], s[48:49]
	v_mov_b64_e32 v[54:55], s[46:47]
	v_mov_b64_e32 v[52:53], s[44:45]
	v_mov_b64_e32 v[50:51], s[42:43]
	v_add_u32_e32 v175, v33, v165
	s_and_b64 vcc, exec, s[0:1]
	s_waitcnt vmcnt(0) lgkmcnt(0)
	ds_write_b128 v200, v[2:5]
	v_add_u32_e32 v2, 0x8800, v24
	ds_write2_b64 v2, v[6:7], v[8:9] offset1:2
	v_add_u32_e32 v2, 0, v220
	v_add_u32_e32 v205, v2, v221
	v_add_u32_e32 v2, 0x8800, v25
	ds_write_b128 v205, v[10:13]
	v_mov_b64_e32 v[10:11], s[6:7]
	ds_write2_b64 v2, v[14:15], v[16:17] offset1:2
	v_mad_i64_i32 v[2:3], s[6:7], v197, s79, v[10:11]
	v_lshl_add_u64 v[2:3], v[2:3], 0, v[0:1]
	v_mad_i64_i32 v[10:11], s[6:7], v198, s79, v[10:11]
	global_load_dwordx4 v[2:5], v[2:3], off
	s_nop 0
	global_load_dwordx4 v[6:9], v[18:19], off offset:128
	v_lshl_add_u64 v[10:11], v[10:11], 0, v[20:21]
	global_load_dwordx4 v[10:13], v[10:11], off
	s_nop 0
	global_load_dwordx4 v[14:17], v[22:23], off offset:128
	s_waitcnt lgkmcnt(0)
	s_barrier
	s_waitcnt vmcnt(0)
	ds_write_b128 v200, v[2:5] offset:17408
	v_add_u32_e32 v2, 0xd000, v24
	ds_write2_b64 v2, v[6:7], v[8:9] offset1:2
	ds_write_b128 v205, v[10:13] offset:17408
	v_add_u32_e32 v2, 0xd000, v25
	ds_write2_b64 v2, v[14:15], v[16:17] offset1:2
	v_mov_b64_e32 v[2:3], s[2:3]
	v_mad_i64_i32 v[4:5], s[2:3], v197, s79, v[2:3]
	v_lshl_add_u64 v[0:1], v[4:5], 0, v[0:1]
	global_load_dwordx4 v[156:159], v[0:1], off
	global_load_dwordx4 v[148:151], v[18:19], off offset:256
	v_mad_i64_i32 v[0:1], s[2:3], v198, s79, v[2:3]
	v_lshl_add_u64 v[0:1], v[0:1], 0, v[20:21]
	global_load_dwordx4 v[152:155], v[0:1], off
	global_load_dwordx4 v[144:147], v[22:23], off offset:256
	s_lshl_b32 s2, s39, 7
	s_add_i32 s2, s2, 0
	v_add3_u32 v171, s2, v26, v164
	ds_read_b128 v[16:19], v171 offset:8704
	ds_read_b128 v[0:3], v171
	ds_read_b128 v[34:37], v171 offset:32
	s_waitcnt lgkmcnt(0)
	v_mfma_f32_32x32x16_bf16 v[0:15], v[0:3], v[140:143], 0
	ds_read_b128 v[38:41], v171 offset:8736
	v_mfma_f32_32x32x16_bf16 v[16:31], v[16:19], v[140:143], 0
	v_mfma_f32_32x32x16_bf16 v[0:15], v[34:37], v[136:139], v[0:15]
	s_waitcnt lgkmcnt(0)
	v_mfma_f32_32x32x16_bf16 v[16:31], v[38:41], v[136:139], v[16:31]
	ds_read_b128 v[34:37], v171 offset:8768
	ds_read_b128 v[38:41], v171 offset:64
	s_waitcnt lgkmcnt(0)
	v_mfma_f32_32x32x16_bf16 v[0:15], v[38:41], v[132:135], v[0:15]
	v_mfma_f32_32x32x16_bf16 v[16:31], v[34:37], v[132:135], v[16:31]
	ds_read_b128 v[34:37], v171 offset:8800
	ds_read_b128 v[38:41], v171 offset:96
	s_waitcnt lgkmcnt(0)
	v_mfma_f32_32x32x16_bf16 v[0:15], v[38:41], v[128:131], v[0:15]
	v_mfma_f32_32x32x16_bf16 v[16:31], v[34:37], v[128:131], v[16:31]
	s_nop 10
	v_max_f32_e32 v34, v1, v1
	v_max_f32_e32 v35, v0, v0
	v_max_f32_e32 v34, v35, v34
	v_max3_f32 v35, v2, v3, v17
	v_max3_f32 v34, v34, v16, v18
	v_max3_f32 v34, v34, v19, v4
	v_max3_f32 v35, v35, v6, v7
	v_max3_f32 v34, v34, v5, v20
	v_max3_f32 v35, v35, v22, v23
	v_max3_f32 v34, v34, v21, v8
	v_max3_f32 v35, v35, v10, v11
	v_max3_f32 v34, v34, v9, v24
	v_max3_f32 v35, v35, v26, v27
	v_max3_f32 v34, v34, v25, v12
	v_max3_f32 v35, v35, v14, v15
	v_max3_f32 v34, v34, v13, v28
	v_max3_f32 v35, v35, v30, v31
	v_max3_f32 v34, v34, v29, v35
	v_mov_b32_e32 v35, v34
	s_nop 1
	v_permlane32_swap_b32_e32 v34, v35
	v_max_f32_e32 v35, v35, v35
	v_max_f32_e32 v34, v34, v34
	v_max_f32_e32 v112, v34, v35
	v_sub_f32_e32 v0, v0, v112
	v_sub_f32_e32 v16, v16, v112
	v_sub_f32_e32 v1, v1, v112
	v_sub_f32_e32 v17, v17, v112
	v_sub_f32_e32 v2, v2, v112
	v_sub_f32_e32 v18, v18, v112
	v_sub_f32_e32 v3, v3, v112
	v_sub_f32_e32 v19, v19, v112
	v_sub_f32_e32 v4, v4, v112
	v_sub_f32_e32 v20, v20, v112
	v_sub_f32_e32 v5, v5, v112
	v_sub_f32_e32 v21, v21, v112
	v_sub_f32_e32 v6, v6, v112
	v_sub_f32_e32 v22, v22, v112
	v_sub_f32_e32 v7, v7, v112
	v_sub_f32_e32 v23, v23, v112
	v_sub_f32_e32 v8, v8, v112
	v_sub_f32_e32 v24, v24, v112
	v_sub_f32_e32 v9, v9, v112
	v_sub_f32_e32 v25, v25, v112
	v_sub_f32_e32 v10, v10, v112
	v_sub_f32_e32 v26, v26, v112
	v_sub_f32_e32 v11, v11, v112
	v_sub_f32_e32 v27, v27, v112
	v_sub_f32_e32 v12, v12, v112
	v_sub_f32_e32 v28, v28, v112
	v_sub_f32_e32 v13, v13, v112
	v_sub_f32_e32 v29, v29, v112
	v_sub_f32_e32 v14, v14, v112
	v_sub_f32_e32 v30, v30, v112
	v_sub_f32_e32 v15, v15, v112
	v_sub_f32_e32 v31, v31, v112
	v_exp_f32_e32 v64, v0
	v_exp_f32_e32 v65, v1
	v_exp_f32_e32 v66, v16
	v_exp_f32_e32 v67, v17
	v_exp_f32_e32 v68, v2
	v_exp_f32_e32 v69, v3
	v_exp_f32_e32 v70, v18
	v_exp_f32_e32 v71, v19
	v_exp_f32_e32 v72, v4
	v_exp_f32_e32 v73, v5
	v_exp_f32_e32 v74, v20
	v_exp_f32_e32 v75, v21
	v_exp_f32_e32 v76, v6
	v_exp_f32_e32 v77, v7
	v_exp_f32_e32 v78, v22
	v_exp_f32_e32 v79, v23
	v_exp_f32_e32 v80, v8
	v_exp_f32_e32 v81, v9
	v_exp_f32_e32 v82, v24
	v_exp_f32_e32 v83, v25
	v_exp_f32_e32 v84, v10
	v_exp_f32_e32 v85, v11
	v_exp_f32_e32 v86, v26
	v_exp_f32_e32 v87, v27
	v_exp_f32_e32 v88, v12
	v_exp_f32_e32 v89, v13
	v_exp_f32_e32 v90, v28
	v_exp_f32_e32 v91, v29
	v_exp_f32_e32 v92, v14
	v_exp_f32_e32 v93, v15
	v_exp_f32_e32 v94, v30
	v_exp_f32_e32 v95, v31
	v_mov_b64_e32 v[32:33], v[48:49]
	v_mov_b64_e32 v[16:17], v[48:49]
	v_mov_b64_e32 v[0:1], v[48:49]
	v_cvt_pk_bf16_f32 v104, v64, v65
	v_cvt_pk_bf16_f32 v105, v68, v69
	v_cvt_pk_bf16_f32 v106, v72, v73
	v_cvt_pk_bf16_f32 v107, v76, v77
	v_cvt_pk_bf16_f32 v96, v66, v67
	v_cvt_pk_bf16_f32 v97, v70, v71
	v_cvt_pk_bf16_f32 v98, v74, v75
	v_cvt_pk_bf16_f32 v99, v78, v79
	v_cvt_pk_bf16_f32 v108, v80, v81
	v_cvt_pk_bf16_f32 v109, v84, v85
	v_cvt_pk_bf16_f32 v110, v88, v89
	v_cvt_pk_bf16_f32 v111, v92, v93
	v_cvt_pk_bf16_f32 v100, v82, v83
	v_cvt_pk_bf16_f32 v101, v86, v87
	v_cvt_pk_bf16_f32 v102, v90, v91
	v_cvt_pk_bf16_f32 v103, v94, v95
	v_mov_b64_e32 v[34:35], v[50:51]
	v_mov_b64_e32 v[36:37], v[52:53]
	v_mov_b64_e32 v[38:39], v[54:55]
	v_mov_b64_e32 v[40:41], v[56:57]
	v_mov_b64_e32 v[42:43], v[58:59]
	v_mov_b64_e32 v[44:45], v[60:61]
	v_mov_b64_e32 v[46:47], v[62:63]
	v_mov_b64_e32 v[18:19], v[50:51]
	v_mov_b64_e32 v[20:21], v[52:53]
	v_mov_b64_e32 v[22:23], v[54:55]
	v_mov_b64_e32 v[24:25], v[56:57]
	v_mov_b64_e32 v[26:27], v[58:59]
	v_mov_b64_e32 v[28:29], v[60:61]
	v_mov_b64_e32 v[30:31], v[62:63]
	v_mov_b64_e32 v[2:3], v[50:51]
	v_mov_b64_e32 v[4:5], v[52:53]
	v_mov_b64_e32 v[6:7], v[54:55]
	v_mov_b64_e32 v[8:9], v[56:57]
	v_mov_b64_e32 v[10:11], v[58:59]
	v_mov_b64_e32 v[12:13], v[60:61]
	v_mov_b64_e32 v[14:15], v[62:63]
	s_cbranch_vccnz .LBB0_927
	ds_read_b128 v[240:243], v175 offset:34816
	ds_read_b128 v[244:247], v175 offset:34848
	ds_read_b128 v[248:251], v175 offset:34880
	ds_read_b128 v[252:255], v175 offset:34912
	s_waitcnt lgkmcnt(3)
	v_mfma_f32_32x32x16_bf16 v[48:63], v[240:243], v[104:107], 0
	ds_read_b128 v[240:243], v175 offset:39424
	s_waitcnt lgkmcnt(3)
	v_mfma_f32_32x32x16_bf16 v[48:63], v[244:247], v[108:111], v[48:63]
	ds_read_b128 v[244:247], v175 offset:39456
	s_waitcnt lgkmcnt(3)
	v_mfma_f32_32x32x16_bf16 v[48:63], v[248:251], v[96:99], v[48:63]
	ds_read_b128 v[248:251], v175 offset:39488
	s_waitcnt lgkmcnt(3)
	v_mfma_f32_32x32x16_bf16 v[48:63], v[252:255], v[100:103], v[48:63]
	ds_read_b128 v[252:255], v175 offset:39520
	s_waitcnt lgkmcnt(3)
	v_mfma_f32_32x32x16_bf16 v[32:47], v[240:243], v[104:107], 0
	ds_read_b128 v[240:243], v175 offset:44032
	s_waitcnt lgkmcnt(3)
	v_mfma_f32_32x32x16_bf16 v[32:47], v[244:247], v[108:111], v[32:47]
	ds_read_b128 v[244:247], v175 offset:44064
	s_waitcnt lgkmcnt(3)
	v_mfma_f32_32x32x16_bf16 v[32:47], v[248:251], v[96:99], v[32:47]
	ds_read_b128 v[248:251], v175 offset:44096
	s_waitcnt lgkmcnt(3)
	v_mfma_f32_32x32x16_bf16 v[32:47], v[252:255], v[100:103], v[32:47]
	ds_read_b128 v[252:255], v175 offset:44128
	s_waitcnt lgkmcnt(3)
	v_mfma_f32_32x32x16_bf16 v[16:31], v[240:243], v[104:107], 0
	ds_read_b128 v[240:243], v175 offset:48640
	s_waitcnt lgkmcnt(3)
	v_mfma_f32_32x32x16_bf16 v[16:31], v[244:247], v[108:111], v[16:31]
	ds_read_b128 v[244:247], v175 offset:48672
	s_waitcnt lgkmcnt(3)
	v_mfma_f32_32x32x16_bf16 v[16:31], v[248:251], v[96:99], v[16:31]
	ds_read_b128 v[248:251], v175 offset:48704
	s_waitcnt lgkmcnt(3)
	v_mfma_f32_32x32x16_bf16 v[16:31], v[252:255], v[100:103], v[16:31]
	ds_read_b128 v[252:255], v175 offset:48736
	s_waitcnt lgkmcnt(3)
	v_mfma_f32_32x32x16_bf16 v[0:15], v[240:243], v[104:107], 0
	s_waitcnt lgkmcnt(2)
	v_mfma_f32_32x32x16_bf16 v[0:15], v[244:247], v[108:111], v[0:15]
	s_waitcnt lgkmcnt(1)
	v_mfma_f32_32x32x16_bf16 v[0:15], v[248:251], v[96:99], v[0:15]
	s_waitcnt lgkmcnt(0)
	v_mfma_f32_32x32x16_bf16 v[0:15], v[252:255], v[100:103], v[0:15]

.LBB0_931:
	v_lshl_add_u64 v[64:65], s[22:23], 0, v[192:193]
	v_mad_i64_i32 v[66:67], s[22:23], s20, v197, 0
	v_lshl_add_u64 v[66:67], v[66:67], 1, s[6:7]
	v_lshl_add_u64 v[66:67], v[168:169], 1, v[66:67]
	global_load_dwordx4 v[156:159], v[66:67], off
	v_mad_i64_i32 v[66:67], s[22:23], s8, v170, 0
	v_lshl_add_u64 v[66:67], v[66:67], 1, v[64:65]
	global_load_dwordx4 v[148:151], v[66:67], off
	v_mad_i64_i32 v[66:67], s[20:21], s20, v198, 0
	v_lshl_add_u64 v[66:67], v[66:67], 1, s[6:7]
	v_lshl_add_u64 v[66:67], v[172:173], 1, v[66:67]
	global_load_dwordx4 v[152:155], v[66:67], off
	v_mad_i64_i32 v[66:67], s[6:7], s8, v174, 0
	v_lshl_add_u64 v[64:65], v[66:67], 1, v[64:65]
	global_load_dwordx4 v[144:147], v[64:65], off
	v_cndmask_b32_e64 v64, 0, 1, s[0:1]
	v_cmp_ne_u32_e64 s[8:9], 1, v64
	s_andn2_b64 vcc, exec, s[0:1]
	s_cbranch_vccnz .LBB0_933
	s_mul_i32 s6, s47, 0x4800
	v_add_u32_e32 v68, s6, v175
	ds_read_b128 v[240:243], v68 offset:34816
	ds_read_b128 v[244:247], v68 offset:34848
	ds_read_b128 v[248:251], v68 offset:34880
	ds_read_b128 v[252:255], v68 offset:34912
	s_waitcnt lgkmcnt(3)
	v_mfma_f32_32x32x16_bf16 v[48:63], v[240:243], v[104:107], v[48:63]
	ds_read_b128 v[240:243], v68 offset:39424
	s_waitcnt lgkmcnt(3)
	v_mfma_f32_32x32x16_bf16 v[48:63], v[244:247], v[108:111], v[48:63]
	ds_read_b128 v[244:247], v68 offset:39456
	s_waitcnt lgkmcnt(3)
	v_mfma_f32_32x32x16_bf16 v[48:63], v[248:251], v[96:99], v[48:63]
	ds_read_b128 v[248:251], v68 offset:39488
	s_waitcnt lgkmcnt(3)
	v_mfma_f32_32x32x16_bf16 v[48:63], v[252:255], v[100:103], v[48:63]
	ds_read_b128 v[252:255], v68 offset:39520
	s_waitcnt lgkmcnt(3)
	v_mfma_f32_32x32x16_bf16 v[32:47], v[240:243], v[104:107], v[32:47]
	ds_read_b128 v[240:243], v68 offset:44032
	s_waitcnt lgkmcnt(3)
	v_mfma_f32_32x32x16_bf16 v[32:47], v[244:247], v[108:111], v[32:47]
	ds_read_b128 v[244:247], v68 offset:44064
	s_waitcnt lgkmcnt(3)
	v_mfma_f32_32x32x16_bf16 v[32:47], v[248:251], v[96:99], v[32:47]
	ds_read_b128 v[248:251], v68 offset:44096
	s_waitcnt lgkmcnt(3)
	v_mfma_f32_32x32x16_bf16 v[32:47], v[252:255], v[100:103], v[32:47]
	ds_read_b128 v[252:255], v68 offset:44128
	s_waitcnt lgkmcnt(3)
	v_mfma_f32_32x32x16_bf16 v[16:31], v[240:243], v[104:107], v[16:31]
	ds_read_b128 v[240:243], v68 offset:48640
	s_waitcnt lgkmcnt(3)
	v_mfma_f32_32x32x16_bf16 v[16:31], v[244:247], v[108:111], v[16:31]
	ds_read_b128 v[244:247], v68 offset:48672
	s_waitcnt lgkmcnt(3)
	v_mfma_f32_32x32x16_bf16 v[16:31], v[248:251], v[96:99], v[16:31]
	ds_read_b128 v[248:251], v68 offset:48704
	s_waitcnt lgkmcnt(3)
	v_mfma_f32_32x32x16_bf16 v[16:31], v[252:255], v[100:103], v[16:31]
	ds_read_b128 v[252:255], v68 offset:48736
	s_waitcnt lgkmcnt(3)
	v_mfma_f32_32x32x16_bf16 v[0:15], v[240:243], v[104:107], v[0:15]
	s_waitcnt lgkmcnt(2)
	v_mfma_f32_32x32x16_bf16 v[0:15], v[244:247], v[108:111], v[0:15]
	s_waitcnt lgkmcnt(1)
	v_mfma_f32_32x32x16_bf16 v[0:15], v[248:251], v[96:99], v[0:15]
	s_waitcnt lgkmcnt(0)
	v_mfma_f32_32x32x16_bf16 v[0:15], v[252:255], v[100:103], v[0:15]
.LBB0_933:
	s_mulk_i32 s48, 0x4400
	v_add_u32_e32 v68, s48, v171
	s_mov_b32 s6, 0x40c00000
	ds_read_b128 v[240:243], v68
	ds_read_b128 v[244:247], v68 offset:8704
	ds_read_b128 v[248:251], v68 offset:32
	ds_read_b128 v[252:255], v68 offset:8736
	s_waitcnt lgkmcnt(3)
	v_mfma_f32_32x32x16_bf16 v[112:127], v[240:243], v[140:143], v[80:95]
	ds_read_b128 v[240:243], v68 offset:64
	s_waitcnt lgkmcnt(3)
	v_mfma_f32_32x32x16_bf16 v[96:111], v[244:247], v[140:143], v[80:95]
	ds_read_b128 v[244:247], v68 offset:8768
	s_waitcnt lgkmcnt(3)
	v_mfma_f32_32x32x16_bf16 v[112:127], v[248:251], v[136:139], v[112:127]
	ds_read_b128 v[248:251], v68 offset:96
	s_waitcnt lgkmcnt(3)
	v_mfma_f32_32x32x16_bf16 v[96:111], v[252:255], v[136:139], v[96:111]
	ds_read_b128 v[252:255], v68 offset:8800
	s_waitcnt lgkmcnt(3)
	v_mfma_f32_32x32x16_bf16 v[112:127], v[240:243], v[132:135], v[112:127]
	s_waitcnt lgkmcnt(2)
	v_mfma_f32_32x32x16_bf16 v[96:111], v[244:247], v[132:135], v[96:111]
	s_waitcnt lgkmcnt(1)
	v_mfma_f32_32x32x16_bf16 v[112:127], v[248:251], v[128:131], v[112:127]
	s_waitcnt lgkmcnt(0)
	v_mfma_f32_32x32x16_bf16 v[96:111], v[252:255], v[128:131], v[96:111]
	s_nop 9
	v_max_f32_e32 v68, v113, v113
	v_max_f32_e32 v69, v112, v112
	v_max_f32_e32 v68, v69, v68
	v_max3_f32 v64, v114, v115, v97
	v_max3_f32 v65, v68, v96, v98
	v_max3_f32 v65, v65, v99, v116
	v_max3_f32 v64, v64, v118, v119
	v_max3_f32 v65, v65, v117, v100
	v_max3_f32 v64, v64, v102, v103
	v_max3_f32 v65, v65, v101, v120
	v_max3_f32 v64, v64, v122, v123
	v_max3_f32 v65, v65, v121, v104
	v_max3_f32 v64, v64, v106, v107
	v_max3_f32 v65, v65, v105, v124
	v_max3_f32 v64, v64, v126, v127
	v_max3_f32 v65, v65, v125, v108
	v_max3_f32 v64, v64, v110, v111
	v_max3_f32 v64, v65, v109, v64
	v_mov_b32_e32 v65, v64
	s_nop 1
	v_permlane32_swap_b32_e32 v64, v65
	v_max_f32_e32 v65, v65, v65
	v_max_f32_e32 v64, v64, v64
	v_max_f32_e32 v64, v64, v65
	v_cmp_lt_f32_e32 vcc, s6, v64
	s_cbranch_vccz .LBB0_935
	v_max_f32_e32 v64, v64, v64
	v_max_f32_e32 v64, 0, v64
	v_exp_f32_e64 v66, -v64
	v_mov_b32_e32 v67, v64
	v_pk_add_f32 v[112:113], v[112:113], v[64:65] op_sel_hi:[1,0] neg_lo:[0,1] neg_hi:[0,1]
	v_pk_add_f32 v[96:97], v[96:97], v[64:65] op_sel_hi:[1,0] neg_lo:[0,1] neg_hi:[0,1]
	v_pk_add_f32 v[114:115], v[114:115], v[64:65] op_sel_hi:[1,0] neg_lo:[0,1] neg_hi:[0,1]
	v_pk_add_f32 v[98:99], v[98:99], v[64:65] op_sel_hi:[1,0] neg_lo:[0,1] neg_hi:[0,1]
	v_pk_add_f32 v[116:117], v[116:117], v[64:65] op_sel_hi:[1,0] neg_lo:[0,1] neg_hi:[0,1]
	v_pk_add_f32 v[100:101], v[100:101], v[64:65] op_sel_hi:[1,0] neg_lo:[0,1] neg_hi:[0,1]
	v_pk_add_f32 v[118:119], v[118:119], v[64:65] op_sel_hi:[1,0] neg_lo:[0,1] neg_hi:[0,1]
	v_pk_add_f32 v[102:103], v[102:103], v[64:65] op_sel_hi:[1,0] neg_lo:[0,1] neg_hi:[0,1]
	v_pk_add_f32 v[120:121], v[120:121], v[64:65] op_sel_hi:[1,0] neg_lo:[0,1] neg_hi:[0,1]
	v_pk_add_f32 v[104:105], v[104:105], v[64:65] op_sel_hi:[1,0] neg_lo:[0,1] neg_hi:[0,1]
	v_pk_add_f32 v[122:123], v[122:123], v[64:65] op_sel_hi:[1,0] neg_lo:[0,1] neg_hi:[0,1]
	v_pk_add_f32 v[106:107], v[106:107], v[64:65] op_sel_hi:[1,0] neg_lo:[0,1] neg_hi:[0,1]
	v_pk_add_f32 v[124:125], v[124:125], v[64:65] op_sel_hi:[1,0] neg_lo:[0,1] neg_hi:[0,1]
	v_pk_add_f32 v[108:109], v[108:109], v[64:65] op_sel_hi:[1,0] neg_lo:[0,1] neg_hi:[0,1]
	v_pk_add_f32 v[126:127], v[126:127], v[64:65] op_sel_hi:[1,0] neg_lo:[0,1] neg_hi:[0,1]
	v_pk_add_f32 v[110:111], v[110:111], v[64:65] op_sel_hi:[1,0] neg_lo:[0,1] neg_hi:[0,1]
	v_pk_add_f32 v[64:65], v[166:167], v[66:67]
	v_pk_mul_f32 v[166:167], v[166:167], v[66:67]
	v_xor_b32_e32 v64, 0x80000000, v65
	v_mov_b32_e32 v167, v65
	v_pk_mul_f32 v[62:63], v[62:63], v[66:67] op_sel_hi:[1,0]
	v_pk_mul_f32 v[60:61], v[60:61], v[66:67] op_sel_hi:[1,0]
	v_pk_mul_f32 v[58:59], v[58:59], v[66:67] op_sel_hi:[1,0]
	v_pk_mul_f32 v[56:57], v[56:57], v[66:67] op_sel_hi:[1,0]
	v_pk_mul_f32 v[54:55], v[54:55], v[66:67] op_sel_hi:[1,0]
	v_pk_mul_f32 v[52:53], v[52:53], v[66:67] op_sel_hi:[1,0]
	v_pk_mul_f32 v[50:51], v[50:51], v[66:67] op_sel_hi:[1,0]
	v_pk_mul_f32 v[48:49], v[48:49], v[66:67] op_sel_hi:[1,0]
	v_pk_mul_f32 v[46:47], v[46:47], v[66:67] op_sel_hi:[1,0]
	v_pk_mul_f32 v[44:45], v[44:45], v[66:67] op_sel_hi:[1,0]
	v_pk_mul_f32 v[42:43], v[42:43], v[66:67] op_sel_hi:[1,0]
	v_pk_mul_f32 v[40:41], v[40:41], v[66:67] op_sel_hi:[1,0]
	v_pk_mul_f32 v[38:39], v[38:39], v[66:67] op_sel_hi:[1,0]
	v_pk_mul_f32 v[36:37], v[36:37], v[66:67] op_sel_hi:[1,0]
	v_pk_mul_f32 v[34:35], v[34:35], v[66:67] op_sel_hi:[1,0]
	v_pk_mul_f32 v[32:33], v[32:33], v[66:67] op_sel_hi:[1,0]
	v_pk_mul_f32 v[30:31], v[30:31], v[66:67] op_sel_hi:[1,0]
	v_pk_mul_f32 v[28:29], v[28:29], v[66:67] op_sel_hi:[1,0]
	v_pk_mul_f32 v[26:27], v[26:27], v[66:67] op_sel_hi:[1,0]
	v_pk_mul_f32 v[24:25], v[24:25], v[66:67] op_sel_hi:[1,0]
	v_pk_mul_f32 v[22:23], v[22:23], v[66:67] op_sel_hi:[1,0]
	v_pk_mul_f32 v[20:21], v[20:21], v[66:67] op_sel_hi:[1,0]
	v_pk_mul_f32 v[18:19], v[18:19], v[66:67] op_sel_hi:[1,0]
	v_pk_mul_f32 v[16:17], v[16:17], v[66:67] op_sel_hi:[1,0]
	v_pk_mul_f32 v[14:15], v[14:15], v[66:67] op_sel_hi:[1,0]
	v_pk_mul_f32 v[12:13], v[12:13], v[66:67] op_sel_hi:[1,0]
	v_pk_mul_f32 v[10:11], v[10:11], v[66:67] op_sel_hi:[1,0]
	v_pk_mul_f32 v[8:9], v[8:9], v[66:67] op_sel_hi:[1,0]
	v_pk_mul_f32 v[6:7], v[6:7], v[66:67] op_sel_hi:[1,0]
	v_pk_mul_f32 v[4:5], v[4:5], v[66:67] op_sel_hi:[1,0]
	v_pk_mul_f32 v[2:3], v[2:3], v[66:67] op_sel_hi:[1,0]
	v_pk_mul_f32 v[0:1], v[0:1], v[66:67] op_sel_hi:[1,0]
	v_mov_b32_e32 v65, v64
	v_mov_b32_e32 v66, v64
	v_mov_b32_e32 v67, v64
	v_mov_b32_e32 v68, v64
	v_mov_b32_e32 v69, v64
	v_mov_b32_e32 v70, v64
	v_mov_b32_e32 v71, v64
	v_mov_b32_e32 v72, v64
	v_mov_b32_e32 v73, v64
	v_mov_b32_e32 v74, v64
	v_mov_b32_e32 v75, v64
	v_mov_b32_e32 v76, v64
	v_mov_b32_e32 v77, v64
	v_mov_b32_e32 v78, v64
	v_mov_b32_e32 v79, v64
	v_mov_b32_e32 v80, v64
	v_mov_b32_e32 v81, v64
	v_mov_b32_e32 v82, v64
	v_mov_b32_e32 v83, v64
	v_mov_b32_e32 v84, v64
	v_mov_b32_e32 v85, v64
	v_mov_b32_e32 v86, v64
	v_mov_b32_e32 v87, v64
	v_mov_b32_e32 v88, v64
	v_mov_b32_e32 v89, v64
	v_mov_b32_e32 v90, v64
	v_mov_b32_e32 v91, v64
	v_mov_b32_e32 v92, v64
	v_mov_b32_e32 v93, v64
	v_mov_b32_e32 v94, v64
	v_mov_b32_e32 v95, v64
	s_branch .LBB0_936

.LBB0_936:
	v_exp_f32_e32 v112, v112
	v_exp_f32_e32 v113, v113
	v_exp_f32_e32 v176, v96
	v_exp_f32_e32 v177, v97
	v_exp_f32_e32 v114, v114
	v_exp_f32_e32 v115, v115
	v_exp_f32_e32 v178, v98
	v_exp_f32_e32 v179, v99
	v_exp_f32_e32 v116, v116
	v_exp_f32_e32 v117, v117
	v_exp_f32_e32 v180, v100
	v_exp_f32_e32 v181, v101
	v_exp_f32_e32 v118, v118
	v_exp_f32_e32 v119, v119
	v_exp_f32_e32 v182, v102
	v_exp_f32_e32 v183, v103
	v_exp_f32_e32 v120, v120
	v_exp_f32_e32 v121, v121
	v_exp_f32_e32 v184, v104
	v_exp_f32_e32 v185, v105
	v_exp_f32_e32 v122, v122
	v_exp_f32_e32 v123, v123
	v_exp_f32_e32 v186, v106
	v_exp_f32_e32 v187, v107
	v_exp_f32_e32 v124, v124
	v_exp_f32_e32 v125, v125
	v_exp_f32_e32 v188, v108
	v_exp_f32_e32 v189, v109
	v_exp_f32_e32 v126, v126
	v_exp_f32_e32 v127, v127
	v_exp_f32_e32 v190, v110
	v_exp_f32_e32 v191, v111
	v_cndmask_b32_e64 v103, 0, 1, s[14:15]
	v_cvt_pk_bf16_f32 v104, v112, v113
	v_cvt_pk_bf16_f32 v105, v114, v115
	v_cvt_pk_bf16_f32 v106, v116, v117
	v_cvt_pk_bf16_f32 v107, v118, v119
	v_cvt_pk_bf16_f32 v96, v176, v177
	v_cvt_pk_bf16_f32 v97, v178, v179
	v_cvt_pk_bf16_f32 v98, v180, v181
	v_cvt_pk_bf16_f32 v99, v182, v183
	v_cvt_pk_bf16_f32 v108, v120, v121
	v_cvt_pk_bf16_f32 v109, v122, v123
	v_cvt_pk_bf16_f32 v110, v124, v125
	v_cvt_pk_bf16_f32 v111, v126, v127
	v_cvt_pk_bf16_f32 v100, v184, v185
	v_cvt_pk_bf16_f32 v101, v186, v187
	v_cvt_pk_bf16_f32 v102, v188, v189
	v_cmp_ne_u32_e64 s[6:7], 1, v103
	s_andn2_b64 vcc, exec, s[14:15]
	v_cvt_pk_bf16_f32 v103, v190, v191
	s_cbranch_vccnz .LBB0_938
	s_mul_i32 s20, s3, 0x4800
	v_add_u32_e32 v226, s20, v175
	ds_read_b128 v[240:243], v226 offset:34816
	ds_read_b128 v[244:247], v226 offset:34848
	ds_read_b128 v[248:251], v226 offset:34880
	ds_read_b128 v[252:255], v226 offset:34912
	s_waitcnt lgkmcnt(3)
	v_mfma_f32_32x32x16_bf16 v[48:63], v[240:243], v[104:107], v[48:63]
	ds_read_b128 v[240:243], v226 offset:39424
	s_waitcnt lgkmcnt(3)
	v_mfma_f32_32x32x16_bf16 v[48:63], v[244:247], v[108:111], v[48:63]
	ds_read_b128 v[244:247], v226 offset:39456
	s_waitcnt lgkmcnt(3)
	v_mfma_f32_32x32x16_bf16 v[48:63], v[248:251], v[96:99], v[48:63]
	ds_read_b128 v[248:251], v226 offset:39488
	s_waitcnt lgkmcnt(3)
	v_mfma_f32_32x32x16_bf16 v[48:63], v[252:255], v[100:103], v[48:63]
	ds_read_b128 v[252:255], v226 offset:39520
	s_waitcnt lgkmcnt(3)
	v_mfma_f32_32x32x16_bf16 v[32:47], v[240:243], v[104:107], v[32:47]
	ds_read_b128 v[240:243], v226 offset:44032
	s_waitcnt lgkmcnt(3)
	v_mfma_f32_32x32x16_bf16 v[32:47], v[244:247], v[108:111], v[32:47]
	ds_read_b128 v[244:247], v226 offset:44064
	s_waitcnt lgkmcnt(3)
	v_mfma_f32_32x32x16_bf16 v[32:47], v[248:251], v[96:99], v[32:47]
	ds_read_b128 v[248:251], v226 offset:44096
	s_waitcnt lgkmcnt(3)
	v_mfma_f32_32x32x16_bf16 v[32:47], v[252:255], v[100:103], v[32:47]
	ds_read_b128 v[252:255], v226 offset:44128
	s_waitcnt lgkmcnt(3)
	v_mfma_f32_32x32x16_bf16 v[16:31], v[240:243], v[104:107], v[16:31]
	ds_read_b128 v[240:243], v226 offset:48640
	s_waitcnt lgkmcnt(3)
	v_mfma_f32_32x32x16_bf16 v[16:31], v[244:247], v[108:111], v[16:31]
	ds_read_b128 v[244:247], v226 offset:48672
	s_waitcnt lgkmcnt(3)
	v_mfma_f32_32x32x16_bf16 v[16:31], v[248:251], v[96:99], v[16:31]
	ds_read_b128 v[248:251], v226 offset:48704
	s_waitcnt lgkmcnt(3)
	v_mfma_f32_32x32x16_bf16 v[16:31], v[252:255], v[100:103], v[16:31]
	ds_read_b128 v[252:255], v226 offset:48736
	s_waitcnt lgkmcnt(3)
	v_mfma_f32_32x32x16_bf16 v[0:15], v[240:243], v[104:107], v[0:15]
	s_waitcnt lgkmcnt(2)
	v_mfma_f32_32x32x16_bf16 v[0:15], v[244:247], v[108:111], v[0:15]
	s_waitcnt lgkmcnt(1)
	v_mfma_f32_32x32x16_bf16 v[0:15], v[248:251], v[96:99], v[0:15]
	s_waitcnt lgkmcnt(0)
	v_mfma_f32_32x32x16_bf16 v[0:15], v[252:255], v[100:103], v[0:15]

.LBB0_940:
	v_add_u32_e32 v80, 0x8800, v199
	v_add_u32_e32 v81, v80, v201
	v_add_u32_e32 v80, v80, v219
	v_add_u32_e32 v81, 0x9000, v81
	v_add_u32_e32 v80, 0x9000, v80
	s_and_b64 vcc, exec, s[8:9]
	s_waitcnt vmcnt(0)
	ds_write_b128 v200, v[156:159] offset:17408
	ds_write2_b64 v81, v[148:149], v[150:151] offset1:2
	ds_write_b128 v205, v[152:155] offset:17408
	ds_write2_b64 v80, v[144:145], v[146:147] offset1:2
	s_cbranch_vccnz .LBB0_942
	ds_read_b128 v[240:243], v175 offset:34816
	ds_read_b128 v[244:247], v175 offset:34848
	ds_read_b128 v[248:251], v175 offset:34880
	ds_read_b128 v[252:255], v175 offset:34912
	s_waitcnt lgkmcnt(3)
	v_mfma_f32_32x32x16_bf16 v[48:63], v[240:243], v[104:107], v[48:63]
	ds_read_b128 v[240:243], v175 offset:39424
	s_waitcnt lgkmcnt(3)
	v_mfma_f32_32x32x16_bf16 v[48:63], v[244:247], v[108:111], v[48:63]
	ds_read_b128 v[244:247], v175 offset:39456
	s_waitcnt lgkmcnt(3)
	v_mfma_f32_32x32x16_bf16 v[48:63], v[248:251], v[96:99], v[48:63]
	ds_read_b128 v[248:251], v175 offset:39488
	s_waitcnt lgkmcnt(3)
	v_mfma_f32_32x32x16_bf16 v[48:63], v[252:255], v[100:103], v[48:63]
	ds_read_b128 v[252:255], v175 offset:39520
	s_waitcnt lgkmcnt(3)
	v_mfma_f32_32x32x16_bf16 v[32:47], v[240:243], v[104:107], v[32:47]
	ds_read_b128 v[240:243], v175 offset:44032
	s_waitcnt lgkmcnt(3)
	v_mfma_f32_32x32x16_bf16 v[32:47], v[244:247], v[108:111], v[32:47]
	ds_read_b128 v[244:247], v175 offset:44064
	s_waitcnt lgkmcnt(3)
	v_mfma_f32_32x32x16_bf16 v[32:47], v[248:251], v[96:99], v[32:47]
	ds_read_b128 v[248:251], v175 offset:44096
	s_waitcnt lgkmcnt(3)
	v_mfma_f32_32x32x16_bf16 v[32:47], v[252:255], v[100:103], v[32:47]
	ds_read_b128 v[252:255], v175 offset:44128
	s_waitcnt lgkmcnt(3)
	v_mfma_f32_32x32x16_bf16 v[16:31], v[240:243], v[104:107], v[16:31]
	ds_read_b128 v[240:243], v175 offset:48640
	s_waitcnt lgkmcnt(3)
	v_mfma_f32_32x32x16_bf16 v[16:31], v[244:247], v[108:111], v[16:31]
	ds_read_b128 v[244:247], v175 offset:48672
	s_waitcnt lgkmcnt(3)
	v_mfma_f32_32x32x16_bf16 v[16:31], v[248:251], v[96:99], v[16:31]
	ds_read_b128 v[248:251], v175 offset:48704
	s_waitcnt lgkmcnt(3)
	v_mfma_f32_32x32x16_bf16 v[16:31], v[252:255], v[100:103], v[16:31]
	ds_read_b128 v[252:255], v175 offset:48736
	s_waitcnt lgkmcnt(3)
	v_mfma_f32_32x32x16_bf16 v[0:15], v[240:243], v[104:107], v[0:15]
	s_waitcnt lgkmcnt(2)
	v_mfma_f32_32x32x16_bf16 v[0:15], v[244:247], v[108:111], v[0:15]
	s_waitcnt lgkmcnt(1)
	v_mfma_f32_32x32x16_bf16 v[0:15], v[248:251], v[96:99], v[0:15]
	s_waitcnt lgkmcnt(0)
	v_mfma_f32_32x32x16_bf16 v[0:15], v[252:255], v[100:103], v[0:15]
.LBB0_942:
	s_mov_b32 s3, 0x40c00000
	ds_read_b128 v[240:243], v171
	ds_read_b128 v[244:247], v171 offset:8704
	ds_read_b128 v[248:251], v171 offset:32
	ds_read_b128 v[252:255], v171 offset:8736
	s_waitcnt lgkmcnt(3)
	v_mfma_f32_32x32x16_bf16 v[96:111], v[240:243], v[140:143], v[64:79]
	ds_read_b128 v[240:243], v171 offset:64
	s_waitcnt lgkmcnt(3)
	v_mfma_f32_32x32x16_bf16 v[80:95], v[244:247], v[140:143], v[64:79]
	ds_read_b128 v[244:247], v171 offset:8768
	s_waitcnt lgkmcnt(3)
	v_mfma_f32_32x32x16_bf16 v[96:111], v[248:251], v[136:139], v[96:111]
	ds_read_b128 v[248:251], v171 offset:96
	s_waitcnt lgkmcnt(3)
	v_mfma_f32_32x32x16_bf16 v[80:95], v[252:255], v[136:139], v[80:95]
	ds_read_b128 v[252:255], v171 offset:8800
	s_waitcnt lgkmcnt(3)
	v_mfma_f32_32x32x16_bf16 v[96:111], v[240:243], v[132:135], v[96:111]
	s_waitcnt lgkmcnt(2)
	v_mfma_f32_32x32x16_bf16 v[80:95], v[244:247], v[132:135], v[80:95]
	s_waitcnt lgkmcnt(1)
	v_mfma_f32_32x32x16_bf16 v[96:111], v[248:251], v[128:131], v[96:111]
	s_waitcnt lgkmcnt(0)
	v_mfma_f32_32x32x16_bf16 v[80:95], v[252:255], v[128:131], v[80:95]
	s_nop 9
	v_max_f32_e32 v116, v97, v97
	v_max_f32_e32 v117, v96, v96
	v_max_f32_e32 v116, v117, v116
	v_max3_f32 v112, v98, v99, v81
	v_max3_f32 v113, v116, v80, v82
	v_max3_f32 v113, v113, v83, v100
	v_max3_f32 v112, v112, v102, v103
	v_max3_f32 v113, v113, v101, v84
	v_max3_f32 v112, v112, v86, v87
	v_max3_f32 v113, v113, v85, v104
	v_max3_f32 v112, v112, v106, v107
	v_max3_f32 v113, v113, v105, v88
	v_max3_f32 v112, v112, v90, v91
	v_max3_f32 v113, v113, v89, v108
	v_max3_f32 v112, v112, v110, v111
	v_max3_f32 v113, v113, v109, v92
	v_max3_f32 v112, v112, v94, v95
	v_max3_f32 v112, v113, v93, v112
	v_mov_b32_e32 v113, v112
	s_nop 1
	v_permlane32_swap_b32_e32 v112, v113
	v_max_f32_e32 v113, v113, v113
	v_max_f32_e32 v112, v112, v112
	v_max_f32_e32 v112, v112, v113
	v_cmp_lt_f32_e32 vcc, s3, v112
	s_cbranch_vccz .LBB0_944
	v_max_f32_e32 v64, v112, v112
	v_max_f32_e32 v64, 0, v64
	v_exp_f32_e64 v66, -v64
	v_pk_add_f32 v[96:97], v[96:97], v[64:65] op_sel_hi:[1,0] neg_lo:[0,1] neg_hi:[0,1]
	v_pk_add_f32 v[80:81], v[80:81], v[64:65] op_sel_hi:[1,0] neg_lo:[0,1] neg_hi:[0,1]
	v_pk_add_f32 v[98:99], v[98:99], v[64:65] op_sel_hi:[1,0] neg_lo:[0,1] neg_hi:[0,1]
	v_pk_add_f32 v[82:83], v[82:83], v[64:65] op_sel_hi:[1,0] neg_lo:[0,1] neg_hi:[0,1]
	v_pk_add_f32 v[100:101], v[100:101], v[64:65] op_sel_hi:[1,0] neg_lo:[0,1] neg_hi:[0,1]
	v_pk_add_f32 v[84:85], v[84:85], v[64:65] op_sel_hi:[1,0] neg_lo:[0,1] neg_hi:[0,1]
	v_pk_add_f32 v[102:103], v[102:103], v[64:65] op_sel_hi:[1,0] neg_lo:[0,1] neg_hi:[0,1]
	v_pk_add_f32 v[86:87], v[86:87], v[64:65] op_sel_hi:[1,0] neg_lo:[0,1] neg_hi:[0,1]
	v_pk_add_f32 v[104:105], v[104:105], v[64:65] op_sel_hi:[1,0] neg_lo:[0,1] neg_hi:[0,1]
	v_pk_add_f32 v[88:89], v[88:89], v[64:65] op_sel_hi:[1,0] neg_lo:[0,1] neg_hi:[0,1]
	v_pk_add_f32 v[106:107], v[106:107], v[64:65] op_sel_hi:[1,0] neg_lo:[0,1] neg_hi:[0,1]
	v_pk_add_f32 v[90:91], v[90:91], v[64:65] op_sel_hi:[1,0] neg_lo:[0,1] neg_hi:[0,1]
	v_pk_add_f32 v[108:109], v[108:109], v[64:65] op_sel_hi:[1,0] neg_lo:[0,1] neg_hi:[0,1]
	v_pk_add_f32 v[92:93], v[92:93], v[64:65] op_sel_hi:[1,0] neg_lo:[0,1] neg_hi:[0,1]
	v_pk_add_f32 v[110:111], v[110:111], v[64:65] op_sel_hi:[1,0] neg_lo:[0,1] neg_hi:[0,1]
	v_pk_add_f32 v[94:95], v[94:95], v[64:65] op_sel_hi:[1,0] neg_lo:[0,1] neg_hi:[0,1]
	v_add_f32_e32 v64, v167, v64
	v_xor_b32_e32 v64, 0x80000000, v64
	v_mul_f32_e32 v166, v166, v66
	v_pk_mul_f32 v[62:63], v[62:63], v[66:67] op_sel_hi:[1,0]
	v_pk_mul_f32 v[60:61], v[60:61], v[66:67] op_sel_hi:[1,0]
	v_pk_mul_f32 v[58:59], v[58:59], v[66:67] op_sel_hi:[1,0]
	v_pk_mul_f32 v[56:57], v[56:57], v[66:67] op_sel_hi:[1,0]
	v_pk_mul_f32 v[54:55], v[54:55], v[66:67] op_sel_hi:[1,0]
	v_pk_mul_f32 v[52:53], v[52:53], v[66:67] op_sel_hi:[1,0]
	v_pk_mul_f32 v[50:51], v[50:51], v[66:67] op_sel_hi:[1,0]
	v_pk_mul_f32 v[48:49], v[48:49], v[66:67] op_sel_hi:[1,0]
	v_pk_mul_f32 v[46:47], v[46:47], v[66:67] op_sel_hi:[1,0]
	v_pk_mul_f32 v[44:45], v[44:45], v[66:67] op_sel_hi:[1,0]
	v_pk_mul_f32 v[42:43], v[42:43], v[66:67] op_sel_hi:[1,0]
	v_pk_mul_f32 v[40:41], v[40:41], v[66:67] op_sel_hi:[1,0]
	v_pk_mul_f32 v[38:39], v[38:39], v[66:67] op_sel_hi:[1,0]
	v_pk_mul_f32 v[36:37], v[36:37], v[66:67] op_sel_hi:[1,0]
	v_pk_mul_f32 v[34:35], v[34:35], v[66:67] op_sel_hi:[1,0]
	v_pk_mul_f32 v[32:33], v[32:33], v[66:67] op_sel_hi:[1,0]
	v_pk_mul_f32 v[30:31], v[30:31], v[66:67] op_sel_hi:[1,0]
	v_pk_mul_f32 v[28:29], v[28:29], v[66:67] op_sel_hi:[1,0]
	v_pk_mul_f32 v[26:27], v[26:27], v[66:67] op_sel_hi:[1,0]
	v_pk_mul_f32 v[24:25], v[24:25], v[66:67] op_sel_hi:[1,0]
	v_pk_mul_f32 v[22:23], v[22:23], v[66:67] op_sel_hi:[1,0]
	v_pk_mul_f32 v[20:21], v[20:21], v[66:67] op_sel_hi:[1,0]
	v_pk_mul_f32 v[18:19], v[18:19], v[66:67] op_sel_hi:[1,0]
	v_pk_mul_f32 v[16:17], v[16:17], v[66:67] op_sel_hi:[1,0]
	v_pk_mul_f32 v[14:15], v[14:15], v[66:67] op_sel_hi:[1,0]
	v_pk_mul_f32 v[12:13], v[12:13], v[66:67] op_sel_hi:[1,0]
	v_pk_mul_f32 v[10:11], v[10:11], v[66:67] op_sel_hi:[1,0]
	v_pk_mul_f32 v[8:9], v[8:9], v[66:67] op_sel_hi:[1,0]
	v_pk_mul_f32 v[6:7], v[6:7], v[66:67] op_sel_hi:[1,0]
	v_pk_mul_f32 v[4:5], v[4:5], v[66:67] op_sel_hi:[1,0]
	v_pk_mul_f32 v[2:3], v[2:3], v[66:67] op_sel_hi:[1,0]
	v_pk_mul_f32 v[0:1], v[0:1], v[66:67] op_sel_hi:[1,0]
	v_mov_b32_e32 v65, v64
	v_mov_b32_e32 v66, v64
	v_mov_b32_e32 v67, v64
	v_mov_b32_e32 v68, v64
	v_mov_b32_e32 v69, v64
	v_mov_b32_e32 v70, v64
	v_mov_b32_e32 v71, v64
	v_mov_b32_e32 v72, v64
	v_mov_b32_e32 v73, v64
	v_mov_b32_e32 v74, v64
	v_mov_b32_e32 v75, v64
	v_mov_b32_e32 v76, v64
	v_mov_b32_e32 v77, v64
	v_mov_b32_e32 v78, v64
	v_mov_b32_e32 v79, v64
.LBB0_944:
	v_exp_f32_e32 v96, v96
	v_exp_f32_e32 v97, v97
	v_exp_f32_e32 v112, v80
	v_exp_f32_e32 v113, v81
	v_exp_f32_e32 v98, v98
	v_exp_f32_e32 v99, v99
	v_exp_f32_e32 v114, v82
	v_exp_f32_e32 v115, v83
	v_exp_f32_e32 v100, v100
	v_exp_f32_e32 v101, v101
	v_exp_f32_e32 v116, v84
	v_exp_f32_e32 v117, v85
	v_exp_f32_e32 v102, v102
	v_exp_f32_e32 v103, v103
	v_exp_f32_e32 v118, v86
	v_exp_f32_e32 v119, v87
	v_exp_f32_e32 v104, v104
	v_exp_f32_e32 v105, v105
	v_exp_f32_e32 v120, v88
	v_exp_f32_e32 v121, v89
	v_exp_f32_e32 v106, v106
	v_exp_f32_e32 v107, v107
	v_exp_f32_e32 v122, v90
	v_exp_f32_e32 v123, v91
	v_exp_f32_e32 v108, v108
	v_exp_f32_e32 v109, v109
	v_exp_f32_e32 v124, v92
	v_exp_f32_e32 v125, v93
	v_exp_f32_e32 v110, v110
	v_exp_f32_e32 v111, v111
	v_exp_f32_e32 v126, v94
	v_exp_f32_e32 v127, v95
	v_add_u32_e32 v144, 0x8800, v175
	v_cvt_pk_bf16_f32 v84, v96, v97
	v_cvt_pk_bf16_f32 v85, v98, v99
	v_cvt_pk_bf16_f32 v86, v100, v101
	v_cvt_pk_bf16_f32 v87, v102, v103
	v_cvt_pk_bf16_f32 v80, v112, v113
	v_cvt_pk_bf16_f32 v81, v114, v115
	v_cvt_pk_bf16_f32 v82, v116, v117
	v_cvt_pk_bf16_f32 v83, v118, v119
	v_cvt_pk_bf16_f32 v92, v104, v105
	v_cvt_pk_bf16_f32 v93, v106, v107
	v_cvt_pk_bf16_f32 v94, v108, v109
	v_cvt_pk_bf16_f32 v95, v110, v111
	v_cvt_pk_bf16_f32 v88, v120, v121
	v_cvt_pk_bf16_f32 v89, v122, v123
	v_cvt_pk_bf16_f32 v90, v124, v125
	s_and_b64 vcc, exec, s[6:7]
	v_cvt_pk_bf16_f32 v91, v126, v127
	s_cbranch_vccnz .LBB0_946
	ds_read_b128 v[240:243], v175 offset:53248
	ds_read_b128 v[244:247], v175 offset:53280
	ds_read_b128 v[248:251], v175 offset:53312
	ds_read_b128 v[252:255], v175 offset:53344
	s_waitcnt lgkmcnt(3)
	v_mfma_f32_32x32x16_bf16 v[48:63], v[240:243], v[84:87], v[48:63]
	ds_read_b128 v[240:243], v175 offset:57856
	s_waitcnt lgkmcnt(3)
	v_mfma_f32_32x32x16_bf16 v[48:63], v[244:247], v[92:95], v[48:63]
	ds_read_b128 v[244:247], v175 offset:57888
	s_waitcnt lgkmcnt(3)
	v_mfma_f32_32x32x16_bf16 v[48:63], v[248:251], v[80:83], v[48:63]
	ds_read_b128 v[248:251], v175 offset:57920
	s_waitcnt lgkmcnt(3)
	v_mfma_f32_32x32x16_bf16 v[48:63], v[252:255], v[88:91], v[48:63]
	ds_read_b128 v[252:255], v175 offset:57952
	s_waitcnt lgkmcnt(3)
	v_mfma_f32_32x32x16_bf16 v[32:47], v[240:243], v[84:87], v[32:47]
	ds_read_b128 v[240:243], v175 offset:62464
	s_waitcnt lgkmcnt(3)
	v_mfma_f32_32x32x16_bf16 v[32:47], v[244:247], v[92:95], v[32:47]
	ds_read_b128 v[244:247], v175 offset:62496
	s_waitcnt lgkmcnt(3)
	v_mfma_f32_32x32x16_bf16 v[32:47], v[248:251], v[80:83], v[32:47]
	ds_read_b128 v[248:251], v175 offset:62528
	s_waitcnt lgkmcnt(3)
	v_mfma_f32_32x32x16_bf16 v[32:47], v[252:255], v[88:91], v[32:47]
	ds_read_b128 v[252:255], v175 offset:62560
	s_waitcnt lgkmcnt(3)
	v_mfma_f32_32x32x16_bf16 v[16:31], v[240:243], v[84:87], v[16:31]
	ds_read_b128 v[240:243], v144 offset:32256
	s_waitcnt lgkmcnt(3)
	v_mfma_f32_32x32x16_bf16 v[16:31], v[244:247], v[92:95], v[16:31]
	ds_read_b128 v[244:247], v144 offset:32288
	s_waitcnt lgkmcnt(3)
	v_mfma_f32_32x32x16_bf16 v[16:31], v[248:251], v[80:83], v[16:31]
	ds_read_b128 v[248:251], v144 offset:32320
	s_waitcnt lgkmcnt(3)
	v_mfma_f32_32x32x16_bf16 v[16:31], v[252:255], v[88:91], v[16:31]
	ds_read_b128 v[252:255], v144 offset:32352
	s_waitcnt lgkmcnt(3)
	v_mfma_f32_32x32x16_bf16 v[0:15], v[240:243], v[84:87], v[0:15]
	s_waitcnt lgkmcnt(2)
	v_mfma_f32_32x32x16_bf16 v[0:15], v[244:247], v[92:95], v[0:15]
	s_waitcnt lgkmcnt(1)
	v_mfma_f32_32x32x16_bf16 v[0:15], v[248:251], v[80:83], v[0:15]
	s_waitcnt lgkmcnt(0)
	v_mfma_f32_32x32x16_bf16 v[0:15], v[252:255], v[88:91], v[0:15]
.LBB0_946:
	s_waitcnt lgkmcnt(0)
	s_barrier
	s_and_b64 vcc, exec, s[8:9]
	s_cbranch_vccnz .LBB0_948
	ds_read_b128 v[240:243], v175 offset:53248
	ds_read_b128 v[244:247], v175 offset:53280
	ds_read_b128 v[248:251], v175 offset:53312
	ds_read_b128 v[252:255], v175 offset:53344
	s_waitcnt lgkmcnt(3)
	v_mfma_f32_32x32x16_bf16 v[48:63], v[240:243], v[84:87], v[48:63]
	ds_read_b128 v[240:243], v175 offset:57856
	s_waitcnt lgkmcnt(3)
	v_mfma_f32_32x32x16_bf16 v[48:63], v[244:247], v[92:95], v[48:63]
	ds_read_b128 v[244:247], v175 offset:57888
	s_waitcnt lgkmcnt(3)
	v_mfma_f32_32x32x16_bf16 v[48:63], v[248:251], v[80:83], v[48:63]
	ds_read_b128 v[248:251], v175 offset:57920
	s_waitcnt lgkmcnt(3)
	v_mfma_f32_32x32x16_bf16 v[48:63], v[252:255], v[88:91], v[48:63]
	ds_read_b128 v[252:255], v175 offset:57952
	s_waitcnt lgkmcnt(3)
	v_mfma_f32_32x32x16_bf16 v[32:47], v[240:243], v[84:87], v[32:47]
	ds_read_b128 v[240:243], v175 offset:62464
	s_waitcnt lgkmcnt(3)
	v_mfma_f32_32x32x16_bf16 v[32:47], v[244:247], v[92:95], v[32:47]
	ds_read_b128 v[244:247], v175 offset:62496
	s_waitcnt lgkmcnt(3)
	v_mfma_f32_32x32x16_bf16 v[32:47], v[248:251], v[80:83], v[32:47]
	ds_read_b128 v[248:251], v175 offset:62528
	s_waitcnt lgkmcnt(3)
	v_mfma_f32_32x32x16_bf16 v[32:47], v[252:255], v[88:91], v[32:47]
	ds_read_b128 v[252:255], v175 offset:62560
	s_waitcnt lgkmcnt(3)
	v_mfma_f32_32x32x16_bf16 v[16:31], v[240:243], v[84:87], v[16:31]
	ds_read_b128 v[240:243], v144 offset:32256
	s_waitcnt lgkmcnt(3)
	v_mfma_f32_32x32x16_bf16 v[16:31], v[244:247], v[92:95], v[16:31]
	ds_read_b128 v[244:247], v144 offset:32288
	s_waitcnt lgkmcnt(3)
	v_mfma_f32_32x32x16_bf16 v[16:31], v[248:251], v[80:83], v[16:31]
	ds_read_b128 v[248:251], v144 offset:32320
	s_waitcnt lgkmcnt(3)
	v_mfma_f32_32x32x16_bf16 v[16:31], v[252:255], v[88:91], v[16:31]
	ds_read_b128 v[252:255], v144 offset:32352
	s_waitcnt lgkmcnt(3)
	v_mfma_f32_32x32x16_bf16 v[0:15], v[240:243], v[84:87], v[0:15]
	s_waitcnt lgkmcnt(2)
	v_mfma_f32_32x32x16_bf16 v[0:15], v[244:247], v[92:95], v[0:15]
	s_waitcnt lgkmcnt(1)
	v_mfma_f32_32x32x16_bf16 v[0:15], v[248:251], v[80:83], v[0:15]
	s_waitcnt lgkmcnt(0)
	v_mfma_f32_32x32x16_bf16 v[0:15], v[252:255], v[88:91], v[0:15]

.LBB0_950:
	v_exp_f32_e32 v80, v80
	v_exp_f32_e32 v81, v81
	v_exp_f32_e32 v96, v64
	v_exp_f32_e32 v97, v65
	v_exp_f32_e32 v82, v82
	v_exp_f32_e32 v83, v83
	v_exp_f32_e32 v98, v66
	v_exp_f32_e32 v99, v67
	v_exp_f32_e32 v84, v84
	v_exp_f32_e32 v85, v85
	v_exp_f32_e32 v100, v68
	v_exp_f32_e32 v101, v69
	v_exp_f32_e32 v86, v86
	v_exp_f32_e32 v87, v87
	v_exp_f32_e32 v102, v70
	v_exp_f32_e32 v103, v71
	v_exp_f32_e32 v88, v88
	v_exp_f32_e32 v89, v89
	v_exp_f32_e32 v104, v72
	v_exp_f32_e32 v105, v73
	v_exp_f32_e32 v90, v90
	v_exp_f32_e32 v91, v91
	v_exp_f32_e32 v106, v74
	v_exp_f32_e32 v107, v75
	v_exp_f32_e32 v92, v92
	v_exp_f32_e32 v93, v93
	v_exp_f32_e32 v108, v76
	v_exp_f32_e32 v109, v77
	v_exp_f32_e32 v94, v94
	v_exp_f32_e32 v95, v95
	v_exp_f32_e32 v110, v78
	v_exp_f32_e32 v111, v79
	v_cvt_pk_bf16_f32 v68, v80, v81
	v_cvt_pk_bf16_f32 v69, v82, v83
	v_cvt_pk_bf16_f32 v70, v84, v85
	v_cvt_pk_bf16_f32 v71, v86, v87
	v_cvt_pk_bf16_f32 v64, v96, v97
	v_cvt_pk_bf16_f32 v65, v98, v99
	v_cvt_pk_bf16_f32 v66, v100, v101
	v_cvt_pk_bf16_f32 v67, v102, v103
	v_cvt_pk_bf16_f32 v76, v88, v89
	v_cvt_pk_bf16_f32 v77, v90, v91
	v_cvt_pk_bf16_f32 v78, v92, v93
	v_cvt_pk_bf16_f32 v79, v94, v95
	v_cvt_pk_bf16_f32 v72, v104, v105
	v_cvt_pk_bf16_f32 v73, v106, v107
	v_cvt_pk_bf16_f32 v74, v108, v109
	s_and_b64 vcc, exec, s[6:7]
	v_cvt_pk_bf16_f32 v75, v110, v111
	s_cbranch_vccnz .LBB0_952
	ds_read_b128 v[240:243], v144 offset:36864
	ds_read_b128 v[244:247], v144 offset:36896
	ds_read_b128 v[248:251], v144 offset:36928
	ds_read_b128 v[252:255], v144 offset:36960
	s_waitcnt lgkmcnt(3)
	v_mfma_f32_32x32x16_bf16 v[48:63], v[240:243], v[68:71], v[48:63]
	ds_read_b128 v[240:243], v144 offset:41472
	s_waitcnt lgkmcnt(3)
	v_mfma_f32_32x32x16_bf16 v[48:63], v[244:247], v[76:79], v[48:63]
	ds_read_b128 v[244:247], v144 offset:41504
	s_waitcnt lgkmcnt(3)
	v_mfma_f32_32x32x16_bf16 v[48:63], v[248:251], v[64:67], v[48:63]
	ds_read_b128 v[248:251], v144 offset:41536
	s_waitcnt lgkmcnt(3)
	v_mfma_f32_32x32x16_bf16 v[48:63], v[252:255], v[72:75], v[48:63]
	ds_read_b128 v[252:255], v144 offset:41568
	s_waitcnt lgkmcnt(3)
	v_mfma_f32_32x32x16_bf16 v[32:47], v[240:243], v[68:71], v[32:47]
	ds_read_b128 v[240:243], v144 offset:46080
	s_waitcnt lgkmcnt(3)
	v_mfma_f32_32x32x16_bf16 v[32:47], v[244:247], v[76:79], v[32:47]
	ds_read_b128 v[244:247], v144 offset:46112
	s_waitcnt lgkmcnt(3)
	v_mfma_f32_32x32x16_bf16 v[32:47], v[248:251], v[64:67], v[32:47]
	ds_read_b128 v[248:251], v144 offset:46144
	s_waitcnt lgkmcnt(3)
	v_mfma_f32_32x32x16_bf16 v[32:47], v[252:255], v[72:75], v[32:47]
	ds_read_b128 v[252:255], v144 offset:46176
	s_waitcnt lgkmcnt(3)
	v_mfma_f32_32x32x16_bf16 v[16:31], v[240:243], v[68:71], v[16:31]
	ds_read_b128 v[240:243], v144 offset:50688
	s_waitcnt lgkmcnt(3)
	v_mfma_f32_32x32x16_bf16 v[16:31], v[244:247], v[76:79], v[16:31]
	ds_read_b128 v[244:247], v144 offset:50720
	s_waitcnt lgkmcnt(3)
	v_mfma_f32_32x32x16_bf16 v[16:31], v[248:251], v[64:67], v[16:31]
	ds_read_b128 v[248:251], v144 offset:50752
	s_waitcnt lgkmcnt(3)
	v_mfma_f32_32x32x16_bf16 v[16:31], v[252:255], v[72:75], v[16:31]
	ds_read_b128 v[252:255], v144 offset:50784
	s_waitcnt lgkmcnt(3)
	v_mfma_f32_32x32x16_bf16 v[0:15], v[240:243], v[68:71], v[0:15]
	s_waitcnt lgkmcnt(2)
	v_mfma_f32_32x32x16_bf16 v[0:15], v[244:247], v[76:79], v[0:15]
	s_waitcnt lgkmcnt(1)
	v_mfma_f32_32x32x16_bf16 v[0:15], v[248:251], v[64:67], v[0:15]
	s_waitcnt lgkmcnt(0)
	v_mfma_f32_32x32x16_bf16 v[0:15], v[252:255], v[72:75], v[0:15]
.LBB0_952:
	s_waitcnt lgkmcnt(0)
	s_barrier
	s_and_b64 vcc, exec, s[0:1]
	s_cbranch_vccz .LBB0_954
	v_add3_u32 v113, s81, v164, v165
	ds_read_b128 v[240:243], v113
	ds_read_b128 v[244:247], v113 offset:32
	ds_read_b128 v[248:251], v113 offset:64
	ds_read_b128 v[252:255], v113 offset:96
	s_waitcnt lgkmcnt(3)
	v_mfma_f32_32x32x16_bf16 v[48:63], v[240:243], v[68:71], v[48:63]
	ds_read_b128 v[240:243], v113 offset:4608
	s_waitcnt lgkmcnt(3)
	v_mfma_f32_32x32x16_bf16 v[48:63], v[244:247], v[76:79], v[48:63]
	ds_read_b128 v[244:247], v113 offset:4640
	s_waitcnt lgkmcnt(3)
	v_mfma_f32_32x32x16_bf16 v[48:63], v[248:251], v[64:67], v[48:63]
	ds_read_b128 v[248:251], v113 offset:4672
	s_waitcnt lgkmcnt(3)
	v_mfma_f32_32x32x16_bf16 v[48:63], v[252:255], v[72:75], v[48:63]
	ds_read_b128 v[252:255], v113 offset:4704
	s_waitcnt lgkmcnt(3)
	v_mfma_f32_32x32x16_bf16 v[32:47], v[240:243], v[68:71], v[32:47]
	ds_read_b128 v[240:243], v113 offset:9216
	s_waitcnt lgkmcnt(3)
	v_mfma_f32_32x32x16_bf16 v[32:47], v[244:247], v[76:79], v[32:47]
	ds_read_b128 v[244:247], v113 offset:9248
	s_waitcnt lgkmcnt(3)
	v_mfma_f32_32x32x16_bf16 v[32:47], v[248:251], v[64:67], v[32:47]
	ds_read_b128 v[248:251], v113 offset:9280
	s_waitcnt lgkmcnt(3)
	v_mfma_f32_32x32x16_bf16 v[32:47], v[252:255], v[72:75], v[32:47]
	ds_read_b128 v[252:255], v113 offset:9312
	s_waitcnt lgkmcnt(3)
	v_mfma_f32_32x32x16_bf16 v[16:31], v[240:243], v[68:71], v[16:31]
	ds_read_b128 v[240:243], v113 offset:13824
	s_waitcnt lgkmcnt(3)
	v_mfma_f32_32x32x16_bf16 v[16:31], v[244:247], v[76:79], v[16:31]
	ds_read_b128 v[244:247], v113 offset:13856
	s_waitcnt lgkmcnt(3)
	v_mfma_f32_32x32x16_bf16 v[16:31], v[248:251], v[64:67], v[16:31]
	ds_read_b128 v[248:251], v113 offset:13888
	s_waitcnt lgkmcnt(3)
	v_mfma_f32_32x32x16_bf16 v[16:31], v[252:255], v[72:75], v[16:31]
	ds_read_b128 v[252:255], v113 offset:13920
	s_waitcnt lgkmcnt(3)
	v_mfma_f32_32x32x16_bf16 v[0:15], v[240:243], v[68:71], v[0:15]
	s_waitcnt lgkmcnt(2)
	v_mfma_f32_32x32x16_bf16 v[0:15], v[244:247], v[76:79], v[0:15]
	s_waitcnt lgkmcnt(1)
	v_mfma_f32_32x32x16_bf16 v[0:15], v[248:251], v[64:67], v[0:15]
	s_waitcnt lgkmcnt(0)
	v_mfma_f32_32x32x16_bf16 v[0:15], v[252:255], v[72:75], v[0:15]

.LBB0_956:
	s_cmpk_gt_u32 s37, 0xff
	s_waitcnt lgkmcnt(0)
	s_barrier
	s_cbranch_scc1 .LBB0_924
	s_lshl_b32 s0, s37, 8
	v_lshl_add_u32 v68, v64, 2, 0
	s_and_b32 s1, s0, 0xc000
	v_add_u32_e32 v69, s1, v68
	ds_read2st64_b32 v[96:97], v69 offset1:1
	ds_read2st64_b32 v[98:99], v69 offset0:2 offset1:3
	ds_read2st64_b32 v[112:113], v69 offset0:4 offset1:5
	ds_read2st64_b32 v[116:117], v69 offset0:6 offset1:7
	ds_read2st64_b32 v[118:119], v69 offset0:8 offset1:9
	ds_read2st64_b32 v[120:121], v69 offset0:10 offset1:11
	ds_read2st64_b32 v[122:123], v69 offset0:12 offset1:13
	ds_read2st64_b32 v[126:127], v69 offset0:14 offset1:15
	ds_read2st64_b32 v[128:129], v69 offset0:16 offset1:17
	ds_read2st64_b32 v[124:125], v69 offset0:18 offset1:19
	ds_read2st64_b32 v[130:131], v69 offset0:20 offset1:21
	ds_read2st64_b32 v[138:139], v69 offset0:22 offset1:23
	ds_read2st64_b32 v[132:133], v69 offset0:24 offset1:25
	ds_read2st64_b32 v[144:145], v69 offset0:26 offset1:27
	ds_read2st64_b32 v[148:149], v69 offset0:28 offset1:29
	ds_read2st64_b32 v[164:165], v69 offset0:30 offset1:31
	ds_read2st64_b32 v[140:141], v69 offset0:32 offset1:33
	ds_read2st64_b32 v[150:151], v69 offset0:34 offset1:35
	ds_read2st64_b32 v[134:135], v69 offset0:36 offset1:37
	ds_read2st64_b32 v[142:143], v69 offset0:38 offset1:39
	ds_read2st64_b32 v[104:105], v69 offset0:40 offset1:41
	ds_read2st64_b32 v[106:107], v69 offset0:42 offset1:43
	ds_read2st64_b32 v[90:91], v69 offset0:44 offset1:45
	ds_read2st64_b32 v[92:93], v69 offset0:46 offset1:47
	ds_read2st64_b32 v[86:87], v69 offset0:48 offset1:49
	ds_read2st64_b32 v[88:89], v69 offset0:50 offset1:51
	ds_read2st64_b32 v[82:83], v69 offset0:52 offset1:53
	ds_read2st64_b32 v[84:85], v69 offset0:54 offset1:55
	ds_read2st64_b32 v[78:79], v69 offset0:56 offset1:57
	ds_read2st64_b32 v[80:81], v69 offset0:58 offset1:59
	ds_read2st64_b32 v[64:65], v69 offset0:60 offset1:61
	s_or_b32 s0, s0, 0x3f00
	s_movk_i32 s6, 0x1400
	s_mov_b32 s3, s41
	s_waitcnt lgkmcnt(14)
	v_pk_mul_f32 v[96:97], v[160:161], v[96:97]
	s_waitcnt lgkmcnt(0)
	v_pk_mul_f32 v[64:65], v[160:161], v[64:65]
	v_pk_mul_f32 v[98:99], v[160:161], v[98:99]
	v_pk_fma_f32 v[66:67], v[12:13], v[72:73], v[64:65] op_sel_hi:[1,0,1] neg_lo:[0,0,1] neg_hi:[0,0,1]
	v_add_u32_e32 v13, s0, v68
	ds_read_b32 v12, v69 offset:15872
	ds_read_b32 v13, v13
	v_pk_mul_f32 v[112:113], v[160:161], v[112:113]
	v_pk_mul_f32 v[116:117], v[160:161], v[116:117]
	v_pk_mul_f32 v[118:119], v[160:161], v[118:119]
	v_pk_mul_f32 v[120:121], v[160:161], v[120:121]
	s_waitcnt lgkmcnt(0)
	v_pk_mul_f32 v[12:13], v[160:161], v[12:13]
	v_pk_mul_f32 v[122:123], v[160:161], v[122:123]
	v_pk_fma_f32 v[64:65], v[14:15], v[72:73], v[12:13] op_sel_hi:[1,0,1] neg_lo:[0,0,1] neg_hi:[0,0,1]
	v_mov_b64_e32 v[14:15], s[4:5]
	v_mad_u64_u32 v[14:15], s[0:1], v196, s6, v[14:15]
	v_mov_b32_e32 v68, v15
	v_mad_u64_u32 v[68:69], s[0:1], v195, s6, v[68:69]
	v_mov_b32_e32 v15, v68
	v_lshrrev_b32_e32 v68, 3, v194
	v_and_b32_e32 v73, 4, v68
	v_lshl_add_u64 v[12:13], v[162:163], 0, s[2:3]
	v_lshlrev_b32_e32 v192, 1, v73
	v_lshl_add_u64 v[12:13], v[12:13], 0, v[192:193]
	s_mov_b64 s[0:1], 0x1000
	v_lshl_add_u64 v[68:69], v[12:13], 0, s[0:1]
	s_movk_i32 s0, 0x1000
	v_add_co_u32_e32 v12, vcc, s0, v12
	v_pk_fma_f32 v[96:97], v[48:49], v[72:73], v[96:97] op_sel_hi:[1,0,1] neg_lo:[0,0,1] neg_hi:[0,0,1]
	s_nop 0
	v_addc_co_u32_e32 v13, vcc, 0, v13, vcc
	global_load_dwordx2 v[100:101], v[12:13], off
	global_load_dwordx2 v[162:163], v[68:69], off offset:16
	global_load_dwordx2 v[146:147], v[68:69], off offset:32
	global_load_dwordx2 v[136:137], v[68:69], off offset:48
	global_load_dwordx2 v[182:183], v[68:69], off offset:64
	global_load_dwordx2 v[188:189], v[68:69], off offset:80
	global_load_dwordx2 v[186:187], v[68:69], off offset:96
	global_load_dwordx2 v[180:181], v[68:69], off offset:112
	global_load_dwordx2 v[174:175], v[68:69], off offset:128
	global_load_dwordx2 v[168:169], v[68:69], off offset:144
	global_load_dwordx2 v[158:159], v[68:69], off offset:160
	global_load_dwordx2 v[152:153], v[68:69], off offset:176
	global_load_dwordx2 v[114:115], v[68:69], off offset:192
	global_load_dwordx2 v[94:95], v[68:69], off offset:208
	global_load_dwordx2 v[70:71], v[68:69], off offset:224
	s_nop 0
	global_load_dwordx2 v[68:69], v[68:69], off offset:240
	v_lshlrev_b32_e32 v205, 2, v73
	v_pk_fma_f32 v[50:51], v[50:51], v[72:73], v[98:99] op_sel_hi:[1,0,1] neg_lo:[0,0,1] neg_hi:[0,0,1]
	v_pk_mul_f32 v[126:127], v[160:161], v[126:127]
	v_pk_mul_f32 v[124:125], v[160:161], v[124:125]
	v_pk_mul_f32 v[80:81], v[160:161], v[80:81]
	v_pk_mul_f32 v[78:79], v[160:161], v[78:79]
	v_pk_mul_f32 v[110:111], v[96:97], v[96:97]
	v_lshl_add_u64 v[154:155], v[14:15], 0, s[2:3]
	global_load_dwordx4 v[12:15], v205, s[10:11]
	v_pk_mul_f32 v[108:109], v[50:51], v[50:51]
	v_pk_mul_f32 v[74:75], v[66:67], v[66:67]
	v_pk_mul_f32 v[76:77], v[64:65], v[64:65]
	s_mov_b64 s[0:1], 0x24000400
	s_waitcnt vmcnt(0) lgkmcnt(0)
	v_lshlrev_b32_e32 v48, 16, v100
	v_mul_f32_e32 v73, 0xbfb8aa3b, v48
	v_exp_f32_e32 v73, v73
	v_and_b32_e32 v49, 0xffff0000, v100
	v_add_f32_e32 v73, 1.0, v73
	v_rcp_f32_e32 v98, v73
	v_mul_f32_e32 v73, 0xbfb8aa3b, v49
	v_exp_f32_e32 v73, v73
	s_nop 0
	v_add_f32_e32 v73, 1.0, v73
	v_rcp_f32_e32 v99, v73
	s_nop 0
	v_pk_mul_f32 v[98:99], v[98:99], v[48:49]
	v_lshlrev_b32_e32 v48, 16, v101
	v_mul_f32_e32 v73, 0xbfb8aa3b, v48
	v_exp_f32_e32 v73, v73
	v_and_b32_e32 v49, 0xffff0000, v101
	v_add_f32_e32 v73, 1.0, v73
	v_rcp_f32_e32 v100, v73
	v_mul_f32_e32 v73, 0xbfb8aa3b, v49
	v_exp_f32_e32 v73, v73
	s_nop 0
	v_add_f32_e32 v73, 1.0, v73
	v_pk_fma_f32 v[52:53], v[52:53], v[72:73], v[112:113] op_sel_hi:[1,0,1] neg_lo:[0,0,1] neg_hi:[0,0,1]
	v_lshlrev_b32_e32 v112, 16, v162
	v_rcp_f32_e32 v101, v73
	v_pk_fma_f32 v[54:55], v[54:55], v[72:73], v[116:117] op_sel_hi:[1,0,1] neg_lo:[0,0,1] neg_hi:[0,0,1]
	v_mul_f32_e32 v73, 0xbfb8aa3b, v112
	v_exp_f32_e32 v73, v73
	v_and_b32_e32 v113, 0xffff0000, v162
	v_pk_mul_f32 v[156:157], v[52:53], v[52:53]
	v_pk_mul_f32 v[102:103], v[100:101], v[48:49]
	v_add_f32_e32 v73, 1.0, v73
	v_rcp_f32_e32 v116, v73
	v_mul_f32_e32 v73, 0xbfb8aa3b, v113
	v_exp_f32_e32 v73, v73
	v_lshl_add_u64 v[100:101], v[154:155], 0, v[192:193]
	v_pk_mul_f32 v[154:155], v[54:55], v[54:55]
	v_lshl_add_u64 v[48:49], v[100:101], 0, s[0:1]
	v_add_f32_e32 v73, 1.0, v73
	v_rcp_f32_e32 v117, v73
	s_mov_b32 s0, 0x800000
	v_pk_mul_f32 v[112:113], v[116:117], v[112:113]
	v_lshlrev_b32_e32 v116, 16, v163
	v_mul_f32_e32 v73, 0xbfb8aa3b, v116
	v_exp_f32_e32 v73, v73
	v_and_b32_e32 v117, 0xffff0000, v163
	v_add_f32_e32 v73, 1.0, v73
	v_rcp_f32_e32 v162, v73
	v_mul_f32_e32 v73, 0xbfb8aa3b, v117
	v_exp_f32_e32 v73, v73
	s_nop 0
	v_add_f32_e32 v73, 1.0, v73
	v_pk_fma_f32 v[56:57], v[56:57], v[72:73], v[118:119] op_sel_hi:[1,0,1] neg_lo:[0,0,1] neg_hi:[0,0,1]
	v_lshlrev_b32_e32 v118, 16, v146
	v_rcp_f32_e32 v163, v73
	v_pk_fma_f32 v[58:59], v[58:59], v[72:73], v[120:121] op_sel_hi:[1,0,1] neg_lo:[0,0,1] neg_hi:[0,0,1]
	v_mul_f32_e32 v73, 0xbfb8aa3b, v118
	v_exp_f32_e32 v73, v73
	v_and_b32_e32 v119, 0xffff0000, v146
	v_pk_mul_f32 v[166:167], v[56:57], v[56:57]
	v_pk_mul_f32 v[116:117], v[162:163], v[116:117]
	v_add_f32_e32 v73, 1.0, v73
	v_rcp_f32_e32 v120, v73
	v_mul_f32_e32 v73, 0xbfb8aa3b, v119
	v_exp_f32_e32 v73, v73
	v_pk_mul_f32 v[162:163], v[58:59], v[58:59]
	v_add_f32_e32 v73, 1.0, v73
	v_rcp_f32_e32 v121, v73
	s_nop 0
	v_pk_mul_f32 v[118:119], v[120:121], v[118:119]
	v_lshlrev_b32_e32 v120, 16, v147
	v_mul_f32_e32 v73, 0xbfb8aa3b, v120
	v_exp_f32_e32 v73, v73
	v_and_b32_e32 v121, 0xffff0000, v147
	v_add_f32_e32 v73, 1.0, v73
	v_rcp_f32_e32 v146, v73
	v_mul_f32_e32 v73, 0xbfb8aa3b, v121
	v_exp_f32_e32 v73, v73
	s_nop 0
	v_add_f32_e32 v73, 1.0, v73
	v_pk_fma_f32 v[60:61], v[60:61], v[72:73], v[122:123] op_sel_hi:[1,0,1] neg_lo:[0,0,1] neg_hi:[0,0,1]
	v_lshlrev_b32_e32 v122, 16, v136
	v_rcp_f32_e32 v147, v73
	v_pk_fma_f32 v[62:63], v[62:63], v[72:73], v[126:127] op_sel_hi:[1,0,1] neg_lo:[0,0,1] neg_hi:[0,0,1]
	v_mul_f32_e32 v73, 0xbfb8aa3b, v122
	v_exp_f32_e32 v73, v73
	v_and_b32_e32 v123, 0xffff0000, v136
	v_pk_mul_f32 v[120:121], v[146:147], v[120:121]
	v_pk_mul_f32 v[172:173], v[60:61], v[60:61]
	v_add_f32_e32 v73, 1.0, v73
	v_rcp_f32_e32 v126, v73
	v_mul_f32_e32 v73, 0xbfb8aa3b, v123
	v_exp_f32_e32 v73, v73
	v_pk_mul_f32 v[170:171], v[62:63], v[62:63]
	v_add_f32_e32 v73, 1.0, v73
	v_rcp_f32_e32 v127, v73
	s_nop 0
	v_pk_mul_f32 v[122:123], v[126:127], v[122:123]
	v_lshlrev_b32_e32 v126, 16, v137
	v_mul_f32_e32 v73, 0xbfb8aa3b, v126
	v_exp_f32_e32 v73, v73
	v_and_b32_e32 v127, 0xffff0000, v137
	v_add_f32_e32 v73, 1.0, v73
	v_rcp_f32_e32 v136, v73
	v_mul_f32_e32 v73, 0xbfb8aa3b, v127
	v_exp_f32_e32 v73, v73
	s_nop 0
	v_add_f32_e32 v73, 1.0, v73
	v_rcp_f32_e32 v137, v73
	v_pk_fma_f32 v[124:125], v[34:35], v[72:73], v[124:125] op_sel_hi:[1,0,1] neg_lo:[0,0,1] neg_hi:[0,0,1]
	v_pk_mul_f32 v[34:35], v[160:161], v[128:129]
	v_pk_mul_f32 v[176:177], v[124:125], v[124:125]
	v_pk_mul_f32 v[126:127], v[136:137], v[126:127]
	v_pk_fma_f32 v[136:137], v[32:33], v[72:73], v[34:35] op_sel_hi:[1,0,1] neg_lo:[0,0,1] neg_hi:[0,0,1]
	v_lshlrev_b32_e32 v32, 16, v182
	v_and_b32_e32 v33, 0xffff0000, v182
	v_mul_f32_e32 v34, 0xbfb8aa3b, v32
	v_mul_f32_e32 v35, 0xbfb8aa3b, v33
	v_exp_f32_e32 v34, v34
	v_exp_f32_e32 v35, v35
	v_pk_mul_f32 v[178:179], v[136:137], v[136:137]
	v_add_f32_e32 v34, 1.0, v34
	v_add_f32_e32 v35, 1.0, v35
	v_rcp_f32_e32 v34, v34
	v_rcp_f32_e32 v35, v35
	s_nop 0
	v_pk_mul_f32 v[146:147], v[34:35], v[32:33]
	v_lshlrev_b32_e32 v32, 16, v183
	v_and_b32_e32 v33, 0xffff0000, v183
	v_mul_f32_e32 v34, 0xbfb8aa3b, v32
	v_mul_f32_e32 v35, 0xbfb8aa3b, v33
	v_exp_f32_e32 v34, v34
	v_exp_f32_e32 v35, v35
	v_add_f32_e32 v34, 1.0, v34
	v_add_f32_e32 v35, 1.0, v35
	v_rcp_f32_e32 v34, v34
	v_rcp_f32_e32 v35, v35
	s_nop 0
	v_pk_mul_f32 v[128:129], v[34:35], v[32:33]
	v_pk_mul_f32 v[34:35], v[160:161], v[130:131]
	v_pk_mul_f32 v[32:33], v[160:161], v[138:139]
	v_pk_fma_f32 v[130:131], v[36:37], v[72:73], v[34:35] op_sel_hi:[1,0,1] neg_lo:[0,0,1] neg_hi:[0,0,1]
	v_lshlrev_b32_e32 v34, 16, v188
	v_and_b32_e32 v35, 0xffff0000, v188
	v_mul_f32_e32 v36, 0xbfb8aa3b, v34
	v_mul_f32_e32 v37, 0xbfb8aa3b, v35
	v_exp_f32_e32 v36, v36
	v_exp_f32_e32 v37, v37
	v_pk_fma_f32 v[32:33], v[38:39], v[72:73], v[32:33] op_sel_hi:[1,0,1] neg_lo:[0,0,1] neg_hi:[0,0,1]
	v_pk_mul_f32 v[184:185], v[130:131], v[130:131]
	v_add_f32_e32 v36, 1.0, v36
	v_add_f32_e32 v37, 1.0, v37
	v_rcp_f32_e32 v36, v36
	v_rcp_f32_e32 v37, v37
	v_pk_mul_f32 v[182:183], v[32:33], v[32:33]
	v_pk_mul_f32 v[138:139], v[36:37], v[34:35]
	v_lshlrev_b32_e32 v34, 16, v189
	v_and_b32_e32 v35, 0xffff0000, v189
	v_mul_f32_e32 v36, 0xbfb8aa3b, v34
	v_mul_f32_e32 v37, 0xbfb8aa3b, v35
	v_exp_f32_e32 v36, v36
	v_exp_f32_e32 v37, v37
	v_add_f32_e32 v36, 1.0, v36
	v_add_f32_e32 v37, 1.0, v37
	v_rcp_f32_e32 v36, v36
	v_rcp_f32_e32 v37, v37
	s_nop 0
	v_pk_mul_f32 v[38:39], v[36:37], v[34:35]
	v_pk_mul_f32 v[36:37], v[160:161], v[132:133]
	v_pk_mul_f32 v[34:35], v[160:161], v[144:145]
	v_pk_fma_f32 v[132:133], v[40:41], v[72:73], v[36:37] op_sel_hi:[1,0,1] neg_lo:[0,0,1] neg_hi:[0,0,1]
	v_lshlrev_b32_e32 v36, 16, v186
	v_and_b32_e32 v37, 0xffff0000, v186
	v_mul_f32_e32 v40, 0xbfb8aa3b, v36
	v_mul_f32_e32 v41, 0xbfb8aa3b, v37
	v_exp_f32_e32 v40, v40
	v_exp_f32_e32 v41, v41
	v_pk_fma_f32 v[34:35], v[42:43], v[72:73], v[34:35] op_sel_hi:[1,0,1] neg_lo:[0,0,1] neg_hi:[0,0,1]
	v_pk_mul_f32 v[42:43], v[160:161], v[148:149]
	v_add_f32_e32 v40, 1.0, v40
	v_add_f32_e32 v41, 1.0, v41
	v_rcp_f32_e32 v40, v40
	v_rcp_f32_e32 v41, v41
	v_pk_mul_f32 v[190:191], v[132:133], v[132:133]
	v_pk_mul_f32 v[188:189], v[34:35], v[34:35]
	v_pk_mul_f32 v[144:145], v[40:41], v[36:37]
	v_lshlrev_b32_e32 v36, 16, v187
	v_and_b32_e32 v37, 0xffff0000, v187
	v_mul_f32_e32 v40, 0xbfb8aa3b, v36
	v_mul_f32_e32 v41, 0xbfb8aa3b, v37
	v_exp_f32_e32 v40, v40
	v_exp_f32_e32 v41, v41
	v_add_f32_e32 v40, 1.0, v40
	v_add_f32_e32 v41, 1.0, v41
	v_rcp_f32_e32 v40, v40
	v_rcp_f32_e32 v41, v41
	s_nop 0
	v_pk_mul_f32 v[40:41], v[40:41], v[36:37]
	v_pk_mul_f32 v[36:37], v[160:161], v[164:165]
	s_nop 0
	v_pk_fma_f32 v[36:37], v[46:47], v[72:73], v[36:37] op_sel_hi:[1,0,1] neg_lo:[0,0,1] neg_hi:[0,0,1]
	v_pk_fma_f32 v[46:47], v[44:45], v[72:73], v[42:43] op_sel_hi:[1,0,1] neg_lo:[0,0,1] neg_hi:[0,0,1]
	v_lshlrev_b32_e32 v42, 16, v180
	v_and_b32_e32 v43, 0xffff0000, v180
	v_mul_f32_e32 v44, 0xbfb8aa3b, v42
	v_mul_f32_e32 v45, 0xbfb8aa3b, v43
	v_exp_f32_e32 v44, v44
	v_exp_f32_e32 v45, v45
	v_pk_mul_f32 v[186:187], v[46:47], v[46:47]
	v_pk_mul_f32 v[164:165], v[36:37], v[36:37]
	v_add_f32_e32 v44, 1.0, v44
	v_add_f32_e32 v45, 1.0, v45
	v_rcp_f32_e32 v44, v44
	v_rcp_f32_e32 v45, v45
	s_nop 0
	v_pk_mul_f32 v[148:149], v[44:45], v[42:43]
	v_lshlrev_b32_e32 v42, 16, v181
	v_and_b32_e32 v43, 0xffff0000, v181
	v_mul_f32_e32 v44, 0xbfb8aa3b, v42
	v_mul_f32_e32 v45, 0xbfb8aa3b, v43
	v_exp_f32_e32 v44, v44
	v_exp_f32_e32 v45, v45
	v_add_f32_e32 v44, 1.0, v44
	v_add_f32_e32 v45, 1.0, v45
	v_rcp_f32_e32 v44, v44
	v_rcp_f32_e32 v45, v45
	s_nop 0
	v_pk_mul_f32 v[42:43], v[44:45], v[42:43]
	v_pk_mul_f32 v[44:45], v[160:161], v[150:151]
	s_nop 0
	v_pk_fma_f32 v[18:19], v[18:19], v[72:73], v[44:45] op_sel_hi:[1,0,1] neg_lo:[0,0,1] neg_hi:[0,0,1]
	v_pk_mul_f32 v[44:45], v[160:161], v[140:141]
	v_pk_mul_f32 v[180:181], v[18:19], v[18:19]
	v_pk_fma_f32 v[140:141], v[16:17], v[72:73], v[44:45] op_sel_hi:[1,0,1] neg_lo:[0,0,1] neg_hi:[0,0,1]
	v_lshlrev_b32_e32 v16, 16, v174
	v_and_b32_e32 v17, 0xffff0000, v174
	v_mul_f32_e32 v44, 0xbfb8aa3b, v16
	v_mul_f32_e32 v45, 0xbfb8aa3b, v17
	v_exp_f32_e32 v44, v44
	v_exp_f32_e32 v45, v45
	v_pk_mul_f32 v[194:195], v[140:141], v[140:141]
	v_add_f32_e32 v44, 1.0, v44
	v_add_f32_e32 v45, 1.0, v45
	v_rcp_f32_e32 v44, v44
	v_rcp_f32_e32 v45, v45
	s_nop 0
	v_pk_mul_f32 v[150:151], v[44:45], v[16:17]
	v_lshlrev_b32_e32 v16, 16, v175
	v_and_b32_e32 v17, 0xffff0000, v175
	v_mul_f32_e32 v44, 0xbfb8aa3b, v16
	v_mul_f32_e32 v45, 0xbfb8aa3b, v17
	v_exp_f32_e32 v44, v44
	v_exp_f32_e32 v45, v45
	v_add_f32_e32 v44, 1.0, v44
	v_add_f32_e32 v45, 1.0, v45
	v_rcp_f32_e32 v44, v44
	v_rcp_f32_e32 v45, v45
	s_nop 0
	v_pk_mul_f32 v[44:45], v[44:45], v[16:17]
	v_pk_mul_f32 v[16:17], v[160:161], v[142:143]
	s_nop 0
	v_pk_fma_f32 v[16:17], v[22:23], v[72:73], v[16:17] op_sel_hi:[1,0,1] neg_lo:[0,0,1] neg_hi:[0,0,1]
	v_pk_mul_f32 v[22:23], v[160:161], v[134:135]
	v_pk_mul_f32 v[174:175], v[16:17], v[16:17]
	v_pk_fma_f32 v[134:135], v[20:21], v[72:73], v[22:23] op_sel_hi:[1,0,1] neg_lo:[0,0,1] neg_hi:[0,0,1]
	v_lshlrev_b32_e32 v20, 16, v168
	v_and_b32_e32 v21, 0xffff0000, v168
	v_mul_f32_e32 v22, 0xbfb8aa3b, v20
	v_mul_f32_e32 v23, 0xbfb8aa3b, v21
	v_exp_f32_e32 v22, v22
	v_exp_f32_e32 v23, v23
	v_pk_mul_f32 v[196:197], v[134:135], v[134:135]
	v_add_f32_e32 v22, 1.0, v22
	v_add_f32_e32 v23, 1.0, v23
	v_rcp_f32_e32 v22, v22
	v_rcp_f32_e32 v23, v23
	s_nop 0
	v_pk_mul_f32 v[142:143], v[22:23], v[20:21]
	v_lshlrev_b32_e32 v20, 16, v169
	v_and_b32_e32 v21, 0xffff0000, v169
	v_mul_f32_e32 v22, 0xbfb8aa3b, v20
	v_mul_f32_e32 v23, 0xbfb8aa3b, v21
	v_exp_f32_e32 v22, v22
	v_exp_f32_e32 v23, v23
	v_add_f32_e32 v22, 1.0, v22
	v_add_f32_e32 v23, 1.0, v23
	v_rcp_f32_e32 v22, v22
	v_rcp_f32_e32 v23, v23
	s_nop 0
	v_pk_mul_f32 v[22:23], v[22:23], v[20:21]
	v_pk_mul_f32 v[20:21], v[160:161], v[106:107]
	s_nop 0
	v_pk_fma_f32 v[20:21], v[26:27], v[72:73], v[20:21] op_sel_hi:[1,0,1] neg_lo:[0,0,1] neg_hi:[0,0,1]
	v_pk_mul_f32 v[26:27], v[160:161], v[104:105]
	v_pk_mul_f32 v[168:169], v[20:21], v[20:21]
	v_pk_fma_f32 v[104:105], v[24:25], v[72:73], v[26:27] op_sel_hi:[1,0,1] neg_lo:[0,0,1] neg_hi:[0,0,1]
	v_lshlrev_b32_e32 v24, 16, v158
	v_and_b32_e32 v25, 0xffff0000, v158
	v_mul_f32_e32 v26, 0xbfb8aa3b, v24
	v_mul_f32_e32 v27, 0xbfb8aa3b, v25
	v_exp_f32_e32 v26, v26
	v_exp_f32_e32 v27, v27
	v_pk_mul_f32 v[198:199], v[104:105], v[104:105]
	v_add_f32_e32 v26, 1.0, v26
	v_add_f32_e32 v27, 1.0, v27
	v_rcp_f32_e32 v26, v26
	v_rcp_f32_e32 v27, v27
	s_nop 0
	v_pk_mul_f32 v[106:107], v[26:27], v[24:25]
	v_lshlrev_b32_e32 v24, 16, v159
	v_and_b32_e32 v25, 0xffff0000, v159
	v_mul_f32_e32 v26, 0xbfb8aa3b, v24
	v_mul_f32_e32 v27, 0xbfb8aa3b, v25
	v_exp_f32_e32 v26, v26
	v_exp_f32_e32 v27, v27
	v_add_f32_e32 v26, 1.0, v26
	v_add_f32_e32 v27, 1.0, v27
	v_rcp_f32_e32 v26, v26
	v_rcp_f32_e32 v27, v27
	s_nop 0
	v_pk_mul_f32 v[26:27], v[26:27], v[24:25]
	v_pk_mul_f32 v[24:25], v[160:161], v[92:93]
	s_nop 0
	v_pk_fma_f32 v[24:25], v[30:31], v[72:73], v[24:25] op_sel_hi:[1,0,1] neg_lo:[0,0,1] neg_hi:[0,0,1]
	v_pk_mul_f32 v[30:31], v[160:161], v[90:91]
	v_pk_mul_f32 v[158:159], v[24:25], v[24:25]
	v_pk_fma_f32 v[90:91], v[28:29], v[72:73], v[30:31] op_sel_hi:[1,0,1] neg_lo:[0,0,1] neg_hi:[0,0,1]
	v_lshlrev_b32_e32 v28, 16, v152
	v_and_b32_e32 v29, 0xffff0000, v152
	v_mul_f32_e32 v30, 0xbfb8aa3b, v28
	v_mul_f32_e32 v31, 0xbfb8aa3b, v29
	v_exp_f32_e32 v30, v30
	v_exp_f32_e32 v31, v31
	v_pk_mul_f32 v[200:201], v[90:91], v[90:91]
	v_add_f32_e32 v30, 1.0, v30
	v_add_f32_e32 v31, 1.0, v31
	v_rcp_f32_e32 v30, v30
	v_rcp_f32_e32 v31, v31
	s_nop 0
	v_pk_mul_f32 v[92:93], v[30:31], v[28:29]
	v_lshlrev_b32_e32 v28, 16, v153
	v_and_b32_e32 v29, 0xffff0000, v153
	v_mul_f32_e32 v30, 0xbfb8aa3b, v28
	v_mul_f32_e32 v31, 0xbfb8aa3b, v29
	v_exp_f32_e32 v30, v30
	v_exp_f32_e32 v31, v31
	v_add_f32_e32 v30, 1.0, v30
	v_add_f32_e32 v31, 1.0, v31
	v_rcp_f32_e32 v30, v30
	v_rcp_f32_e32 v31, v31
	s_nop 0
	v_pk_mul_f32 v[28:29], v[30:31], v[28:29]
	v_pk_mul_f32 v[30:31], v[160:161], v[88:89]
	s_nop 0
	v_pk_fma_f32 v[2:3], v[2:3], v[72:73], v[30:31] op_sel_hi:[1,0,1] neg_lo:[0,0,1] neg_hi:[0,0,1]
	v_pk_mul_f32 v[30:31], v[160:161], v[86:87]
	v_pk_mul_f32 v[152:153], v[2:3], v[2:3]
	v_pk_fma_f32 v[86:87], v[0:1], v[72:73], v[30:31] op_sel_hi:[1,0,1] neg_lo:[0,0,1] neg_hi:[0,0,1]
	v_lshlrev_b32_e32 v0, 16, v114
	v_and_b32_e32 v1, 0xffff0000, v114
	v_mul_f32_e32 v30, 0xbfb8aa3b, v0
	v_mul_f32_e32 v31, 0xbfb8aa3b, v1
	v_exp_f32_e32 v30, v30
	v_exp_f32_e32 v31, v31
	v_pk_mul_f32 v[202:203], v[86:87], v[86:87]
	v_add_f32_e32 v30, 1.0, v30
	v_add_f32_e32 v31, 1.0, v31
	v_rcp_f32_e32 v30, v30
	v_rcp_f32_e32 v31, v31
	s_nop 0
	v_pk_mul_f32 v[88:89], v[30:31], v[0:1]
	v_lshlrev_b32_e32 v0, 16, v115
	v_and_b32_e32 v1, 0xffff0000, v115
	v_mul_f32_e32 v30, 0xbfb8aa3b, v0
	v_mul_f32_e32 v31, 0xbfb8aa3b, v1
	v_exp_f32_e32 v30, v30
	v_exp_f32_e32 v31, v31
	v_add_f32_e32 v30, 1.0, v30
	v_add_f32_e32 v31, 1.0, v31
	v_rcp_f32_e32 v30, v30
	v_rcp_f32_e32 v31, v31
	s_nop 0
	v_pk_mul_f32 v[30:31], v[30:31], v[0:1]
	v_pk_mul_f32 v[0:1], v[160:161], v[84:85]
	s_nop 0
	v_pk_fma_f32 v[0:1], v[6:7], v[72:73], v[0:1] op_sel_hi:[1,0,1] neg_lo:[0,0,1] neg_hi:[0,0,1]
	v_pk_mul_f32 v[6:7], v[160:161], v[82:83]
	v_pk_mul_f32 v[84:85], v[0:1], v[0:1]
	v_pk_fma_f32 v[6:7], v[4:5], v[72:73], v[6:7] op_sel_hi:[1,0,1] neg_lo:[0,0,1] neg_hi:[0,0,1]
	v_lshlrev_b32_e32 v4, 16, v94
	v_mul_f32_e32 v73, 0xbfb8aa3b, v4
	v_exp_f32_e32 v73, v73
	v_and_b32_e32 v5, 0xffff0000, v94
	v_pk_mul_f32 v[114:115], v[6:7], v[6:7]
	v_add_f32_e32 v73, 1.0, v73
	v_rcp_f32_e32 v82, v73
	v_mul_f32_e32 v73, 0xbfb8aa3b, v5
	v_exp_f32_e32 v73, v73
	s_nop 0
	v_add_f32_e32 v73, 1.0, v73
	v_rcp_f32_e32 v83, v73
	s_nop 0
	v_pk_mul_f32 v[82:83], v[82:83], v[4:5]
	v_lshlrev_b32_e32 v4, 16, v95
	v_mul_f32_e32 v73, 0xbfb8aa3b, v4
	v_exp_f32_e32 v73, v73
	v_and_b32_e32 v5, 0xffff0000, v95
	v_add_f32_e32 v73, 1.0, v73
	v_rcp_f32_e32 v94, v73
	v_mul_f32_e32 v73, 0xbfb8aa3b, v5
	v_exp_f32_e32 v73, v73
	s_nop 0
	v_add_f32_e32 v73, 1.0, v73
	v_rcp_f32_e32 v95, v73
	v_pk_fma_f32 v[10:11], v[10:11], v[72:73], v[80:81] op_sel_hi:[1,0,1] neg_lo:[0,0,1] neg_hi:[0,0,1]
	v_pk_fma_f32 v[72:73], v[8:9], v[72:73], v[78:79] op_sel_hi:[1,0,1] neg_lo:[0,0,1] neg_hi:[0,0,1]
	v_lshlrev_b32_e32 v78, 16, v70
	v_and_b32_e32 v79, 0xffff0000, v70
	v_mul_f32_e32 v70, 0xbfb8aa3b, v78
	v_exp_f32_e32 v70, v70
	v_pk_mul_f32 v[4:5], v[94:95], v[4:5]
	v_pk_mul_f32 v[8:9], v[72:73], v[72:73]
	v_pk_mul_f32 v[80:81], v[10:11], v[10:11]
	v_add_f32_e32 v70, 1.0, v70
	v_rcp_f32_e32 v94, v70
	v_mul_f32_e32 v70, 0xbfb8aa3b, v79
	v_exp_f32_e32 v70, v70
	s_nop 0
	v_add_f32_e32 v70, 1.0, v70
	v_rcp_f32_e32 v95, v70
	v_add_f32_e32 v70, v110, v111
	v_add_f32_e32 v70, v70, v108
	v_add_f32_e32 v70, v70, v109
	v_add_f32_e32 v70, v70, v156
	v_add_f32_e32 v70, v70, v157
	v_add_f32_e32 v70, v70, v154
	v_add_f32_e32 v70, v70, v155
	v_add_f32_e32 v70, v70, v166
	v_add_f32_e32 v70, v70, v167
	v_add_f32_e32 v70, v70, v162
	v_add_f32_e32 v70, v70, v163
	v_add_f32_e32 v70, v70, v172
	v_add_f32_e32 v70, v70, v173
	v_add_f32_e32 v70, v70, v170
	v_add_f32_e32 v70, v70, v171
	v_add_f32_e32 v70, v70, v178
	v_add_f32_e32 v70, v70, v179
	v_add_f32_e32 v70, v70, v176
	v_add_f32_e32 v70, v70, v177
	v_add_f32_e32 v70, v70, v184
	v_add_f32_e32 v70, v70, v185
	v_add_f32_e32 v70, v70, v182
	v_add_f32_e32 v70, v70, v183
	v_add_f32_e32 v70, v70, v190
	v_add_f32_e32 v70, v70, v191
	v_add_f32_e32 v70, v70, v188
	v_add_f32_e32 v70, v70, v189
	v_add_f32_e32 v70, v70, v186
	v_add_f32_e32 v70, v70, v187
	v_add_f32_e32 v70, v70, v164
	v_add_f32_e32 v70, v70, v165
	v_add_f32_e32 v70, v70, v194
	v_add_f32_e32 v70, v70, v195
	v_add_f32_e32 v70, v70, v180
	v_add_f32_e32 v70, v70, v181
	v_add_f32_e32 v70, v70, v196
	v_add_f32_e32 v70, v70, v197
	v_add_f32_e32 v70, v70, v174
	v_add_f32_e32 v70, v70, v175
	v_add_f32_e32 v70, v70, v198
	v_add_f32_e32 v70, v70, v199
	v_add_f32_e32 v70, v70, v168
	v_add_f32_e32 v70, v70, v169
	v_add_f32_e32 v70, v70, v200
	v_add_f32_e32 v70, v70, v201
	v_add_f32_e32 v70, v70, v158
	v_add_f32_e32 v70, v70, v159
	v_add_f32_e32 v70, v70, v202
	v_add_f32_e32 v70, v70, v203
	v_add_f32_e32 v70, v70, v152
	v_add_f32_e32 v70, v70, v153
	v_add_f32_e32 v70, v70, v114
	v_add_f32_e32 v70, v70, v115
	v_add_f32_e32 v70, v70, v84
	v_add_f32_e32 v70, v70, v85
	v_add_f32_e32 v8, v70, v8
	v_add_f32_e32 v8, v8, v9
	v_add_f32_e32 v8, v8, v80
	v_add_f32_e32 v8, v8, v81
	v_add_f32_e32 v8, v8, v74
	v_add_f32_e32 v8, v8, v75
	v_add_f32_e32 v8, v8, v76
	v_add_f32_e32 v8, v8, v77
	ds_bpermute_b32 v9, v218, v8
	v_pk_mul_f32 v[78:79], v[94:95], v[78:79]
	s_waitcnt lgkmcnt(0)
	v_add_f32_e32 v8, v8, v9
	v_fmamk_f32 v8, v8, 0x3c000000, v207
	v_cmp_gt_f32_e32 vcc, s0, v8
	v_mul_f32_e32 v9, 0x4b800000, v8
	s_brev_b32 s0, 36
	v_cndmask_b32_e32 v8, v8, v9, vcc
	v_rsq_f32_e32 v8, v8
	s_nop 0
	v_mul_f32_e32 v9, 0x45800000, v8
	v_cndmask_b32_e32 v8, v8, v9, vcc
	v_mul_f32_e32 v8, v204, v8
	v_pk_mul_f32 v[74:75], v[96:97], v[8:9] op_sel_hi:[1,0]
	v_pk_mul_f32 v[50:51], v[50:51], v[8:9] op_sel_hi:[1,0]
	v_pk_mul_f32 v[12:13], v[74:75], v[12:13]
	v_pk_mul_f32 v[14:15], v[50:51], v[14:15]
	v_pk_mul_f32 v[12:13], v[98:99], v[12:13]
	v_pk_mul_f32 v[14:15], v[102:103], v[14:15]
	v_cvt_pk_bf16_f32 v12, v12, v13
	v_cvt_pk_bf16_f32 v13, v14, v15
	v_add_co_u32_e32 v14, vcc, s0, v100
	v_pk_mul_f32 v[50:51], v[52:53], v[8:9] op_sel_hi:[1,0]
	s_nop 0
	v_addc_co_u32_e32 v15, vcc, 0, v101, vcc
	flat_store_dwordx2 v[14:15], v[12:13] offset:1024
	global_load_dwordx4 v[12:15], v205, s[10:11] offset:32
	v_pk_mul_f32 v[32:33], v[32:33], v[8:9] op_sel_hi:[1,0]
	v_pk_mul_f32 v[18:19], v[18:19], v[8:9] op_sel_hi:[1,0]
	v_pk_mul_f32 v[16:17], v[16:17], v[8:9] op_sel_hi:[1,0]
	v_pk_mul_f32 v[2:3], v[2:3], v[8:9] op_sel_hi:[1,0]
	v_pk_mul_f32 v[0:1], v[0:1], v[8:9] op_sel_hi:[1,0]
	v_pk_mul_f32 v[10:11], v[10:11], v[8:9] op_sel_hi:[1,0]
	s_waitcnt vmcnt(0)
	v_pk_mul_f32 v[12:13], v[50:51], v[12:13]
	v_pk_mul_f32 v[50:51], v[54:55], v[8:9] op_sel_hi:[1,0]
	v_pk_mul_f32 v[12:13], v[112:113], v[12:13]
	v_pk_mul_f32 v[14:15], v[50:51], v[14:15]
	v_cvt_pk_bf16_f32 v12, v12, v13
	v_pk_mul_f32 v[14:15], v[116:117], v[14:15]
	v_pk_mul_f32 v[50:51], v[56:57], v[8:9] op_sel_hi:[1,0]
	v_cvt_pk_bf16_f32 v13, v14, v15
	flat_store_dwordx2 v[48:49], v[12:13] offset:16
	global_load_dwordx4 v[12:15], v205, s[10:11] offset:64
	s_waitcnt vmcnt(0)
	v_pk_mul_f32 v[12:13], v[50:51], v[12:13]
	v_pk_mul_f32 v[50:51], v[58:59], v[8:9] op_sel_hi:[1,0]
	v_pk_mul_f32 v[12:13], v[118:119], v[12:13]
	v_pk_mul_f32 v[14:15], v[50:51], v[14:15]
	v_cvt_pk_bf16_f32 v12, v12, v13
	v_pk_mul_f32 v[14:15], v[120:121], v[14:15]
	v_pk_mul_f32 v[50:51], v[60:61], v[8:9] op_sel_hi:[1,0]
	v_cvt_pk_bf16_f32 v13, v14, v15
	flat_store_dwordx2 v[48:49], v[12:13] offset:32
	global_load_dwordx4 v[12:15], v205, s[10:11] offset:96
	s_waitcnt vmcnt(0)
	v_pk_mul_f32 v[12:13], v[50:51], v[12:13]
	v_pk_mul_f32 v[50:51], v[62:63], v[8:9] op_sel_hi:[1,0]
	v_pk_mul_f32 v[12:13], v[122:123], v[12:13]
	v_pk_mul_f32 v[14:15], v[50:51], v[14:15]
	v_cvt_pk_bf16_f32 v12, v12, v13
	v_pk_mul_f32 v[14:15], v[126:127], v[14:15]
	v_pk_mul_f32 v[50:51], v[136:137], v[8:9] op_sel_hi:[1,0]
	v_cvt_pk_bf16_f32 v13, v14, v15
	flat_store_dwordx2 v[48:49], v[12:13] offset:48
	global_load_dwordx4 v[12:15], v205, s[10:11] offset:128
	s_waitcnt vmcnt(0)
	v_pk_mul_f32 v[12:13], v[50:51], v[12:13]
	v_pk_mul_f32 v[50:51], v[124:125], v[8:9] op_sel_hi:[1,0]
	v_pk_mul_f32 v[12:13], v[146:147], v[12:13]
	v_pk_mul_f32 v[14:15], v[50:51], v[14:15]
	v_cvt_pk_bf16_f32 v12, v12, v13
	v_pk_mul_f32 v[14:15], v[128:129], v[14:15]
	v_pk_mul_f32 v[50:51], v[130:131], v[8:9] op_sel_hi:[1,0]
	v_cvt_pk_bf16_f32 v13, v14, v15
	flat_store_dwordx2 v[48:49], v[12:13] offset:64
	global_load_dwordx4 v[12:15], v205, s[10:11] offset:160
	s_waitcnt vmcnt(0)
	v_pk_mul_f32 v[12:13], v[50:51], v[12:13]
	v_pk_mul_f32 v[14:15], v[32:33], v[14:15]
	v_pk_mul_f32 v[12:13], v[138:139], v[12:13]
	v_pk_mul_f32 v[14:15], v[38:39], v[14:15]
	v_cvt_pk_bf16_f32 v12, v12, v13
	v_cvt_pk_bf16_f32 v13, v14, v15
	flat_store_dwordx2 v[48:49], v[12:13] offset:80
	global_load_dwordx4 v[12:15], v205, s[10:11] offset:192
	v_pk_mul_f32 v[32:33], v[132:133], v[8:9] op_sel_hi:[1,0]
	s_waitcnt vmcnt(0)
	v_pk_mul_f32 v[12:13], v[32:33], v[12:13]
	v_pk_mul_f32 v[32:33], v[34:35], v[8:9] op_sel_hi:[1,0]
	v_pk_mul_f32 v[12:13], v[144:145], v[12:13]
	v_pk_mul_f32 v[14:15], v[32:33], v[14:15]
	v_cvt_pk_bf16_f32 v12, v12, v13
	v_pk_mul_f32 v[14:15], v[40:41], v[14:15]
	v_pk_mul_f32 v[32:33], v[46:47], v[8:9] op_sel_hi:[1,0]
	v_cvt_pk_bf16_f32 v13, v14, v15
	flat_store_dwordx2 v[48:49], v[12:13] offset:96
	global_load_dwordx4 v[12:15], v205, s[10:11] offset:224
	s_waitcnt vmcnt(0)
	v_pk_mul_f32 v[12:13], v[32:33], v[12:13]
	v_pk_mul_f32 v[32:33], v[36:37], v[8:9] op_sel_hi:[1,0]
	v_pk_mul_f32 v[12:13], v[148:149], v[12:13]
	v_pk_mul_f32 v[14:15], v[32:33], v[14:15]
	v_cvt_pk_bf16_f32 v12, v12, v13
	v_pk_mul_f32 v[14:15], v[42:43], v[14:15]
	v_pk_mul_f32 v[32:33], v[140:141], v[8:9] op_sel_hi:[1,0]
	v_cvt_pk_bf16_f32 v13, v14, v15
	flat_store_dwordx2 v[48:49], v[12:13] offset:112
	global_load_dwordx4 v[12:15], v205, s[10:11] offset:256
	s_waitcnt vmcnt(0)
	v_pk_mul_f32 v[12:13], v[32:33], v[12:13]
	v_pk_mul_f32 v[14:15], v[18:19], v[14:15]
	v_pk_mul_f32 v[12:13], v[150:151], v[12:13]
	v_pk_mul_f32 v[14:15], v[44:45], v[14:15]
	v_cvt_pk_bf16_f32 v12, v12, v13
	v_cvt_pk_bf16_f32 v13, v14, v15
	flat_store_dwordx2 v[48:49], v[12:13] offset:128
	global_load_dwordx4 v[12:15], v205, s[10:11] offset:288
	v_pk_mul_f32 v[18:19], v[134:135], v[8:9] op_sel_hi:[1,0]
	s_waitcnt vmcnt(0)
	v_pk_mul_f32 v[14:15], v[16:17], v[14:15]
	v_pk_mul_f32 v[12:13], v[18:19], v[12:13]
	v_pk_mul_f32 v[14:15], v[22:23], v[14:15]
	v_pk_mul_f32 v[12:13], v[142:143], v[12:13]
	v_pk_mul_f32 v[16:17], v[104:105], v[8:9] op_sel_hi:[1,0]
	v_cvt_pk_bf16_f32 v12, v12, v13
	v_cvt_pk_bf16_f32 v13, v14, v15
	flat_store_dwordx2 v[48:49], v[12:13] offset:144
	global_load_dwordx4 v[12:15], v205, s[10:11] offset:320
	s_waitcnt vmcnt(0)
	v_pk_mul_f32 v[12:13], v[16:17], v[12:13]
	v_pk_mul_f32 v[16:17], v[20:21], v[8:9] op_sel_hi:[1,0]
	v_pk_mul_f32 v[12:13], v[106:107], v[12:13]
	v_pk_mul_f32 v[14:15], v[16:17], v[14:15]
	v_cvt_pk_bf16_f32 v12, v12, v13
	v_pk_mul_f32 v[14:15], v[26:27], v[14:15]
	v_pk_mul_f32 v[16:17], v[90:91], v[8:9] op_sel_hi:[1,0]
	v_cvt_pk_bf16_f32 v13, v14, v15
	flat_store_dwordx2 v[48:49], v[12:13] offset:160
	global_load_dwordx4 v[12:15], v205, s[10:11] offset:352
	s_waitcnt vmcnt(0)
	v_pk_mul_f32 v[12:13], v[16:17], v[12:13]
	v_pk_mul_f32 v[16:17], v[24:25], v[8:9] op_sel_hi:[1,0]
	v_pk_mul_f32 v[12:13], v[92:93], v[12:13]
	v_pk_mul_f32 v[14:15], v[16:17], v[14:15]
	v_cvt_pk_bf16_f32 v12, v12, v13
	v_pk_mul_f32 v[14:15], v[28:29], v[14:15]
	v_pk_mul_f32 v[16:17], v[86:87], v[8:9] op_sel_hi:[1,0]
	v_cvt_pk_bf16_f32 v13, v14, v15
	flat_store_dwordx2 v[48:49], v[12:13] offset:176
	global_load_dwordx4 v[12:15], v205, s[10:11] offset:384
	s_waitcnt vmcnt(0)
	v_pk_mul_f32 v[12:13], v[16:17], v[12:13]
	v_pk_mul_f32 v[2:3], v[2:3], v[14:15]
	v_pk_mul_f32 v[12:13], v[88:89], v[12:13]
	v_pk_mul_f32 v[2:3], v[30:31], v[2:3]
	v_cvt_pk_bf16_f32 v12, v12, v13
	v_cvt_pk_bf16_f32 v13, v2, v3
	flat_store_dwordx2 v[48:49], v[12:13] offset:192
	global_load_dwordx4 v[12:15], v205, s[10:11] offset:416
	v_pk_mul_f32 v[2:3], v[6:7], v[8:9] op_sel_hi:[1,0]
	s_waitcnt vmcnt(0)
	v_pk_mul_f32 v[0:1], v[0:1], v[14:15]
	v_pk_mul_f32 v[2:3], v[2:3], v[12:13]
	v_pk_mul_f32 v[0:1], v[4:5], v[0:1]
	v_pk_mul_f32 v[2:3], v[82:83], v[2:3]
	v_pk_mul_f32 v[4:5], v[72:73], v[8:9] op_sel_hi:[1,0]
	v_cvt_pk_bf16_f32 v2, v2, v3
	v_cvt_pk_bf16_f32 v3, v0, v1
	flat_store_dwordx2 v[48:49], v[2:3] offset:208
	global_load_dwordx4 v[0:3], v205, s[10:11] offset:448
	s_waitcnt vmcnt(0)
	v_pk_mul_f32 v[0:1], v[4:5], v[0:1]
	s_nop 0
	v_pk_mul_f32 v[0:1], v[78:79], v[0:1]
	v_lshlrev_b32_e32 v4, 16, v71
	v_cvt_pk_bf16_f32 v0, v0, v1
	v_mul_f32_e32 v1, 0xbfb8aa3b, v4
	v_exp_f32_e32 v1, v1
	v_and_b32_e32 v5, 0xffff0000, v71
	v_pk_mul_f32 v[2:3], v[10:11], v[2:3]
	v_pk_mul_f32 v[10:11], v[66:67], v[8:9] op_sel_hi:[1,0]
	v_add_f32_e32 v1, 1.0, v1
	v_rcp_f32_e32 v6, v1
	v_mul_f32_e32 v1, 0xbfb8aa3b, v5
	v_exp_f32_e32 v1, v1
	v_pk_mul_f32 v[8:9], v[64:65], v[8:9] op_sel_hi:[1,0]
	v_add_f32_e32 v1, 1.0, v1
	v_rcp_f32_e32 v7, v1
	s_nop 0
	v_pk_mul_f32 v[4:5], v[6:7], v[4:5]
	s_nop 0
	v_pk_mul_f32 v[2:3], v[4:5], v[2:3]
	v_lshlrev_b32_e32 v4, 16, v68
	v_cvt_pk_bf16_f32 v1, v2, v3
	flat_store_dwordx2 v[48:49], v[0:1] offset:224
	global_load_dwordx4 v[0:3], v205, s[10:11] offset:480
	v_and_b32_e32 v5, 0xffff0000, v68
	v_mul_f32_e32 v6, 0xbfb8aa3b, v4
	v_mul_f32_e32 v7, 0xbfb8aa3b, v5
	v_exp_f32_e32 v6, v6
	v_exp_f32_e32 v7, v7
	v_add_f32_e32 v6, 1.0, v6
	v_add_f32_e32 v7, 1.0, v7
	v_rcp_f32_e32 v6, v6
	v_rcp_f32_e32 v7, v7
	s_waitcnt vmcnt(0)
	v_pk_mul_f32 v[0:1], v[10:11], v[0:1]
	v_pk_mul_f32 v[4:5], v[6:7], v[4:5]
	v_pk_mul_f32 v[2:3], v[8:9], v[2:3]
	v_pk_mul_f32 v[0:1], v[4:5], v[0:1]
	v_lshlrev_b32_e32 v4, 16, v69
	v_cvt_pk_bf16_f32 v0, v0, v1
	v_mul_f32_e32 v1, 0xbfb8aa3b, v4
	v_exp_f32_e32 v1, v1
	v_and_b32_e32 v5, 0xffff0000, v69
	v_add_f32_e32 v1, 1.0, v1
	v_rcp_f32_e32 v6, v1
	v_mul_f32_e32 v1, 0xbfb8aa3b, v5
	v_exp_f32_e32 v1, v1
	s_nop 0
	v_add_f32_e32 v1, 1.0, v1
	v_rcp_f32_e32 v7, v1
	s_nop 0
	v_pk_mul_f32 v[4:5], v[6:7], v[4:5]
	s_nop 0
	v_pk_mul_f32 v[2:3], v[4:5], v[2:3]
	s_nop 0
	v_cvt_pk_bf16_f32 v1, v2, v3
	flat_store_dwordx2 v[48:49], v[0:1] offset:240
	s_branch .LBB0_924

	.amdhsa_kernel _Z14fwd_megakernel6Params
		.amdhsa_group_segment_fixed_size 0
		.amdhsa_private_segment_fixed_size 0
		.amdhsa_kernarg_size 488
		.amdhsa_user_sgpr_count 2
		.amdhsa_user_sgpr_dispatch_ptr 0
		.amdhsa_user_sgpr_queue_ptr 0
		.amdhsa_user_sgpr_kernarg_segment_ptr 1
		.amdhsa_user_sgpr_dispatch_id 0
		.amdhsa_user_sgpr_kernarg_preload_length 0
		.amdhsa_user_sgpr_kernarg_preload_offset 0
		.amdhsa_user_sgpr_private_segment_size 0
		.amdhsa_uses_dynamic_stack 0
		.amdhsa_enable_private_segment 0
		.amdhsa_system_sgpr_workgroup_id_x 1
		.amdhsa_system_sgpr_workgroup_id_y 0
		.amdhsa_system_sgpr_workgroup_id_z 0
		.amdhsa_system_sgpr_workgroup_info 0
		.amdhsa_system_vgpr_workitem_id 2
		.amdhsa_next_free_vgpr 256
		.amdhsa_next_free_sgpr 100
		.amdhsa_accum_offset 256
		.amdhsa_reserve_vcc 1
		.amdhsa_float_round_mode_32 0
		.amdhsa_float_round_mode_16_64 0
		.amdhsa_float_denorm_mode_32 3
		.amdhsa_float_denorm_mode_16_64 3
		.amdhsa_dx10_clamp 1
		.amdhsa_ieee_mode 1
		.amdhsa_fp16_overflow 0
		.amdhsa_tg_split 0
		.amdhsa_exception_fp_ieee_invalid_op 0
		.amdhsa_exception_fp_denorm_src 0
		.amdhsa_exception_fp_ieee_div_zero 0
		.amdhsa_exception_fp_ieee_overflow 0
		.amdhsa_exception_fp_ieee_underflow 0
		.amdhsa_exception_fp_ieee_inexact 0
		.amdhsa_exception_int_div_zero 0
	.end_amdhsa_kernel

.Lfunc_end0:
	.size	_Z14fwd_megakernel6Params, .Lfunc_end0-_Z14fwd_megakernel6Params
	.set _Z14fwd_megakernel6Params.num_vgpr, 256
	.set _Z14fwd_megakernel6Params.num_agpr, 0
	.set _Z14fwd_megakernel6Params.numbered_sgpr, 100
	.set _Z14fwd_megakernel6Params.num_named_barrier, 0
	.set _Z14fwd_megakernel6Params.private_seg_size, 0
	.set _Z14fwd_megakernel6Params.uses_vcc, 1
	.set _Z14fwd_megakernel6Params.uses_flat_scratch, 0
	.set _Z14fwd_megakernel6Params.has_dyn_sized_stack, 0
	.set _Z14fwd_megakernel6Params.has_recursion, 0
	.set _Z14fwd_megakernel6Params.has_indirect_call, 0

amdhsa.kernels:
  - .agpr_count:     0
    .args:
      - .offset:         0
        .size:           232
        .value_kind:     by_value
      - .offset:         232
        .size:           4
        .value_kind:     hidden_block_count_x
      - .offset:         236
        .size:           4
        .value_kind:     hidden_block_count_y
      - .offset:         240
        .size:           4
        .value_kind:     hidden_block_count_z
      - .offset:         244
        .size:           2
        .value_kind:     hidden_group_size_x
      - .offset:         246
        .size:           2
        .value_kind:     hidden_group_size_y
      - .offset:         248
        .size:           2
        .value_kind:     hidden_group_size_z
      - .offset:         250
        .size:           2
        .value_kind:     hidden_remainder_x
      - .offset:         252
        .size:           2
        .value_kind:     hidden_remainder_y
      - .offset:         254
        .size:           2
        .value_kind:     hidden_remainder_z
      - .offset:         272
        .size:           8
        .value_kind:     hidden_global_offset_x
      - .offset:         280
        .size:           8
        .value_kind:     hidden_global_offset_y
      - .offset:         288
        .size:           8
        .value_kind:     hidden_global_offset_z
      - .offset:         296
        .size:           2
        .value_kind:     hidden_grid_dims
      - .offset:         320
        .size:           8
        .value_kind:     hidden_multigrid_sync_arg
      - .offset:         352
        .size:           4
        .value_kind:     hidden_dynamic_lds_size
    .group_segment_fixed_size: 0
    .kernarg_segment_align: 8
    .kernarg_segment_size: 488
    .language:       OpenCL C
    .language_version:
      - 2
      - 0
    .max_flat_workgroup_size: 512
    .name:           _Z14fwd_megakernel6Params
    .private_segment_fixed_size: 0
    .sgpr_count:     106
    .sgpr_spill_count: 134
    .symbol:         _Z14fwd_megakernel6Params.kd
    .uniform_work_group_size: 1
    .uses_dynamic_stack: false
    .vgpr_count:     256
    .vgpr_spill_count: 0
    .wavefront_size: 64
